# v18: v17 + half of the GEMM LDS-DMA loads use SGPR-base addressing (drops 8 of 16 64-bit VALU adds per K-iteration)
# speedup vs baseline: 1.0097x; 1.0009x over previous
; #define PG8_STAGE(bufoff, gbase, voff) do { _Pragma("unroll") for (int _i = 0; _i < 2; ++_i) \
;         __builtin_amdgcn_global_load_lds((const unsigned*)((const char*)(gbase) + (voff)[_i]), (LAS unsigned*)(lds + (bufoff) + ldsw + _i * 8192), 16, 0, 0); } while (0)
; #define PG8_LDA(dst, b, h) do { _Pragma("unroll") for (int m = 0; m < 4; ++m) _Pragma("unroll") for (int k = 0; k < 2; ++k) dst[m][k] = *(const LAS f16x8*)(lds + PG8_SA(b, h) + aoff + m * 2048 + k * 1024); } while (0)
; #define PG8_LDB(dst, b, h) do { _Pragma("unroll") for (int n = 0; n < 2; ++n) _Pragma("unroll") for (int k = 0; k < 2; ++k) dst[n][k] = *(const LAS f16x8*)(lds + PG8_SB(b, h) + boff + n * 2048 + k * 1024); } while (0)
; #define PG8_MMA(ai, bj, At, Bt) do { __builtin_amdgcn_s_setprio(1); _Pragma("unroll") for (int m = 0; m < 4; ++m) _Pragma("unroll") for (int n = 0; n < 2; ++n) _Pragma("unroll") for (int k = 0; k < 2; ++k) \
;         acc[ai][bj][m][n] = mma16_<Epi::BF16>(Bt[n][k], At[m][k], acc[ai][bj][m][n]); __builtin_amdgcn_s_setprio(0); } while (0)
; #define PG8_WAIT_V(n) asm volatile("s_waitcnt vmcnt(" #n ")" ::: "memory")
; #define PG8_WAIT_L(n) asm volatile("s_waitcnt lgkmcnt(" #n ")" ::: "memory")
; #define PG8_BAR __builtin_amdgcn_s_barrier()
; #define PG8_SCHED __builtin_amdgcn_sched_barrier(0)
;     ...
;         const char* nA = has_next ? (const char*)g.A + (size_t)nxt.pm * tA + (nxt.roff ? hA : (size_t)0) : cA; const char* nB = has_next ? (const char*)g.Bt + (size_t)nxt.pn * tB : cB;
;         for (int t = 0; t < nt; t += 2) {
;             const bool last = (t == nt - 2);
;             const char* a1 = cA + (size_t)(t + 1) * kstep;
;             const char* a2 = last ? nA : cA + (size_t)(t + 2) * kstep; const char* b2 = last ? nB : cB + (size_t)(t + 2) * kstep;
;             const char* a3 = a2 + kstep; const char* b3 = b2 + kstep;
;             if constexpr (SP2) {
;             PG8_LDB(B0, 0, 0); PG8_LDB(B1, 0, 1); PG8_SCHED; PG8_LDA(At, 0, 0); PG8_STAGE(PG8_SA(1, 1), a1 + hA, voffA);
;             PG8_WAIT_V(8); PG8_WAIT_L(0); PG8_BAR; PG8_MMA(0, 0, At, B0); PG8_MMA(0, 1, At, B1); PG8_BAR; PG8_SCHED;
;             PG8_LDA(At, 0, 1); PG8_STAGE(PG8_SB(0, 0), b2, voffB); PG8_STAGE(PG8_SB(0, 1), b2 + hB, voffB); PG8_STAGE(PG8_SA(0, 0), a2, voffA);
.LBB0_157:
	s_add_u32 s28, s26, 0xfffc0080
	s_addc_u32 s29, s27, -1
	s_add_i32 s50, 0, 0x10000
	s_cmp_eq_u32 s49, 12
	s_cselect_b32 s31, s2, s29
	s_cselect_b32 s30, s3, s28
	s_cselect_b32 s29, s11, s48
	s_cselect_b32 s28, s19, s47
	s_add_i32 s52, 0, 0x14000
	v_add_u32_e32 v156, s50, v141
	v_add_u32_e32 v172, s52, v141
	ds_read_b128 v[144:147], v156
	ds_read_b128 v[148:151], v156 offset:1024
	ds_read_b128 v[152:155], v156 offset:2048
	ds_read_b128 v[156:159], v156 offset:3072
	ds_read_b128 v[160:163], v172
	ds_read_b128 v[164:167], v172 offset:1024
	ds_read_b128 v[168:171], v172 offset:2048
	ds_read_b128 v[172:175], v172 offset:3072
	s_add_i32 m0, s25, 0xc000
	ds_read_b128 v[176:179], v143
	ds_read_b128 v[180:183], v143 offset:1024
	ds_read_b128 v[184:187], v143 offset:2048
	ds_read_b128 v[188:191], v143 offset:3072
	ds_read_b128 v[192:195], v143 offset:4096
	ds_read_b128 v[214:217], v143 offset:5120
	ds_read_b128 v[218:221], v143 offset:6144
	ds_read_b128 v[222:225], v143 offset:7168
	global_load_lds_dwordx4 v136, s[26:27]
	s_add_i32 m0, s25, 0xe000
	s_nop 0
	global_load_lds_dwordx4 v138, s[26:27]
	s_waitcnt vmcnt(8)
	s_waitcnt lgkmcnt(0)
	s_barrier
	s_setprio 1
	v_mfma_f32_16x16x32_bf16 v[126:129], v[144:147], v[176:179], v[126:129]
	v_mfma_f32_16x16x32_bf16 v[118:121], v[152:155], v[176:179], v[118:121]
	v_mfma_f32_16x16x32_bf16 v[110:113], v[144:147], v[184:187], v[110:113]
	v_mfma_f32_16x16x32_bf16 v[102:105], v[152:155], v[184:187], v[102:105]
	v_mfma_f32_16x16x32_bf16 v[94:97], v[144:147], v[192:195], v[94:97]
	v_mfma_f32_16x16x32_bf16 v[86:89], v[152:155], v[192:195], v[86:89]
	v_mfma_f32_16x16x32_bf16 v[78:81], v[144:147], v[218:221], v[78:81]
	v_mfma_f32_16x16x32_bf16 v[70:73], v[152:155], v[218:221], v[70:73]
	v_mfma_f32_16x16x32_bf16 v[126:129], v[148:151], v[180:183], v[126:129]
	v_mfma_f32_16x16x32_bf16 v[118:121], v[156:159], v[180:183], v[118:121]
	v_mfma_f32_16x16x32_bf16 v[110:113], v[148:151], v[188:191], v[110:113]
	v_mfma_f32_16x16x32_bf16 v[102:105], v[156:159], v[188:191], v[102:105]
	v_mfma_f32_16x16x32_bf16 v[94:97], v[148:151], v[214:217], v[94:97]
	v_mfma_f32_16x16x32_bf16 v[86:89], v[156:159], v[214:217], v[86:89]
	v_mfma_f32_16x16x32_bf16 v[78:81], v[148:151], v[222:225], v[78:81]
	v_mfma_f32_16x16x32_bf16 v[70:73], v[156:159], v[222:225], v[70:73]
	s_setprio 0
	s_setprio 1
	v_mfma_f32_16x16x32_bf16 v[122:125], v[160:163], v[176:179], v[122:125]
	v_mfma_f32_16x16x32_bf16 v[114:117], v[168:171], v[176:179], v[114:117]
	v_mfma_f32_16x16x32_bf16 v[106:109], v[160:163], v[184:187], v[106:109]
	v_mfma_f32_16x16x32_bf16 v[98:101], v[168:171], v[184:187], v[98:101]
	v_mfma_f32_16x16x32_bf16 v[90:93], v[160:163], v[192:195], v[90:93]
	v_mfma_f32_16x16x32_bf16 v[82:85], v[168:171], v[192:195], v[82:85]
	v_mfma_f32_16x16x32_bf16 v[74:77], v[160:163], v[218:221], v[74:77]
	v_mfma_f32_16x16x32_bf16 v[66:69], v[168:171], v[218:221], v[66:69]
	v_mfma_f32_16x16x32_bf16 v[122:125], v[164:167], v[180:183], v[122:125]
	v_mfma_f32_16x16x32_bf16 v[114:117], v[172:175], v[180:183], v[114:117]
	v_mfma_f32_16x16x32_bf16 v[106:109], v[164:167], v[188:191], v[106:109]
	v_mfma_f32_16x16x32_bf16 v[98:101], v[172:175], v[188:191], v[98:101]
	v_mfma_f32_16x16x32_bf16 v[90:93], v[164:167], v[214:217], v[90:93]
	v_mfma_f32_16x16x32_bf16 v[82:85], v[172:175], v[214:217], v[82:85]
	v_mfma_f32_16x16x32_bf16 v[74:77], v[164:167], v[222:225], v[74:77]
	v_mfma_f32_16x16x32_bf16 v[66:69], v[172:175], v[222:225], v[66:69]
	s_setprio 0
	s_barrier
	s_add_i32 s50, s50, s34
	v_lshl_add_u64 v[200:201], s[28:29], 0, v[0:1]
	s_mov_b32 m0, s50
	ds_read_b128 v[176:179], v143 offset:16384
	ds_read_b128 v[180:183], v143 offset:17408
	ds_read_b128 v[184:187], v143 offset:18432
	ds_read_b128 v[188:191], v143 offset:19456
	ds_read_b128 v[192:195], v143 offset:20480
	ds_read_b128 v[214:217], v143 offset:21504
	ds_read_b128 v[218:221], v143 offset:22528
	ds_read_b128 v[222:225], v143 offset:23552
	global_load_lds_dwordx4 v[200:201], off
	s_add_i32 m0, s50, 0x2000
	s_add_u32 s50, s28, 0x40000
	v_lshl_add_u64 v[202:203], s[28:29], 0, v[130:131]
	s_addc_u32 s51, s29, 0
	s_add_i32 s52, s52, s34
	global_load_lds_dwordx4 v[202:203], off
	s_mov_b32 m0, s52
	v_lshl_add_u64 v[228:229], s[30:31], 0, v[132:133]
	global_load_lds_dwordx4 v0, s[50:51]
	s_add_i32 m0, s52, 0x2000
	s_nop 0
	global_load_lds_dwordx4 v130, s[50:51]
	v_lshl_add_u64 v[226:227], s[30:31], 0, v[134:135]
	s_mov_b32 m0, s25
	s_nop 0
	global_load_lds_dwordx4 v[226:227], off
	s_mov_b32 m0, s36
	s_nop 0
	global_load_lds_dwordx4 v[228:229], off
	s_waitcnt vmcnt(8)
	s_waitcnt lgkmcnt(0)
	s_barrier
; #define PG8_STAGE(bufoff, gbase, voff) do { _Pragma("unroll") for (int _i = 0; _i < 2; ++_i) \
;         __builtin_amdgcn_global_load_lds((const unsigned*)((const char*)(gbase) + (voff)[_i]), (LAS unsigned*)(lds + (bufoff) + ldsw + _i * 8192), 16, 0, 0); } while (0)
; #define PG8_LDA(dst, b, h) do { _Pragma("unroll") for (int m = 0; m < 4; ++m) _Pragma("unroll") for (int k = 0; k < 2; ++k) dst[m][k] = *(const LAS f16x8*)(lds + PG8_SA(b, h) + aoff + m * 2048 + k * 1024); } while (0)
; #define PG8_LDB(dst, b, h) do { _Pragma("unroll") for (int n = 0; n < 2; ++n) _Pragma("unroll") for (int k = 0; k < 2; ++k) dst[n][k] = *(const LAS f16x8*)(lds + PG8_SB(b, h) + boff + n * 2048 + k * 1024); } while (0)
; #define PG8_MMA(ai, bj, At, Bt) do { __builtin_amdgcn_s_setprio(1); _Pragma("unroll") for (int m = 0; m < 4; ++m) _Pragma("unroll") for (int n = 0; n < 2; ++n) _Pragma("unroll") for (int k = 0; k < 2; ++k) \
;         acc[ai][bj][m][n] = mma16_<Epi::BF16>(Bt[n][k], At[m][k], acc[ai][bj][m][n]); __builtin_amdgcn_s_setprio(0); } while (0)
; #define PG8_WAIT_V(n) asm volatile("s_waitcnt vmcnt(" #n ")" ::: "memory")
; #define PG8_WAIT_L(n) asm volatile("s_waitcnt lgkmcnt(" #n ")" ::: "memory")
; #define PG8_BAR __builtin_amdgcn_s_barrier()
; #define PG8_SCHED __builtin_amdgcn_sched_barrier(0)
;     ...
;             PG8_WAIT_V(8); PG8_WAIT_L(0); PG8_BAR; if (!cur.half) { PG8_MMA(1, 0, At, B0); PG8_MMA(1, 1, At, B1); } PG8_BAR; PG8_SCHED;
;             PG8_LDB(B0, 1, 0); PG8_LDB(B1, 1, 1); PG8_SCHED; PG8_LDA(At, 1, 0); PG8_STAGE(PG8_SA(0, 1), a2 + hA, voffA);
;             PG8_WAIT_V(8); PG8_WAIT_L(0); PG8_BAR; PG8_MMA(0, 0, At, B0); PG8_MMA(0, 1, At, B1); PG8_BAR; PG8_SCHED;
	s_setprio 1
	v_mfma_f32_16x16x32_bf16 v[62:65], v[144:147], v[176:179], v[62:65]
	v_mfma_f32_16x16x32_bf16 v[54:57], v[152:155], v[176:179], v[54:57]
	v_mfma_f32_16x16x32_bf16 v[46:49], v[144:147], v[184:187], v[46:49]
	v_mfma_f32_16x16x32_bf16 v[38:41], v[152:155], v[184:187], v[38:41]
	v_mfma_f32_16x16x32_bf16 v[30:33], v[144:147], v[192:195], v[30:33]
	v_mfma_f32_16x16x32_bf16 v[22:25], v[152:155], v[192:195], v[22:25]
	v_mfma_f32_16x16x32_bf16 v[14:17], v[144:147], v[218:221], v[14:17]
	v_mfma_f32_16x16x32_bf16 v[6:9], v[152:155], v[218:221], v[6:9]
	v_mfma_f32_16x16x32_bf16 v[62:65], v[148:151], v[180:183], v[62:65]
	v_mfma_f32_16x16x32_bf16 v[54:57], v[156:159], v[180:183], v[54:57]
	v_mfma_f32_16x16x32_bf16 v[46:49], v[148:151], v[188:191], v[46:49]
	v_mfma_f32_16x16x32_bf16 v[38:41], v[156:159], v[188:191], v[38:41]
	v_mfma_f32_16x16x32_bf16 v[30:33], v[148:151], v[214:217], v[30:33]
	v_mfma_f32_16x16x32_bf16 v[22:25], v[156:159], v[214:217], v[22:25]
	v_mfma_f32_16x16x32_bf16 v[14:17], v[148:151], v[222:225], v[14:17]
	v_mfma_f32_16x16x32_bf16 v[6:9], v[156:159], v[222:225], v[6:9]
	s_setprio 0
	s_setprio 1
	v_mfma_f32_16x16x32_bf16 v[58:61], v[160:163], v[176:179], v[58:61]
	v_mfma_f32_16x16x32_bf16 v[50:53], v[168:171], v[176:179], v[50:53]
	v_mfma_f32_16x16x32_bf16 v[42:45], v[160:163], v[184:187], v[42:45]
	v_mfma_f32_16x16x32_bf16 v[34:37], v[168:171], v[184:187], v[34:37]
	v_mfma_f32_16x16x32_bf16 v[26:29], v[160:163], v[192:195], v[26:29]
	v_mfma_f32_16x16x32_bf16 v[18:21], v[168:171], v[192:195], v[18:21]
	v_mfma_f32_16x16x32_bf16 v[10:13], v[160:163], v[218:221], v[10:13]
	v_mfma_f32_16x16x32_bf16 v[2:5], v[168:171], v[218:221], v[2:5]
	v_mfma_f32_16x16x32_bf16 v[58:61], v[164:167], v[180:183], v[58:61]
	v_mfma_f32_16x16x32_bf16 v[50:53], v[172:175], v[180:183], v[50:53]
	v_mfma_f32_16x16x32_bf16 v[42:45], v[164:167], v[188:191], v[42:45]
	v_mfma_f32_16x16x32_bf16 v[34:37], v[172:175], v[188:191], v[34:37]
	v_mfma_f32_16x16x32_bf16 v[26:29], v[164:167], v[214:217], v[26:29]
	v_mfma_f32_16x16x32_bf16 v[18:21], v[172:175], v[214:217], v[18:21]
	v_mfma_f32_16x16x32_bf16 v[10:13], v[164:167], v[222:225], v[10:13]
	v_mfma_f32_16x16x32_bf16 v[2:5], v[172:175], v[222:225], v[2:5]
	s_setprio 0
	s_barrier
	s_add_i32 s50, 0, 0x18000
	s_add_i32 s51, 0, 0x1c000
	v_add_u32_e32 v156, s50, v141
	v_add_u32_e32 v172, s51, v141
	ds_read_b128 v[144:147], v156
	ds_read_b128 v[148:151], v156 offset:1024
	ds_read_b128 v[152:155], v156 offset:2048
	ds_read_b128 v[156:159], v156 offset:3072
	ds_read_b128 v[160:163], v172
	ds_read_b128 v[164:167], v172 offset:1024
	ds_read_b128 v[168:171], v172 offset:2048
	ds_read_b128 v[172:175], v172 offset:3072
	s_add_u32 s30, s30, 0x40000
	s_addc_u32 s31, s31, 0
	s_mov_b32 m0, s37
	ds_read_b128 v[176:179], v143 offset:32768
	ds_read_b128 v[180:183], v143 offset:33792
	ds_read_b128 v[184:187], v143 offset:34816
	ds_read_b128 v[188:191], v143 offset:35840
	ds_read_b128 v[192:195], v143 offset:36864
	ds_read_b128 v[214:217], v143 offset:37888
	ds_read_b128 v[218:221], v143 offset:38912
	ds_read_b128 v[222:225], v143 offset:39936
	global_load_lds_dwordx4 v134, s[30:31]
	s_mov_b32 m0, s40
	s_nop 0
	global_load_lds_dwordx4 v132, s[30:31]
	s_waitcnt vmcnt(8)
	s_waitcnt lgkmcnt(0)
	s_barrier
	s_setprio 1
	v_mfma_f32_16x16x32_bf16 v[126:129], v[144:147], v[176:179], v[126:129]
	v_mfma_f32_16x16x32_bf16 v[118:121], v[152:155], v[176:179], v[118:121]
	v_mfma_f32_16x16x32_bf16 v[110:113], v[144:147], v[184:187], v[110:113]
	v_mfma_f32_16x16x32_bf16 v[102:105], v[152:155], v[184:187], v[102:105]
	v_mfma_f32_16x16x32_bf16 v[94:97], v[144:147], v[192:195], v[94:97]
	v_mfma_f32_16x16x32_bf16 v[86:89], v[152:155], v[192:195], v[86:89]
	v_mfma_f32_16x16x32_bf16 v[78:81], v[144:147], v[218:221], v[78:81]
	v_mfma_f32_16x16x32_bf16 v[70:73], v[152:155], v[218:221], v[70:73]
	v_mfma_f32_16x16x32_bf16 v[126:129], v[148:151], v[180:183], v[126:129]
	v_mfma_f32_16x16x32_bf16 v[118:121], v[156:159], v[180:183], v[118:121]
	v_mfma_f32_16x16x32_bf16 v[110:113], v[148:151], v[188:191], v[110:113]
	v_mfma_f32_16x16x32_bf16 v[102:105], v[156:159], v[188:191], v[102:105]
	v_mfma_f32_16x16x32_bf16 v[94:97], v[148:151], v[214:217], v[94:97]
	v_mfma_f32_16x16x32_bf16 v[86:89], v[156:159], v[214:217], v[86:89]
	v_mfma_f32_16x16x32_bf16 v[78:81], v[148:151], v[222:225], v[78:81]
	v_mfma_f32_16x16x32_bf16 v[70:73], v[156:159], v[222:225], v[70:73]
	s_setprio 0
	s_setprio 1
	v_mfma_f32_16x16x32_bf16 v[122:125], v[160:163], v[176:179], v[122:125]
	v_mfma_f32_16x16x32_bf16 v[114:117], v[168:171], v[176:179], v[114:117]
	v_mfma_f32_16x16x32_bf16 v[106:109], v[160:163], v[184:187], v[106:109]
	v_mfma_f32_16x16x32_bf16 v[98:101], v[168:171], v[184:187], v[98:101]
	v_mfma_f32_16x16x32_bf16 v[90:93], v[160:163], v[192:195], v[90:93]
	v_mfma_f32_16x16x32_bf16 v[82:85], v[168:171], v[192:195], v[82:85]
	v_mfma_f32_16x16x32_bf16 v[74:77], v[160:163], v[218:221], v[74:77]
	v_mfma_f32_16x16x32_bf16 v[66:69], v[168:171], v[218:221], v[66:69]
	v_mfma_f32_16x16x32_bf16 v[122:125], v[164:167], v[180:183], v[122:125]
	v_mfma_f32_16x16x32_bf16 v[114:117], v[172:175], v[180:183], v[114:117]
	v_mfma_f32_16x16x32_bf16 v[106:109], v[164:167], v[188:191], v[106:109]
	v_mfma_f32_16x16x32_bf16 v[98:101], v[172:175], v[188:191], v[98:101]
	v_mfma_f32_16x16x32_bf16 v[90:93], v[164:167], v[214:217], v[90:93]
	v_mfma_f32_16x16x32_bf16 v[82:85], v[172:175], v[214:217], v[82:85]
	v_mfma_f32_16x16x32_bf16 v[74:77], v[164:167], v[222:225], v[74:77]
	v_mfma_f32_16x16x32_bf16 v[66:69], v[172:175], v[222:225], v[66:69]
	s_setprio 0
	s_barrier
; #define PG8_STAGE(bufoff, gbase, voff) do { _Pragma("unroll") for (int _i = 0; _i < 2; ++_i) \
;         __builtin_amdgcn_global_load_lds((const unsigned*)((const char*)(gbase) + (voff)[_i]), (LAS unsigned*)(lds + (bufoff) + ldsw + _i * 8192), 16, 0, 0); } while (0)
; #define PG8_LDA(dst, b, h) do { _Pragma("unroll") for (int m = 0; m < 4; ++m) _Pragma("unroll") for (int k = 0; k < 2; ++k) dst[m][k] = *(const LAS f16x8*)(lds + PG8_SA(b, h) + aoff + m * 2048 + k * 1024); } while (0)
; #define PG8_LDB(dst, b, h) do { _Pragma("unroll") for (int n = 0; n < 2; ++n) _Pragma("unroll") for (int k = 0; k < 2; ++k) dst[n][k] = *(const LAS f16x8*)(lds + PG8_SB(b, h) + boff + n * 2048 + k * 1024); } while (0)
;     ...
;             PG8_LDA(At, 1, 1); PG8_STAGE(PG8_SB(1, 0), b3, voffB); PG8_STAGE(PG8_SB(1, 1), b3 + hB, voffB); PG8_STAGE(PG8_SA(1, 0), a3, voffA);
;             PG8_WAIT_V(8); PG8_WAIT_L(0); PG8_BAR; if (!cur.half) { PG8_MMA(1, 0, At, B0); PG8_MMA(1, 1, At, B1); } PG8_BAR; PG8_SCHED;
;             } else {
;             PG8_LDB(B0, 0, 0); PG8_SCHED; PG8_LDA(At, 0, 0); PG8_STAGE(PG8_SA(1, 1), a1 + hA, voffA);
;             PG8_WAIT_L(8); PG8_BAR; PG8_WAIT_L(0); PG8_MMA(0, 0, At, B0); PG8_BAR; PG8_SCHED;
;             PG8_LDB(B1, 0, 1); PG8_STAGE(PG8_SB(0, 0), b2, voffB);
;             PG8_BAR; PG8_WAIT_L(0); PG8_MMA(0, 1, At, B1); PG8_BAR;
;             PG8_LDA(At, 0, 1); PG8_STAGE(PG8_SA(0, 0), a2, voffA);
;             PG8_BAR; PG8_WAIT_L(0); if (!cur.half) PG8_MMA(1, 0, At, B0); PG8_BAR; PG8_SCHED;
;             PG8_STAGE(PG8_SB(0, 1), b2 + hB, voffB);
;             PG8_WAIT_V(6); PG8_BAR; if (!cur.half) PG8_MMA(1, 1, At, B1); PG8_BAR;
;             PG8_LDB(B0, 1, 0); PG8_SCHED; PG8_LDA(At, 1, 0); PG8_STAGE(PG8_SA(0, 1), a2 + hA, voffA);
;             PG8_WAIT_L(8); PG8_BAR; PG8_WAIT_L(0); PG8_MMA(0, 0, At, B0); PG8_BAR; PG8_SCHED;
;             PG8_LDB(B1, 1, 1); PG8_STAGE(PG8_SB(1, 0), b3, voffB);
;             PG8_BAR; PG8_WAIT_L(0); PG8_MMA(0, 1, At, B1); PG8_BAR;
;             PG8_LDA(At, 1, 1); PG8_STAGE(PG8_SA(1, 0), a3, voffA);
;             PG8_BAR; PG8_WAIT_L(0); if (!cur.half) PG8_MMA(1, 0, At, B0); PG8_BAR; PG8_SCHED;
;             PG8_STAGE(PG8_SB(1, 1), b3 + hB, voffB);
;             PG8_WAIT_V(6); PG8_BAR; if (!cur.half) PG8_MMA(1, 1, At, B1); PG8_BAR;
;             }
;         }
;         if constexpr (ALIGN_EPI) { if (wr == 0) PG8_BAR; }
	s_add_i32 s30, s50, s34
	v_lshl_add_u64 v[200:201], v[200:201], 0, s[96:97]
	s_mov_b32 m0, s30
	ds_read_b128 v[176:179], v143 offset:49152
	ds_read_b128 v[180:183], v143 offset:50176
	ds_read_b128 v[184:187], v143 offset:51200
	ds_read_b128 v[188:191], v143 offset:52224
	ds_read_b128 v[192:195], v143 offset:53248
	ds_read_b128 v[214:217], v143 offset:54272
	ds_read_b128 v[218:221], v143 offset:55296
	ds_read_b128 v[222:225], v143 offset:56320
	global_load_lds_dwordx4 v[200:201], off
	s_add_i32 m0, s30, 0x2000
	s_add_u32 s28, s28, 0x40080
	v_lshl_add_u64 v[200:201], v[202:203], 0, s[96:97]
	s_addc_u32 s29, s29, 0
	s_add_i32 s30, s51, s34
	global_load_lds_dwordx4 v[200:201], off
	s_mov_b32 m0, s30
	s_nop 0
	global_load_lds_dwordx4 v0, s[28:29]
	s_add_i32 m0, s30, 0x2000
	s_nop 0
	global_load_lds_dwordx4 v130, s[28:29]
	v_lshl_add_u64 v[200:201], v[226:227], 0, s[96:97]
	s_mov_b32 m0, s41
	s_nop 0
	global_load_lds_dwordx4 v[200:201], off
	v_lshl_add_u64 v[200:201], v[228:229], 0, s[96:97]
	s_mov_b32 m0, s42
	s_nop 0
	global_load_lds_dwordx4 v[200:201], off
	s_waitcnt vmcnt(8)
	s_waitcnt lgkmcnt(0)
	s_barrier
	s_setprio 1
	v_mfma_f32_16x16x32_bf16 v[62:65], v[144:147], v[176:179], v[62:65]
	v_mfma_f32_16x16x32_bf16 v[54:57], v[152:155], v[176:179], v[54:57]
	v_mfma_f32_16x16x32_bf16 v[46:49], v[144:147], v[184:187], v[46:49]
	v_mfma_f32_16x16x32_bf16 v[38:41], v[152:155], v[184:187], v[38:41]
	v_mfma_f32_16x16x32_bf16 v[30:33], v[144:147], v[192:195], v[30:33]
	v_mfma_f32_16x16x32_bf16 v[22:25], v[152:155], v[192:195], v[22:25]
	v_mfma_f32_16x16x32_bf16 v[14:17], v[144:147], v[218:221], v[14:17]
	v_mfma_f32_16x16x32_bf16 v[6:9], v[152:155], v[218:221], v[6:9]
	v_mfma_f32_16x16x32_bf16 v[62:65], v[148:151], v[180:183], v[62:65]
	v_mfma_f32_16x16x32_bf16 v[54:57], v[156:159], v[180:183], v[54:57]
	v_mfma_f32_16x16x32_bf16 v[46:49], v[148:151], v[188:191], v[46:49]
	v_mfma_f32_16x16x32_bf16 v[38:41], v[156:159], v[188:191], v[38:41]
	v_mfma_f32_16x16x32_bf16 v[30:33], v[148:151], v[214:217], v[30:33]
	v_mfma_f32_16x16x32_bf16 v[22:25], v[156:159], v[214:217], v[22:25]
	v_mfma_f32_16x16x32_bf16 v[14:17], v[148:151], v[222:225], v[14:17]
	v_mfma_f32_16x16x32_bf16 v[6:9], v[156:159], v[222:225], v[6:9]
	s_setprio 0
	s_setprio 1
	v_mfma_f32_16x16x32_bf16 v[58:61], v[160:163], v[176:179], v[58:61]
	v_mfma_f32_16x16x32_bf16 v[50:53], v[168:171], v[176:179], v[50:53]
	v_mfma_f32_16x16x32_bf16 v[42:45], v[160:163], v[184:187], v[42:45]
	v_mfma_f32_16x16x32_bf16 v[34:37], v[168:171], v[184:187], v[34:37]
	v_mfma_f32_16x16x32_bf16 v[26:29], v[160:163], v[192:195], v[26:29]
	v_mfma_f32_16x16x32_bf16 v[18:21], v[168:171], v[192:195], v[18:21]
	v_mfma_f32_16x16x32_bf16 v[10:13], v[160:163], v[218:221], v[10:13]
	v_mfma_f32_16x16x32_bf16 v[2:5], v[168:171], v[218:221], v[2:5]
	v_mfma_f32_16x16x32_bf16 v[58:61], v[164:167], v[180:183], v[58:61]
	v_mfma_f32_16x16x32_bf16 v[50:53], v[172:175], v[180:183], v[50:53]
	v_mfma_f32_16x16x32_bf16 v[42:45], v[164:167], v[188:191], v[42:45]
	v_mfma_f32_16x16x32_bf16 v[34:37], v[172:175], v[188:191], v[34:37]
	v_mfma_f32_16x16x32_bf16 v[26:29], v[164:167], v[214:217], v[26:29]
	v_mfma_f32_16x16x32_bf16 v[18:21], v[172:175], v[214:217], v[18:21]
	v_mfma_f32_16x16x32_bf16 v[10:13], v[164:167], v[222:225], v[10:13]
	v_mfma_f32_16x16x32_bf16 v[2:5], v[172:175], v[222:225], v[2:5]
	s_setprio 0
	s_barrier
	s_add_i32 s49, s49, 2
	s_add_u32 s26, s26, 0x100
	s_addc_u32 s27, s27, 0
	s_add_u32 s47, s47, 0x100
	s_addc_u32 s48, s48, 0
	s_cmp_gt_u32 s49, 13
	s_cbranch_scc0 .LBB0_157
	s_and_b64 vcc, exec, s[8:9]
	s_cbranch_vccz .LBB0_160
	s_barrier

; #define PG8_STAGE(bufoff, gbase, voff) do { _Pragma("unroll") for (int _i = 0; _i < 2; ++_i) \
;         __builtin_amdgcn_global_load_lds((const unsigned*)((const char*)(gbase) + (voff)[_i]), (LAS unsigned*)(lds + (bufoff) + ldsw + _i * 8192), 16, 0, 0); } while (0)
; #define PG8_LDA(dst, b, h) do { _Pragma("unroll") for (int m = 0; m < 4; ++m) _Pragma("unroll") for (int k = 0; k < 2; ++k) dst[m][k] = *(const LAS f16x8*)(lds + PG8_SA(b, h) + aoff + m * 2048 + k * 1024); } while (0)
; #define PG8_LDB(dst, b, h) do { _Pragma("unroll") for (int n = 0; n < 2; ++n) _Pragma("unroll") for (int k = 0; k < 2; ++k) dst[n][k] = *(const LAS f16x8*)(lds + PG8_SB(b, h) + boff + n * 2048 + k * 1024); } while (0)
; #define PG8_MMA(ai, bj, At, Bt) do { __builtin_amdgcn_s_setprio(1); _Pragma("unroll") for (int m = 0; m < 4; ++m) _Pragma("unroll") for (int n = 0; n < 2; ++n) _Pragma("unroll") for (int k = 0; k < 2; ++k) \
;         acc[ai][bj][m][n] = mma16_<Epi::BF16>(Bt[n][k], At[m][k], acc[ai][bj][m][n]); __builtin_amdgcn_s_setprio(0); } while (0)
; #define PG8_WAIT_V(n) asm volatile("s_waitcnt vmcnt(" #n ")" ::: "memory")
; #define PG8_WAIT_L(n) asm volatile("s_waitcnt lgkmcnt(" #n ")" ::: "memory")
; #define PG8_BAR __builtin_amdgcn_s_barrier()
;     ...
;         const char* nA = has_next ? (const char*)g.A + (size_t)nxt.pm * tA + (nxt.roff ? hA : (size_t)0) : cA; const char* nB = has_next ? (const char*)g.Bt + (size_t)nxt.pn * tB : cB;
;         for (int t = 0; t < nt; t += 2) {
;             const bool last = (t == nt - 2);
;             const char* a1 = cA + (size_t)(t + 1) * kstep;
;             const char* a2 = last ? nA : cA + (size_t)(t + 2) * kstep; const char* b2 = last ? nB : cB + (size_t)(t + 2) * kstep;
;             const char* a3 = a2 + kstep; const char* b3 = b2 + kstep;
;             if constexpr (SP2) {
;             PG8_LDB(B0, 0, 0); PG8_LDB(B1, 0, 1); PG8_SCHED; PG8_LDA(At, 0, 0); PG8_STAGE(PG8_SA(1, 1), a1 + hA, voffA);
;             PG8_WAIT_V(8); PG8_WAIT_L(0); PG8_BAR; PG8_MMA(0, 0, At, B0); PG8_MMA(0, 1, At, B1); PG8_BAR; PG8_SCHED;
;             PG8_LDA(At, 0, 1); PG8_STAGE(PG8_SB(0, 0), b2, voffB); PG8_STAGE(PG8_SB(0, 1), b2 + hB, voffB); PG8_STAGE(PG8_SA(0, 0), a2, voffA);
;             PG8_WAIT_V(8); PG8_WAIT_L(0); PG8_BAR; if (!cur.half) { PG8_MMA(1, 0, At, B0); PG8_MMA(1, 1, At, B1); } PG8_BAR; PG8_SCHED;
.LBB0_242:
	s_mov_b64 s[42:43], s[44:45]
	s_add_u32 s44, s42, 0x100
	s_addc_u32 s45, s43, 0
	s_add_i32 s37, 0, 0x10000
	s_cmp_eq_u32 s14, 40
	s_cselect_b32 s55, s9, s45
	s_cselect_b32 s54, s8, s44
	s_cselect_b32 s53, s11, s3
	s_cselect_b32 s52, s10, s2
	s_add_i32 s78, 0, 0x14000
	v_add_u32_e32 v130, s37, v243
	v_add_u32_e32 v142, s78, v243
	ds_read_b128 v[146:149], v130
	ds_read_b128 v[150:153], v130 offset:1024
	ds_read_b128 v[154:157], v130 offset:2048
	ds_read_b128 v[158:161], v130 offset:3072
	ds_read_b128 v[130:133], v142
	ds_read_b128 v[134:137], v142 offset:1024
	ds_read_b128 v[138:141], v142 offset:2048
	ds_read_b128 v[142:145], v142 offset:3072
	s_add_i32 m0, s63, 0xc000
	s_waitcnt lgkmcnt(0)
	ds_read_b128 v[162:165], v244
	ds_read_b128 v[166:169], v244 offset:1024
	ds_read_b128 v[170:173], v244 offset:2048
	ds_read_b128 v[174:177], v244 offset:3072
	ds_read_b128 v[178:181], v244 offset:4096
	ds_read_b128 v[182:185], v244 offset:5120
	ds_read_b128 v[186:189], v244 offset:6144
	ds_read_b128 v[190:193], v244 offset:7168
	global_load_lds_dwordx4 v222, s[42:43]
	s_add_i32 m0, s63, 0xe000
	s_nop 0
	global_load_lds_dwordx4 v224, s[42:43]
	s_waitcnt vmcnt(8)
	s_waitcnt lgkmcnt(0)
	s_barrier
	s_setprio 1
	v_mfma_f32_16x16x32_bf16 v[126:129], v[146:149], v[162:165], v[126:129]
	v_mfma_f32_16x16x32_bf16 v[122:125], v[154:157], v[162:165], v[122:125]
	v_mfma_f32_16x16x32_bf16 v[118:121], v[146:149], v[170:173], v[118:121]
	v_mfma_f32_16x16x32_bf16 v[114:117], v[154:157], v[170:173], v[114:117]
	v_mfma_f32_16x16x32_bf16 v[110:113], v[146:149], v[178:181], v[110:113]
	v_mfma_f32_16x16x32_bf16 v[106:109], v[154:157], v[178:181], v[106:109]
	v_mfma_f32_16x16x32_bf16 v[102:105], v[146:149], v[186:189], v[102:105]
	v_mfma_f32_16x16x32_bf16 v[98:101], v[154:157], v[186:189], v[98:101]
	v_mfma_f32_16x16x32_bf16 v[126:129], v[150:153], v[166:169], v[126:129]
	v_mfma_f32_16x16x32_bf16 v[122:125], v[158:161], v[166:169], v[122:125]
	v_mfma_f32_16x16x32_bf16 v[118:121], v[150:153], v[174:177], v[118:121]
	v_mfma_f32_16x16x32_bf16 v[114:117], v[158:161], v[174:177], v[114:117]
	v_mfma_f32_16x16x32_bf16 v[110:113], v[150:153], v[182:185], v[110:113]
	v_mfma_f32_16x16x32_bf16 v[106:109], v[158:161], v[182:185], v[106:109]
	v_mfma_f32_16x16x32_bf16 v[102:105], v[150:153], v[190:193], v[102:105]
	v_mfma_f32_16x16x32_bf16 v[98:101], v[158:161], v[190:193], v[98:101]
	s_setprio 0
	s_setprio 1
	v_mfma_f32_16x16x32_bf16 v[70:73], v[130:133], v[162:165], v[70:73]
	v_mfma_f32_16x16x32_bf16 v[66:69], v[138:141], v[162:165], v[66:69]
	v_mfma_f32_16x16x32_bf16 v[54:57], v[130:133], v[170:173], v[54:57]
	v_mfma_f32_16x16x32_bf16 v[50:53], v[138:141], v[170:173], v[50:53]
	v_mfma_f32_16x16x32_bf16 v[46:49], v[130:133], v[178:181], v[46:49]
	v_mfma_f32_16x16x32_bf16 v[42:45], v[138:141], v[178:181], v[42:45]
	v_mfma_f32_16x16x32_bf16 v[38:41], v[130:133], v[186:189], v[38:41]
	v_mfma_f32_16x16x32_bf16 v[34:37], v[138:141], v[186:189], v[34:37]
	v_mfma_f32_16x16x32_bf16 v[70:73], v[134:137], v[166:169], v[70:73]
	v_mfma_f32_16x16x32_bf16 v[66:69], v[142:145], v[166:169], v[66:69]
	v_mfma_f32_16x16x32_bf16 v[54:57], v[134:137], v[174:177], v[54:57]
	v_mfma_f32_16x16x32_bf16 v[50:53], v[142:145], v[174:177], v[50:53]
	v_mfma_f32_16x16x32_bf16 v[46:49], v[134:137], v[182:185], v[46:49]
	v_mfma_f32_16x16x32_bf16 v[42:45], v[142:145], v[182:185], v[42:45]
	v_mfma_f32_16x16x32_bf16 v[38:41], v[134:137], v[190:193], v[38:41]
	v_mfma_f32_16x16x32_bf16 v[34:37], v[142:145], v[190:193], v[34:37]
	s_setprio 0
	s_barrier
	s_add_i32 s37, s37, s62
	v_lshl_add_u64 v[226:227], s[52:53], 0, v[214:215]
	s_mov_b32 m0, s37
	ds_read_b128 v[186:189], v244 offset:16384
	ds_read_b128 v[190:193], v244 offset:17408
	ds_read_b128 v[178:181], v244 offset:18432
	ds_read_b128 v[182:185], v244 offset:19456
	ds_read_b128 v[170:173], v244 offset:20480
	ds_read_b128 v[174:177], v244 offset:21504
	ds_read_b128 v[162:165], v244 offset:22528
	ds_read_b128 v[166:169], v244 offset:23552
	global_load_lds_dwordx4 v[226:227], off
	s_add_i32 m0, s37, 0x2000
	s_add_u32 s42, s52, 0xb0000
	v_lshl_add_u64 v[228:229], s[52:53], 0, v[218:219]
	s_addc_u32 s43, s53, 0
	s_add_i32 s37, s78, s62
	global_load_lds_dwordx4 v[228:229], off
	s_mov_b32 m0, s37
	v_lshl_add_u64 v[230:231], s[54:55], 0, v[194:195]
	global_load_lds_dwordx4 v214, s[42:43]
	s_add_i32 m0, s37, 0x2000
	v_lshl_add_u64 v[232:233], s[54:55], 0, v[216:217]
	global_load_lds_dwordx4 v218, s[42:43]
	s_mov_b32 m0, s63
	v_cndmask_b32_e64 v200, 0, 1, s[50:51]
	global_load_lds_dwordx4 v[230:231], off
	s_mov_b32 m0, s64
	v_cmp_ne_u32_e64 s[42:43], 1, v200
	global_load_lds_dwordx4 v[232:233], off
	s_waitcnt vmcnt(8)
	s_waitcnt lgkmcnt(0)
	s_andn2_b64 vcc, exec, s[50:51]
	s_barrier
	s_cbranch_vccnz .LBB0_244
	s_setprio 1
	v_mfma_f32_16x16x32_bf16 v[94:97], v[146:149], v[186:189], v[94:97]
	v_mfma_f32_16x16x32_bf16 v[90:93], v[154:157], v[186:189], v[90:93]
	v_mfma_f32_16x16x32_bf16 v[86:89], v[146:149], v[178:181], v[86:89]
	v_mfma_f32_16x16x32_bf16 v[82:85], v[154:157], v[178:181], v[82:85]
	v_mfma_f32_16x16x32_bf16 v[78:81], v[146:149], v[170:173], v[78:81]
	v_mfma_f32_16x16x32_bf16 v[74:77], v[154:157], v[170:173], v[74:77]
	v_mfma_f32_16x16x32_bf16 v[62:65], v[146:149], v[162:165], v[62:65]
	v_mfma_f32_16x16x32_bf16 v[58:61], v[154:157], v[162:165], v[58:61]
	v_mfma_f32_16x16x32_bf16 v[94:97], v[150:153], v[190:193], v[94:97]
	v_mfma_f32_16x16x32_bf16 v[90:93], v[158:161], v[190:193], v[90:93]
	v_mfma_f32_16x16x32_bf16 v[86:89], v[150:153], v[182:185], v[86:89]
	v_mfma_f32_16x16x32_bf16 v[82:85], v[158:161], v[182:185], v[82:85]
	v_mfma_f32_16x16x32_bf16 v[78:81], v[150:153], v[174:177], v[78:81]
	v_mfma_f32_16x16x32_bf16 v[74:77], v[158:161], v[174:177], v[74:77]
	v_mfma_f32_16x16x32_bf16 v[62:65], v[150:153], v[166:169], v[62:65]
	v_mfma_f32_16x16x32_bf16 v[58:61], v[158:161], v[166:169], v[58:61]
	s_setprio 0
	s_setprio 1
	v_mfma_f32_16x16x32_bf16 v[30:33], v[130:133], v[186:189], v[30:33]
	v_mfma_f32_16x16x32_bf16 v[26:29], v[138:141], v[186:189], v[26:29]
	v_mfma_f32_16x16x32_bf16 v[22:25], v[130:133], v[178:181], v[22:25]
	v_mfma_f32_16x16x32_bf16 v[18:21], v[138:141], v[178:181], v[18:21]
	v_mfma_f32_16x16x32_bf16 v[14:17], v[130:133], v[170:173], v[14:17]
	v_mfma_f32_16x16x32_bf16 v[10:13], v[138:141], v[170:173], v[10:13]
	v_mfma_f32_16x16x32_bf16 v[6:9], v[130:133], v[162:165], v[6:9]
	v_mfma_f32_16x16x32_bf16 v[2:5], v[138:141], v[162:165], v[2:5]
	v_mfma_f32_16x16x32_bf16 v[30:33], v[134:137], v[190:193], v[30:33]
	v_mfma_f32_16x16x32_bf16 v[26:29], v[142:145], v[190:193], v[26:29]
	v_mfma_f32_16x16x32_bf16 v[22:25], v[134:137], v[182:185], v[22:25]
	v_mfma_f32_16x16x32_bf16 v[18:21], v[142:145], v[182:185], v[18:21]
	v_mfma_f32_16x16x32_bf16 v[14:17], v[134:137], v[174:177], v[14:17]
	v_mfma_f32_16x16x32_bf16 v[10:13], v[142:145], v[174:177], v[10:13]
	v_mfma_f32_16x16x32_bf16 v[6:9], v[134:137], v[166:169], v[6:9]
	v_mfma_f32_16x16x32_bf16 v[2:5], v[142:145], v[166:169], v[2:5]
	s_setprio 0
; #define PG8_STAGE(bufoff, gbase, voff) do { _Pragma("unroll") for (int _i = 0; _i < 2; ++_i) \
;         __builtin_amdgcn_global_load_lds((const unsigned*)((const char*)(gbase) + (voff)[_i]), (LAS unsigned*)(lds + (bufoff) + ldsw + _i * 8192), 16, 0, 0); } while (0)
; #define PG8_LDA(dst, b, h) do { _Pragma("unroll") for (int m = 0; m < 4; ++m) _Pragma("unroll") for (int k = 0; k < 2; ++k) dst[m][k] = *(const LAS f16x8*)(lds + PG8_SA(b, h) + aoff + m * 2048 + k * 1024); } while (0)
; #define PG8_LDB(dst, b, h) do { _Pragma("unroll") for (int n = 0; n < 2; ++n) _Pragma("unroll") for (int k = 0; k < 2; ++k) dst[n][k] = *(const LAS f16x8*)(lds + PG8_SB(b, h) + boff + n * 2048 + k * 1024); } while (0)
; #define PG8_MMA(ai, bj, At, Bt) do { __builtin_amdgcn_s_setprio(1); _Pragma("unroll") for (int m = 0; m < 4; ++m) _Pragma("unroll") for (int n = 0; n < 2; ++n) _Pragma("unroll") for (int k = 0; k < 2; ++k) \
;         acc[ai][bj][m][n] = mma16_<Epi::BF16>(Bt[n][k], At[m][k], acc[ai][bj][m][n]); __builtin_amdgcn_s_setprio(0); } while (0)
; #define PG8_WAIT_V(n) asm volatile("s_waitcnt vmcnt(" #n ")" ::: "memory")
; #define PG8_WAIT_L(n) asm volatile("s_waitcnt lgkmcnt(" #n ")" ::: "memory")
; #define PG8_BAR __builtin_amdgcn_s_barrier()
; #define PG8_SCHED __builtin_amdgcn_sched_barrier(0)
;     ...
;             PG8_LDB(B0, 1, 0); PG8_LDB(B1, 1, 1); PG8_SCHED; PG8_LDA(At, 1, 0); PG8_STAGE(PG8_SA(0, 1), a2 + hA, voffA);
;             PG8_WAIT_V(8); PG8_WAIT_L(0); PG8_BAR; PG8_MMA(0, 0, At, B0); PG8_MMA(0, 1, At, B1); PG8_BAR; PG8_SCHED;
;             PG8_LDA(At, 1, 1); PG8_STAGE(PG8_SB(1, 0), b3, voffB); PG8_STAGE(PG8_SB(1, 1), b3 + hB, voffB); PG8_STAGE(PG8_SA(1, 0), a3, voffA);
;             PG8_WAIT_V(8); PG8_WAIT_L(0); PG8_BAR; if (!cur.half) { PG8_MMA(1, 0, At, B0); PG8_MMA(1, 1, At, B1); } PG8_BAR; PG8_SCHED;
.LBB0_244:
	s_barrier
	s_add_i32 s37, 0, 0x18000
	s_add_i32 s78, 0, 0x1c000
	v_add_u32_e32 v130, s37, v243
	v_add_u32_e32 v142, s78, v243
	ds_read_b128 v[146:149], v130
	ds_read_b128 v[150:153], v130 offset:1024
	ds_read_b128 v[154:157], v130 offset:2048
	ds_read_b128 v[158:161], v130 offset:3072
	ds_read_b128 v[130:133], v142
	ds_read_b128 v[134:137], v142 offset:1024
	ds_read_b128 v[138:141], v142 offset:2048
	ds_read_b128 v[142:145], v142 offset:3072
	s_add_u32 s54, s54, 0xb0000
	s_addc_u32 s55, s55, 0
	s_mov_b32 m0, s65
	s_waitcnt lgkmcnt(0)
	ds_read_b128 v[162:165], v244 offset:32768
	ds_read_b128 v[166:169], v244 offset:33792
	ds_read_b128 v[170:173], v244 offset:34816
	ds_read_b128 v[174:177], v244 offset:35840
	ds_read_b128 v[178:181], v244 offset:36864
	ds_read_b128 v[182:185], v244 offset:37888
	ds_read_b128 v[186:189], v244 offset:38912
	ds_read_b128 v[190:193], v244 offset:39936
	global_load_lds_dwordx4 v194, s[54:55]
	s_mov_b32 m0, s66
	s_nop 0
	global_load_lds_dwordx4 v216, s[54:55]
	s_waitcnt vmcnt(8)
	s_waitcnt lgkmcnt(0)
	s_barrier
	s_setprio 1
	v_mfma_f32_16x16x32_bf16 v[126:129], v[146:149], v[162:165], v[126:129]
	v_mfma_f32_16x16x32_bf16 v[122:125], v[154:157], v[162:165], v[122:125]
	v_mfma_f32_16x16x32_bf16 v[118:121], v[146:149], v[170:173], v[118:121]
	v_mfma_f32_16x16x32_bf16 v[114:117], v[154:157], v[170:173], v[114:117]
	v_mfma_f32_16x16x32_bf16 v[110:113], v[146:149], v[178:181], v[110:113]
	v_mfma_f32_16x16x32_bf16 v[106:109], v[154:157], v[178:181], v[106:109]
	v_mfma_f32_16x16x32_bf16 v[102:105], v[146:149], v[186:189], v[102:105]
	v_mfma_f32_16x16x32_bf16 v[98:101], v[154:157], v[186:189], v[98:101]
	v_mfma_f32_16x16x32_bf16 v[126:129], v[150:153], v[166:169], v[126:129]
	v_mfma_f32_16x16x32_bf16 v[122:125], v[158:161], v[166:169], v[122:125]
	v_mfma_f32_16x16x32_bf16 v[118:121], v[150:153], v[174:177], v[118:121]
	v_mfma_f32_16x16x32_bf16 v[114:117], v[158:161], v[174:177], v[114:117]
	v_mfma_f32_16x16x32_bf16 v[110:113], v[150:153], v[182:185], v[110:113]
	v_mfma_f32_16x16x32_bf16 v[106:109], v[158:161], v[182:185], v[106:109]
	v_mfma_f32_16x16x32_bf16 v[102:105], v[150:153], v[190:193], v[102:105]
	v_mfma_f32_16x16x32_bf16 v[98:101], v[158:161], v[190:193], v[98:101]
	s_setprio 0
	s_setprio 1
	v_mfma_f32_16x16x32_bf16 v[70:73], v[130:133], v[162:165], v[70:73]
	v_mfma_f32_16x16x32_bf16 v[66:69], v[138:141], v[162:165], v[66:69]
	v_mfma_f32_16x16x32_bf16 v[54:57], v[130:133], v[170:173], v[54:57]
	v_mfma_f32_16x16x32_bf16 v[50:53], v[138:141], v[170:173], v[50:53]
	v_mfma_f32_16x16x32_bf16 v[46:49], v[130:133], v[178:181], v[46:49]
	v_mfma_f32_16x16x32_bf16 v[42:45], v[138:141], v[178:181], v[42:45]
	v_mfma_f32_16x16x32_bf16 v[38:41], v[130:133], v[186:189], v[38:41]
	v_mfma_f32_16x16x32_bf16 v[34:37], v[138:141], v[186:189], v[34:37]
	v_mfma_f32_16x16x32_bf16 v[70:73], v[134:137], v[166:169], v[70:73]
	v_mfma_f32_16x16x32_bf16 v[66:69], v[142:145], v[166:169], v[66:69]
	v_mfma_f32_16x16x32_bf16 v[54:57], v[134:137], v[174:177], v[54:57]
	v_mfma_f32_16x16x32_bf16 v[50:53], v[142:145], v[174:177], v[50:53]
	v_mfma_f32_16x16x32_bf16 v[46:49], v[134:137], v[182:185], v[46:49]
	v_mfma_f32_16x16x32_bf16 v[42:45], v[142:145], v[182:185], v[42:45]
	v_mfma_f32_16x16x32_bf16 v[38:41], v[134:137], v[190:193], v[38:41]
	v_mfma_f32_16x16x32_bf16 v[34:37], v[142:145], v[190:193], v[34:37]
	s_setprio 0
	s_barrier
	s_add_i32 s37, s37, s62
	v_lshl_add_u64 v[200:201], v[226:227], 0, s[96:97]
	s_mov_b32 m0, s37
	ds_read_b128 v[186:189], v244 offset:49152
	ds_read_b128 v[190:193], v244 offset:50176
	ds_read_b128 v[178:181], v244 offset:51200
	ds_read_b128 v[182:185], v244 offset:52224
	ds_read_b128 v[170:173], v244 offset:53248
	ds_read_b128 v[174:177], v244 offset:54272
	ds_read_b128 v[162:165], v244 offset:55296
	ds_read_b128 v[166:169], v244 offset:56320
	global_load_lds_dwordx4 v[200:201], off
	s_add_i32 m0, s37, 0x2000
	s_add_u32 s52, s52, 0xb0080
	v_lshl_add_u64 v[200:201], v[228:229], 0, s[96:97]
	s_addc_u32 s53, s53, 0
	s_add_i32 s37, s78, s62
	global_load_lds_dwordx4 v[200:201], off
	s_mov_b32 m0, s37
	s_and_b64 vcc, exec, s[42:43]
	global_load_lds_dwordx4 v214, s[52:53]
	s_add_i32 m0, s37, 0x2000
	s_nop 0
	global_load_lds_dwordx4 v218, s[52:53]
	v_lshl_add_u64 v[200:201], v[230:231], 0, s[96:97]
	s_mov_b32 m0, s0
	s_nop 0
	global_load_lds_dwordx4 v[200:201], off
	v_lshl_add_u64 v[200:201], v[232:233], 0, s[96:97]
	s_mov_b32 m0, s69
	s_nop 0
	global_load_lds_dwordx4 v[200:201], off
	s_waitcnt vmcnt(8)
	s_waitcnt lgkmcnt(0)
	s_barrier
	s_cbranch_vccnz .LBB0_241
	s_setprio 1
	v_mfma_f32_16x16x32_bf16 v[94:97], v[146:149], v[186:189], v[94:97]
	v_mfma_f32_16x16x32_bf16 v[90:93], v[154:157], v[186:189], v[90:93]
	v_mfma_f32_16x16x32_bf16 v[86:89], v[146:149], v[178:181], v[86:89]
	v_mfma_f32_16x16x32_bf16 v[82:85], v[154:157], v[178:181], v[82:85]
	v_mfma_f32_16x16x32_bf16 v[78:81], v[146:149], v[170:173], v[78:81]
	v_mfma_f32_16x16x32_bf16 v[74:77], v[154:157], v[170:173], v[74:77]
	v_mfma_f32_16x16x32_bf16 v[62:65], v[146:149], v[162:165], v[62:65]
	v_mfma_f32_16x16x32_bf16 v[58:61], v[154:157], v[162:165], v[58:61]
	v_mfma_f32_16x16x32_bf16 v[94:97], v[150:153], v[190:193], v[94:97]
	v_mfma_f32_16x16x32_bf16 v[90:93], v[158:161], v[190:193], v[90:93]
	v_mfma_f32_16x16x32_bf16 v[86:89], v[150:153], v[182:185], v[86:89]
	v_mfma_f32_16x16x32_bf16 v[82:85], v[158:161], v[182:185], v[82:85]
	v_mfma_f32_16x16x32_bf16 v[78:81], v[150:153], v[174:177], v[78:81]
	v_mfma_f32_16x16x32_bf16 v[74:77], v[158:161], v[174:177], v[74:77]
	v_mfma_f32_16x16x32_bf16 v[62:65], v[150:153], v[166:169], v[62:65]
	v_mfma_f32_16x16x32_bf16 v[58:61], v[158:161], v[166:169], v[58:61]
	s_setprio 0
	s_setprio 1
	v_mfma_f32_16x16x32_bf16 v[30:33], v[130:133], v[186:189], v[30:33]
	v_mfma_f32_16x16x32_bf16 v[26:29], v[138:141], v[186:189], v[26:29]
	v_mfma_f32_16x16x32_bf16 v[22:25], v[130:133], v[178:181], v[22:25]
	v_mfma_f32_16x16x32_bf16 v[18:21], v[138:141], v[178:181], v[18:21]
	v_mfma_f32_16x16x32_bf16 v[14:17], v[130:133], v[170:173], v[14:17]
	v_mfma_f32_16x16x32_bf16 v[10:13], v[138:141], v[170:173], v[10:13]
	v_mfma_f32_16x16x32_bf16 v[6:9], v[130:133], v[162:165], v[6:9]
	v_mfma_f32_16x16x32_bf16 v[2:5], v[138:141], v[162:165], v[2:5]
	v_mfma_f32_16x16x32_bf16 v[30:33], v[134:137], v[190:193], v[30:33]
	v_mfma_f32_16x16x32_bf16 v[26:29], v[142:145], v[190:193], v[26:29]
	v_mfma_f32_16x16x32_bf16 v[22:25], v[134:137], v[182:185], v[22:25]
	v_mfma_f32_16x16x32_bf16 v[18:21], v[142:145], v[182:185], v[18:21]
	v_mfma_f32_16x16x32_bf16 v[14:17], v[134:137], v[174:177], v[14:17]
	v_mfma_f32_16x16x32_bf16 v[10:13], v[142:145], v[174:177], v[10:13]
	v_mfma_f32_16x16x32_bf16 v[6:9], v[134:137], v[166:169], v[6:9]
	v_mfma_f32_16x16x32_bf16 v[2:5], v[142:145], v[166:169], v[2:5]
	s_setprio 0
	s_branch .LBB0_241

; #define PG8_STAGE(bufoff, gbase, voff) do { _Pragma("unroll") for (int _i = 0; _i < 2; ++_i) \
;         __builtin_amdgcn_global_load_lds((const unsigned*)((const char*)(gbase) + (voff)[_i]), (LAS unsigned*)(lds + (bufoff) + ldsw + _i * 8192), 16, 0, 0); } while (0)
; #define PG8_LDA(dst, b, h) do { _Pragma("unroll") for (int m = 0; m < 4; ++m) _Pragma("unroll") for (int k = 0; k < 2; ++k) dst[m][k] = *(const LAS f16x8*)(lds + PG8_SA(b, h) + aoff + m * 2048 + k * 1024); } while (0)
; #define PG8_LDB(dst, b, h) do { _Pragma("unroll") for (int n = 0; n < 2; ++n) _Pragma("unroll") for (int k = 0; k < 2; ++k) dst[n][k] = *(const LAS f16x8*)(lds + PG8_SB(b, h) + boff + n * 2048 + k * 1024); } while (0)
; #define PG8_MMA(ai, bj, At, Bt) do { __builtin_amdgcn_s_setprio(1); _Pragma("unroll") for (int m = 0; m < 4; ++m) _Pragma("unroll") for (int n = 0; n < 2; ++n) _Pragma("unroll") for (int k = 0; k < 2; ++k) \
;         acc[ai][bj][m][n] = mma16_<Epi::BF16>(Bt[n][k], At[m][k], acc[ai][bj][m][n]); __builtin_amdgcn_s_setprio(0); } while (0)
; #define PG8_WAIT_V(n) asm volatile("s_waitcnt vmcnt(" #n ")" ::: "memory")
; #define PG8_WAIT_L(n) asm volatile("s_waitcnt lgkmcnt(" #n ")" ::: "memory")
; #define PG8_BAR __builtin_amdgcn_s_barrier()
; #define PG8_SCHED __builtin_amdgcn_sched_barrier(0)
;     ...
;         const char* nA = has_next ? (const char*)g.A + (size_t)nxt.pm * tA + (nxt.roff ? hA : (size_t)0) : cA; const char* nB = has_next ? (const char*)g.Bt + (size_t)nxt.pn * tB : cB;
;         for (int t = 0; t < nt; t += 2) {
;             const bool last = (t == nt - 2);
;             const char* a1 = cA + (size_t)(t + 1) * kstep;
;             const char* a2 = last ? nA : cA + (size_t)(t + 2) * kstep; const char* b2 = last ? nB : cB + (size_t)(t + 2) * kstep;
;             const char* a3 = a2 + kstep; const char* b3 = b2 + kstep;
;             if constexpr (SP2) {
;             PG8_LDB(B0, 0, 0); PG8_LDB(B1, 0, 1); PG8_SCHED; PG8_LDA(At, 0, 0); PG8_STAGE(PG8_SA(1, 1), a1 + hA, voffA);
;             PG8_WAIT_V(8); PG8_WAIT_L(0); PG8_BAR; PG8_MMA(0, 0, At, B0); PG8_MMA(0, 1, At, B1); PG8_BAR; PG8_SCHED;
;             PG8_LDA(At, 0, 1); PG8_STAGE(PG8_SB(0, 0), b2, voffB); PG8_STAGE(PG8_SB(0, 1), b2 + hB, voffB); PG8_STAGE(PG8_SA(0, 0), a2, voffA);
.LBB0_516:
	s_add_u32 s28, s26, 0xfffc0080
	s_addc_u32 s29, s27, -1
	s_add_i32 s50, 0, 0x10000
	s_cmp_eq_u32 s49, 12
	s_cselect_b32 s31, s2, s29
	s_cselect_b32 s30, s3, s28
	v_add_u32_e32 v142, s50, v145
	s_cselect_b32 s29, s19, s48
	s_cselect_b32 s28, s21, s47
	s_add_i32 s52, 0, 0x14000
	ds_read_b128 v[148:151], v142
	ds_read_b128 v[152:155], v142 offset:1024
	ds_read_b128 v[156:159], v142 offset:2048
	ds_read_b128 v[160:163], v142 offset:3072
	v_add_u32_e32 v142, s52, v145
	ds_read_b128 v[164:167], v142
	ds_read_b128 v[168:171], v142 offset:1024
	ds_read_b128 v[172:175], v142 offset:2048
	ds_read_b128 v[176:179], v142 offset:3072
	s_add_i32 m0, s17, 0xc000
	ds_read_b128 v[180:183], v147
	ds_read_b128 v[184:187], v147 offset:1024
	ds_read_b128 v[188:191], v147 offset:2048
	ds_read_b128 v[192:195], v147 offset:3072
	ds_read_b128 v[214:217], v147 offset:4096
	ds_read_b128 v[218:221], v147 offset:5120
	ds_read_b128 v[222:225], v147 offset:6144
	ds_read_b128 v[226:229], v147 offset:7168
	global_load_lds_dwordx4 v138, s[26:27]
	s_add_i32 m0, s17, 0xe000
	s_nop 0
	global_load_lds_dwordx4 v140, s[26:27]
	s_waitcnt vmcnt(8)
	s_waitcnt lgkmcnt(0)
	s_barrier
	s_setprio 1
	v_mfma_f32_16x16x32_bf16 v[126:129], v[148:151], v[180:183], v[126:129]
	v_mfma_f32_16x16x32_bf16 v[122:125], v[156:159], v[180:183], v[122:125]
	v_mfma_f32_16x16x32_bf16 v[118:121], v[148:151], v[188:191], v[118:121]
	v_mfma_f32_16x16x32_bf16 v[114:117], v[156:159], v[188:191], v[114:117]
	v_mfma_f32_16x16x32_bf16 v[102:105], v[148:151], v[214:217], v[102:105]
	v_mfma_f32_16x16x32_bf16 v[98:101], v[156:159], v[214:217], v[98:101]
	v_mfma_f32_16x16x32_bf16 v[86:89], v[148:151], v[222:225], v[86:89]
	v_mfma_f32_16x16x32_bf16 v[82:85], v[156:159], v[222:225], v[82:85]
	v_mfma_f32_16x16x32_bf16 v[126:129], v[152:155], v[184:187], v[126:129]
	v_mfma_f32_16x16x32_bf16 v[122:125], v[160:163], v[184:187], v[122:125]
	v_mfma_f32_16x16x32_bf16 v[118:121], v[152:155], v[192:195], v[118:121]
	v_mfma_f32_16x16x32_bf16 v[114:117], v[160:163], v[192:195], v[114:117]
	v_mfma_f32_16x16x32_bf16 v[102:105], v[152:155], v[218:221], v[102:105]
	v_mfma_f32_16x16x32_bf16 v[98:101], v[160:163], v[218:221], v[98:101]
	v_mfma_f32_16x16x32_bf16 v[86:89], v[152:155], v[226:229], v[86:89]
	v_mfma_f32_16x16x32_bf16 v[82:85], v[160:163], v[226:229], v[82:85]
	s_setprio 0
	s_setprio 1
	v_mfma_f32_16x16x32_bf16 v[110:113], v[164:167], v[180:183], v[110:113]
	v_mfma_f32_16x16x32_bf16 v[106:109], v[172:175], v[180:183], v[106:109]
	v_mfma_f32_16x16x32_bf16 v[94:97], v[164:167], v[188:191], v[94:97]
	v_mfma_f32_16x16x32_bf16 v[90:93], v[172:175], v[188:191], v[90:93]
	v_mfma_f32_16x16x32_bf16 v[78:81], v[164:167], v[214:217], v[78:81]
	v_mfma_f32_16x16x32_bf16 v[74:77], v[172:175], v[214:217], v[74:77]
	v_mfma_f32_16x16x32_bf16 v[70:73], v[164:167], v[222:225], v[70:73]
	v_mfma_f32_16x16x32_bf16 v[66:69], v[172:175], v[222:225], v[66:69]
	v_mfma_f32_16x16x32_bf16 v[110:113], v[168:171], v[184:187], v[110:113]
	v_mfma_f32_16x16x32_bf16 v[106:109], v[176:179], v[184:187], v[106:109]
	v_mfma_f32_16x16x32_bf16 v[94:97], v[168:171], v[192:195], v[94:97]
	v_mfma_f32_16x16x32_bf16 v[90:93], v[176:179], v[192:195], v[90:93]
	v_mfma_f32_16x16x32_bf16 v[78:81], v[168:171], v[218:221], v[78:81]
	v_mfma_f32_16x16x32_bf16 v[74:77], v[176:179], v[218:221], v[74:77]
	v_mfma_f32_16x16x32_bf16 v[70:73], v[168:171], v[226:229], v[70:73]
	v_mfma_f32_16x16x32_bf16 v[66:69], v[176:179], v[226:229], v[66:69]
	s_setprio 0
	s_barrier
	s_add_i32 s50, s50, s34
	v_lshl_add_u64 v[142:143], s[28:29], 0, v[0:1]
	s_mov_b32 m0, s50
	ds_read_b128 v[180:183], v147 offset:16384
	ds_read_b128 v[184:187], v147 offset:17408
	ds_read_b128 v[188:191], v147 offset:18432
	ds_read_b128 v[192:195], v147 offset:19456
	ds_read_b128 v[214:217], v147 offset:20480
	ds_read_b128 v[218:221], v147 offset:21504
	ds_read_b128 v[222:225], v147 offset:22528
	ds_read_b128 v[226:229], v147 offset:23552
	global_load_lds_dwordx4 v[142:143], off
	s_add_i32 m0, s50, 0x2000
	s_add_u32 s50, s28, 0x40000
	v_lshl_add_u64 v[200:201], s[28:29], 0, v[130:131]
	s_addc_u32 s51, s29, 0
	s_add_i32 s52, s52, s34
	global_load_lds_dwordx4 v[200:201], off
	s_mov_b32 m0, s52
	v_lshl_add_u64 v[230:231], s[30:31], 0, v[132:133]
	global_load_lds_dwordx4 v0, s[50:51]
	s_add_i32 m0, s52, 0x2000
	s_nop 0
	global_load_lds_dwordx4 v130, s[50:51]
	v_lshl_add_u64 v[202:203], s[30:31], 0, v[134:135]
	s_mov_b32 m0, s17
	s_nop 0
	global_load_lds_dwordx4 v[202:203], off
	s_mov_b32 m0, s36
	s_nop 0
	global_load_lds_dwordx4 v[230:231], off
	s_waitcnt vmcnt(8)
	s_waitcnt lgkmcnt(0)
	s_barrier
; #define PG8_STAGE(bufoff, gbase, voff) do { _Pragma("unroll") for (int _i = 0; _i < 2; ++_i) \
;         __builtin_amdgcn_global_load_lds((const unsigned*)((const char*)(gbase) + (voff)[_i]), (LAS unsigned*)(lds + (bufoff) + ldsw + _i * 8192), 16, 0, 0); } while (0)
; #define PG8_LDA(dst, b, h) do { _Pragma("unroll") for (int m = 0; m < 4; ++m) _Pragma("unroll") for (int k = 0; k < 2; ++k) dst[m][k] = *(const LAS f16x8*)(lds + PG8_SA(b, h) + aoff + m * 2048 + k * 1024); } while (0)
; #define PG8_LDB(dst, b, h) do { _Pragma("unroll") for (int n = 0; n < 2; ++n) _Pragma("unroll") for (int k = 0; k < 2; ++k) dst[n][k] = *(const LAS f16x8*)(lds + PG8_SB(b, h) + boff + n * 2048 + k * 1024); } while (0)
; #define PG8_MMA(ai, bj, At, Bt) do { __builtin_amdgcn_s_setprio(1); _Pragma("unroll") for (int m = 0; m < 4; ++m) _Pragma("unroll") for (int n = 0; n < 2; ++n) _Pragma("unroll") for (int k = 0; k < 2; ++k) \
;         acc[ai][bj][m][n] = mma16_<Epi::BF16>(Bt[n][k], At[m][k], acc[ai][bj][m][n]); __builtin_amdgcn_s_setprio(0); } while (0)
; #define PG8_WAIT_V(n) asm volatile("s_waitcnt vmcnt(" #n ")" ::: "memory")
; #define PG8_WAIT_L(n) asm volatile("s_waitcnt lgkmcnt(" #n ")" ::: "memory")
; #define PG8_BAR __builtin_amdgcn_s_barrier()
; #define PG8_SCHED __builtin_amdgcn_sched_barrier(0)
;     ...
;             PG8_WAIT_V(8); PG8_WAIT_L(0); PG8_BAR; if (!cur.half) { PG8_MMA(1, 0, At, B0); PG8_MMA(1, 1, At, B1); } PG8_BAR; PG8_SCHED;
;             PG8_LDB(B0, 1, 0); PG8_LDB(B1, 1, 1); PG8_SCHED; PG8_LDA(At, 1, 0); PG8_STAGE(PG8_SA(0, 1), a2 + hA, voffA);
;             PG8_WAIT_V(8); PG8_WAIT_L(0); PG8_BAR; PG8_MMA(0, 0, At, B0); PG8_MMA(0, 1, At, B1); PG8_BAR; PG8_SCHED;
	s_setprio 1
	v_mfma_f32_16x16x32_bf16 v[62:65], v[148:151], v[180:183], v[62:65]
	v_mfma_f32_16x16x32_bf16 v[58:61], v[156:159], v[180:183], v[58:61]
	v_mfma_f32_16x16x32_bf16 v[54:57], v[148:151], v[188:191], v[54:57]
	v_mfma_f32_16x16x32_bf16 v[50:53], v[156:159], v[188:191], v[50:53]
	v_mfma_f32_16x16x32_bf16 v[38:41], v[148:151], v[214:217], v[38:41]
	v_mfma_f32_16x16x32_bf16 v[34:37], v[156:159], v[214:217], v[34:37]
	v_mfma_f32_16x16x32_bf16 v[22:25], v[148:151], v[222:225], v[22:25]
	v_mfma_f32_16x16x32_bf16 v[18:21], v[156:159], v[222:225], v[18:21]
	v_mfma_f32_16x16x32_bf16 v[62:65], v[152:155], v[184:187], v[62:65]
	v_mfma_f32_16x16x32_bf16 v[58:61], v[160:163], v[184:187], v[58:61]
	v_mfma_f32_16x16x32_bf16 v[54:57], v[152:155], v[192:195], v[54:57]
	v_mfma_f32_16x16x32_bf16 v[50:53], v[160:163], v[192:195], v[50:53]
	v_mfma_f32_16x16x32_bf16 v[38:41], v[152:155], v[218:221], v[38:41]
	v_mfma_f32_16x16x32_bf16 v[34:37], v[160:163], v[218:221], v[34:37]
	v_mfma_f32_16x16x32_bf16 v[22:25], v[152:155], v[226:229], v[22:25]
	v_mfma_f32_16x16x32_bf16 v[18:21], v[160:163], v[226:229], v[18:21]
	s_setprio 0
	s_setprio 1
	v_mfma_f32_16x16x32_bf16 v[46:49], v[164:167], v[180:183], v[46:49]
	v_mfma_f32_16x16x32_bf16 v[42:45], v[172:175], v[180:183], v[42:45]
	v_mfma_f32_16x16x32_bf16 v[30:33], v[164:167], v[188:191], v[30:33]
	v_mfma_f32_16x16x32_bf16 v[26:29], v[172:175], v[188:191], v[26:29]
	v_mfma_f32_16x16x32_bf16 v[14:17], v[164:167], v[214:217], v[14:17]
	v_mfma_f32_16x16x32_bf16 v[10:13], v[172:175], v[214:217], v[10:13]
	v_mfma_f32_16x16x32_bf16 v[6:9], v[164:167], v[222:225], v[6:9]
	v_mfma_f32_16x16x32_bf16 v[2:5], v[172:175], v[222:225], v[2:5]
	v_mfma_f32_16x16x32_bf16 v[46:49], v[168:171], v[184:187], v[46:49]
	v_mfma_f32_16x16x32_bf16 v[42:45], v[176:179], v[184:187], v[42:45]
	v_mfma_f32_16x16x32_bf16 v[30:33], v[168:171], v[192:195], v[30:33]
	v_mfma_f32_16x16x32_bf16 v[26:29], v[176:179], v[192:195], v[26:29]
	v_mfma_f32_16x16x32_bf16 v[14:17], v[168:171], v[218:221], v[14:17]
	v_mfma_f32_16x16x32_bf16 v[10:13], v[176:179], v[218:221], v[10:13]
	v_mfma_f32_16x16x32_bf16 v[6:9], v[168:171], v[226:229], v[6:9]
	v_mfma_f32_16x16x32_bf16 v[2:5], v[176:179], v[226:229], v[2:5]
	s_setprio 0
	s_barrier
	s_add_i32 s50, 0, 0x18000
	s_add_i32 s51, 0, 0x1c000
	v_add_u32_e32 v160, s50, v145
	v_add_u32_e32 v176, s51, v145
	ds_read_b128 v[148:151], v160
	ds_read_b128 v[152:155], v160 offset:1024
	ds_read_b128 v[156:159], v160 offset:2048
	ds_read_b128 v[160:163], v160 offset:3072
	ds_read_b128 v[164:167], v176
	ds_read_b128 v[168:171], v176 offset:1024
	ds_read_b128 v[172:175], v176 offset:2048
	ds_read_b128 v[176:179], v176 offset:3072
	s_add_u32 s30, s30, 0x40000
	s_addc_u32 s31, s31, 0
	s_mov_b32 m0, s37
	ds_read_b128 v[180:183], v147 offset:32768
	ds_read_b128 v[184:187], v147 offset:33792
	ds_read_b128 v[188:191], v147 offset:34816
	ds_read_b128 v[192:195], v147 offset:35840
	ds_read_b128 v[214:217], v147 offset:36864
	ds_read_b128 v[218:221], v147 offset:37888
	ds_read_b128 v[222:225], v147 offset:38912
	ds_read_b128 v[226:229], v147 offset:39936
	global_load_lds_dwordx4 v134, s[30:31]
	s_mov_b32 m0, s40
	s_nop 0
	global_load_lds_dwordx4 v132, s[30:31]
	s_waitcnt vmcnt(8)
	s_waitcnt lgkmcnt(0)
	s_barrier
	s_setprio 1
	v_mfma_f32_16x16x32_bf16 v[126:129], v[148:151], v[180:183], v[126:129]
	v_mfma_f32_16x16x32_bf16 v[122:125], v[156:159], v[180:183], v[122:125]
	v_mfma_f32_16x16x32_bf16 v[118:121], v[148:151], v[188:191], v[118:121]
	v_mfma_f32_16x16x32_bf16 v[114:117], v[156:159], v[188:191], v[114:117]
	v_mfma_f32_16x16x32_bf16 v[102:105], v[148:151], v[214:217], v[102:105]
	v_mfma_f32_16x16x32_bf16 v[98:101], v[156:159], v[214:217], v[98:101]
	v_mfma_f32_16x16x32_bf16 v[86:89], v[148:151], v[222:225], v[86:89]
	v_mfma_f32_16x16x32_bf16 v[82:85], v[156:159], v[222:225], v[82:85]
	v_mfma_f32_16x16x32_bf16 v[126:129], v[152:155], v[184:187], v[126:129]
	v_mfma_f32_16x16x32_bf16 v[122:125], v[160:163], v[184:187], v[122:125]
	v_mfma_f32_16x16x32_bf16 v[118:121], v[152:155], v[192:195], v[118:121]
	v_mfma_f32_16x16x32_bf16 v[114:117], v[160:163], v[192:195], v[114:117]
	v_mfma_f32_16x16x32_bf16 v[102:105], v[152:155], v[218:221], v[102:105]
	v_mfma_f32_16x16x32_bf16 v[98:101], v[160:163], v[218:221], v[98:101]
	v_mfma_f32_16x16x32_bf16 v[86:89], v[152:155], v[226:229], v[86:89]
	v_mfma_f32_16x16x32_bf16 v[82:85], v[160:163], v[226:229], v[82:85]
	s_setprio 0
	s_setprio 1
	v_mfma_f32_16x16x32_bf16 v[110:113], v[164:167], v[180:183], v[110:113]
	v_mfma_f32_16x16x32_bf16 v[106:109], v[172:175], v[180:183], v[106:109]
	v_mfma_f32_16x16x32_bf16 v[94:97], v[164:167], v[188:191], v[94:97]
	v_mfma_f32_16x16x32_bf16 v[90:93], v[172:175], v[188:191], v[90:93]
	v_mfma_f32_16x16x32_bf16 v[78:81], v[164:167], v[214:217], v[78:81]
	v_mfma_f32_16x16x32_bf16 v[74:77], v[172:175], v[214:217], v[74:77]
	v_mfma_f32_16x16x32_bf16 v[70:73], v[164:167], v[222:225], v[70:73]
	v_mfma_f32_16x16x32_bf16 v[66:69], v[172:175], v[222:225], v[66:69]
	v_mfma_f32_16x16x32_bf16 v[110:113], v[168:171], v[184:187], v[110:113]
	v_mfma_f32_16x16x32_bf16 v[106:109], v[176:179], v[184:187], v[106:109]
	v_mfma_f32_16x16x32_bf16 v[94:97], v[168:171], v[192:195], v[94:97]
	v_mfma_f32_16x16x32_bf16 v[90:93], v[176:179], v[192:195], v[90:93]
	v_mfma_f32_16x16x32_bf16 v[78:81], v[168:171], v[218:221], v[78:81]
	v_mfma_f32_16x16x32_bf16 v[74:77], v[176:179], v[218:221], v[74:77]
	v_mfma_f32_16x16x32_bf16 v[70:73], v[168:171], v[226:229], v[70:73]
	v_mfma_f32_16x16x32_bf16 v[66:69], v[176:179], v[226:229], v[66:69]
	s_setprio 0
	s_barrier
; #define PG8_STAGE(bufoff, gbase, voff) do { _Pragma("unroll") for (int _i = 0; _i < 2; ++_i) \
;         __builtin_amdgcn_global_load_lds((const unsigned*)((const char*)(gbase) + (voff)[_i]), (LAS unsigned*)(lds + (bufoff) + ldsw + _i * 8192), 16, 0, 0); } while (0)
; #define PG8_WAIT_V(n) asm volatile("s_waitcnt vmcnt(" #n ")" ::: "memory")
; #define PG8_WAIT_L(n) asm volatile("s_waitcnt lgkmcnt(" #n ")" ::: "memory")
;     ...
;             PG8_LDA(At, 1, 1); PG8_STAGE(PG8_SB(1, 0), b3, voffB); PG8_STAGE(PG8_SB(1, 1), b3 + hB, voffB); PG8_STAGE(PG8_SA(1, 0), a3, voffA);
;             PG8_WAIT_V(8); PG8_WAIT_L(0); PG8_BAR; if (!cur.half) { PG8_MMA(1, 0, At, B0); PG8_MMA(1, 1, At, B1); } PG8_BAR; PG8_SCHED;
;             } else {
;             PG8_LDB(B0, 0, 0); PG8_SCHED; PG8_LDA(At, 0, 0); PG8_STAGE(PG8_SA(1, 1), a1 + hA, voffA);
;             PG8_WAIT_L(8); PG8_BAR; PG8_WAIT_L(0); PG8_MMA(0, 0, At, B0); PG8_BAR; PG8_SCHED;
;             PG8_LDB(B1, 0, 1); PG8_STAGE(PG8_SB(0, 0), b2, voffB);
;             PG8_BAR; PG8_WAIT_L(0); PG8_MMA(0, 1, At, B1); PG8_BAR;
;             PG8_LDA(At, 0, 1); PG8_STAGE(PG8_SA(0, 0), a2, voffA);
;             PG8_BAR; PG8_WAIT_L(0); if (!cur.half) PG8_MMA(1, 0, At, B0); PG8_BAR; PG8_SCHED;
;             PG8_STAGE(PG8_SB(0, 1), b2 + hB, voffB);
;             PG8_WAIT_V(6); PG8_BAR; if (!cur.half) PG8_MMA(1, 1, At, B1); PG8_BAR;
;             PG8_LDB(B0, 1, 0); PG8_SCHED; PG8_LDA(At, 1, 0); PG8_STAGE(PG8_SA(0, 1), a2 + hA, voffA);
;             PG8_WAIT_L(8); PG8_BAR; PG8_WAIT_L(0); PG8_MMA(0, 0, At, B0); PG8_BAR; PG8_SCHED;
;             PG8_LDB(B1, 1, 1); PG8_STAGE(PG8_SB(1, 0), b3, voffB);
;             PG8_BAR; PG8_WAIT_L(0); PG8_MMA(0, 1, At, B1); PG8_BAR;
;             PG8_LDA(At, 1, 1); PG8_STAGE(PG8_SA(1, 0), a3, voffA);
;             PG8_BAR; PG8_WAIT_L(0); if (!cur.half) PG8_MMA(1, 0, At, B0); PG8_BAR; PG8_SCHED;
;             PG8_STAGE(PG8_SB(1, 1), b3 + hB, voffB);
;             PG8_WAIT_V(6); PG8_BAR; if (!cur.half) PG8_MMA(1, 1, At, B1); PG8_BAR;
;             }
;         }
;         if constexpr (ALIGN_EPI) { if (wr == 0) PG8_BAR; }
;     __device__ __forceinline__ void operator()(const f32x4 (&acc)[2][2][4][2], const Unit& u, int wr, int wc, int fr, int fq) const {
;         const int row0 = u.pm * 256 + wr * 64 + fr;
;         if (u.pn < 26) {
;             const int col0 = u.pn * 256 + wc * 32 + 8 * fq;
	s_add_i32 s30, s50, s34
	v_lshl_add_u64 v[142:143], v[142:143], 0, s[96:97]
	s_mov_b32 m0, s30
	ds_read_b128 v[180:183], v147 offset:49152
	ds_read_b128 v[184:187], v147 offset:50176
	ds_read_b128 v[188:191], v147 offset:51200
	ds_read_b128 v[192:195], v147 offset:52224
	ds_read_b128 v[214:217], v147 offset:53248
	ds_read_b128 v[218:221], v147 offset:54272
	ds_read_b128 v[222:225], v147 offset:55296
	ds_read_b128 v[226:229], v147 offset:56320
	global_load_lds_dwordx4 v[142:143], off
	s_add_i32 m0, s30, 0x2000
	s_add_u32 s28, s28, 0x40080
	v_lshl_add_u64 v[142:143], v[200:201], 0, s[96:97]
	s_addc_u32 s29, s29, 0
	s_add_i32 s30, s51, s34
	global_load_lds_dwordx4 v[142:143], off
	s_mov_b32 m0, s30
	s_nop 0
	global_load_lds_dwordx4 v0, s[28:29]
	s_add_i32 m0, s30, 0x2000
	s_nop 0
	global_load_lds_dwordx4 v130, s[28:29]
	v_lshl_add_u64 v[142:143], v[202:203], 0, s[96:97]
	s_mov_b32 m0, s41
	s_nop 0
	global_load_lds_dwordx4 v[142:143], off
	v_lshl_add_u64 v[142:143], v[230:231], 0, s[96:97]
	s_mov_b32 m0, s42
	s_nop 0
	global_load_lds_dwordx4 v[142:143], off
	s_waitcnt vmcnt(8)
	s_waitcnt lgkmcnt(0)
	s_barrier
	s_setprio 1
	v_mfma_f32_16x16x32_bf16 v[62:65], v[148:151], v[180:183], v[62:65]
	v_mfma_f32_16x16x32_bf16 v[58:61], v[156:159], v[180:183], v[58:61]
	v_mfma_f32_16x16x32_bf16 v[54:57], v[148:151], v[188:191], v[54:57]
	v_mfma_f32_16x16x32_bf16 v[50:53], v[156:159], v[188:191], v[50:53]
	v_mfma_f32_16x16x32_bf16 v[38:41], v[148:151], v[214:217], v[38:41]
	v_mfma_f32_16x16x32_bf16 v[34:37], v[156:159], v[214:217], v[34:37]
	v_mfma_f32_16x16x32_bf16 v[22:25], v[148:151], v[222:225], v[22:25]
	v_mfma_f32_16x16x32_bf16 v[18:21], v[156:159], v[222:225], v[18:21]
	v_mfma_f32_16x16x32_bf16 v[62:65], v[152:155], v[184:187], v[62:65]
	v_mfma_f32_16x16x32_bf16 v[58:61], v[160:163], v[184:187], v[58:61]
	v_mfma_f32_16x16x32_bf16 v[54:57], v[152:155], v[192:195], v[54:57]
	v_mfma_f32_16x16x32_bf16 v[50:53], v[160:163], v[192:195], v[50:53]
	v_mfma_f32_16x16x32_bf16 v[38:41], v[152:155], v[218:221], v[38:41]
	v_mfma_f32_16x16x32_bf16 v[34:37], v[160:163], v[218:221], v[34:37]
	v_mfma_f32_16x16x32_bf16 v[22:25], v[152:155], v[226:229], v[22:25]
	v_mfma_f32_16x16x32_bf16 v[18:21], v[160:163], v[226:229], v[18:21]
	s_setprio 0
	s_setprio 1
	v_mfma_f32_16x16x32_bf16 v[46:49], v[164:167], v[180:183], v[46:49]
	v_mfma_f32_16x16x32_bf16 v[42:45], v[172:175], v[180:183], v[42:45]
	v_mfma_f32_16x16x32_bf16 v[30:33], v[164:167], v[188:191], v[30:33]
	v_mfma_f32_16x16x32_bf16 v[26:29], v[172:175], v[188:191], v[26:29]
	v_mfma_f32_16x16x32_bf16 v[14:17], v[164:167], v[214:217], v[14:17]
	v_mfma_f32_16x16x32_bf16 v[10:13], v[172:175], v[214:217], v[10:13]
	v_mfma_f32_16x16x32_bf16 v[6:9], v[164:167], v[222:225], v[6:9]
	v_mfma_f32_16x16x32_bf16 v[2:5], v[172:175], v[222:225], v[2:5]
	v_mfma_f32_16x16x32_bf16 v[46:49], v[168:171], v[184:187], v[46:49]
	v_mfma_f32_16x16x32_bf16 v[42:45], v[176:179], v[184:187], v[42:45]
	v_mfma_f32_16x16x32_bf16 v[30:33], v[168:171], v[192:195], v[30:33]
	v_mfma_f32_16x16x32_bf16 v[26:29], v[176:179], v[192:195], v[26:29]
	v_mfma_f32_16x16x32_bf16 v[14:17], v[168:171], v[218:221], v[14:17]
	v_mfma_f32_16x16x32_bf16 v[10:13], v[176:179], v[218:221], v[10:13]
	v_mfma_f32_16x16x32_bf16 v[6:9], v[168:171], v[226:229], v[6:9]
	v_mfma_f32_16x16x32_bf16 v[2:5], v[176:179], v[226:229], v[2:5]
	s_setprio 0
	s_barrier
	s_add_i32 s49, s49, 2
	s_add_u32 s26, s26, 0x100
	s_addc_u32 s27, s27, 0
	s_add_u32 s47, s47, 0x100
	s_addc_u32 s48, s48, 0
	s_cmp_gt_u32 s49, 13
	s_cbranch_scc0 .LBB0_516
	s_and_b64 vcc, exec, s[8:9]
	s_cbranch_vccnz .LBB0_521
	v_lshl_add_u32 v142, s16, 8, v144
	s_cmp_gt_i32 s46, 25
	s_mov_b64 s[2:3], -1
	s_cbranch_scc1 .LBB0_522

; #define PG8_STAGE(bufoff, gbase, voff) do { _Pragma("unroll") for (int _i = 0; _i < 2; ++_i) \
;         __builtin_amdgcn_global_load_lds((const unsigned*)((const char*)(gbase) + (voff)[_i]), (LAS unsigned*)(lds + (bufoff) + ldsw + _i * 8192), 16, 0, 0); } while (0)
; #define PG8_LDA(dst, b, h) do { _Pragma("unroll") for (int m = 0; m < 4; ++m) _Pragma("unroll") for (int k = 0; k < 2; ++k) dst[m][k] = *(const LAS f16x8*)(lds + PG8_SA(b, h) + aoff + m * 2048 + k * 1024); } while (0)
; #define PG8_LDB(dst, b, h) do { _Pragma("unroll") for (int n = 0; n < 2; ++n) _Pragma("unroll") for (int k = 0; k < 2; ++k) dst[n][k] = *(const LAS f16x8*)(lds + PG8_SB(b, h) + boff + n * 2048 + k * 1024); } while (0)
; #define PG8_MMA(ai, bj, At, Bt) do { __builtin_amdgcn_s_setprio(1); _Pragma("unroll") for (int m = 0; m < 4; ++m) _Pragma("unroll") for (int n = 0; n < 2; ++n) _Pragma("unroll") for (int k = 0; k < 2; ++k) \
;         acc[ai][bj][m][n] = mma16_<Epi::BF16>(Bt[n][k], At[m][k], acc[ai][bj][m][n]); __builtin_amdgcn_s_setprio(0); } while (0)
; #define PG8_WAIT_V(n) asm volatile("s_waitcnt vmcnt(" #n ")" ::: "memory")
; #define PG8_WAIT_L(n) asm volatile("s_waitcnt lgkmcnt(" #n ")" ::: "memory")
; #define PG8_BAR __builtin_amdgcn_s_barrier()
;     ...
;         const char* nA = has_next ? (const char*)g.A + (size_t)nxt.pm * tA + (nxt.roff ? hA : (size_t)0) : cA; const char* nB = has_next ? (const char*)g.Bt + (size_t)nxt.pn * tB : cB;
;         for (int t = 0; t < nt; t += 2) {
;             const bool last = (t == nt - 2);
;             const char* a1 = cA + (size_t)(t + 1) * kstep;
;             const char* a2 = last ? nA : cA + (size_t)(t + 2) * kstep; const char* b2 = last ? nB : cB + (size_t)(t + 2) * kstep;
;             const char* a3 = a2 + kstep; const char* b3 = b2 + kstep;
;             if constexpr (SP2) {
;             PG8_LDB(B0, 0, 0); PG8_LDB(B1, 0, 1); PG8_SCHED; PG8_LDA(At, 0, 0); PG8_STAGE(PG8_SA(1, 1), a1 + hA, voffA);
;             PG8_WAIT_V(8); PG8_WAIT_L(0); PG8_BAR; PG8_MMA(0, 0, At, B0); PG8_MMA(0, 1, At, B1); PG8_BAR; PG8_SCHED;
;             PG8_LDA(At, 0, 1); PG8_STAGE(PG8_SB(0, 0), b2, voffB); PG8_STAGE(PG8_SB(0, 1), b2 + hB, voffB); PG8_STAGE(PG8_SA(0, 0), a2, voffA);
;             PG8_WAIT_V(8); PG8_WAIT_L(0); PG8_BAR; if (!cur.half) { PG8_MMA(1, 0, At, B0); PG8_MMA(1, 1, At, B1); } PG8_BAR; PG8_SCHED;
.LBB0_758:
	s_mov_b64 s[30:31], s[10:11]
	s_add_u32 s10, s30, 0x100
	s_addc_u32 s11, s31, 0
	s_add_i32 s40, 0, 0x10000
	s_cmp_eq_u32 s59, 12
	s_cselect_b32 s29, s43, s11
	s_cselect_b32 s28, s42, s10
	v_add_u32_e32 v0, s40, v233
	s_cselect_b32 s27, s2, s58
	s_cselect_b32 s26, s3, s23
	s_add_i32 s41, 0, 0x14000
	ds_read_b128 v[148:151], v0
	ds_read_b128 v[152:155], v0 offset:1024
	ds_read_b128 v[156:159], v0 offset:2048
	ds_read_b128 v[160:163], v0 offset:3072
	v_add_u32_e32 v0, s41, v233
	ds_read_b128 v[132:135], v0
	ds_read_b128 v[136:139], v0 offset:1024
	ds_read_b128 v[140:143], v0 offset:2048
	ds_read_b128 v[144:147], v0 offset:3072
	s_add_i32 m0, s9, 0xc000
	s_waitcnt lgkmcnt(0)
	ds_read_b128 v[164:167], v243
	ds_read_b128 v[168:171], v243 offset:1024
	ds_read_b128 v[172:175], v243 offset:2048
	ds_read_b128 v[176:179], v243 offset:3072
	ds_read_b128 v[180:183], v243 offset:4096
	ds_read_b128 v[184:187], v243 offset:5120
	ds_read_b128 v[188:191], v243 offset:6144
	ds_read_b128 v[192:195], v243 offset:7168
	global_load_lds_dwordx4 v222, s[30:31]
	s_add_i32 m0, s9, 0xe000
	s_nop 0
	global_load_lds_dwordx4 v224, s[30:31]
	s_waitcnt vmcnt(8)
	s_waitcnt lgkmcnt(0)
	s_barrier
	s_setprio 1
	v_mfma_f32_16x16x32_f16 v[128:131], v[148:151], v[164:167], v[128:131]
	v_mfma_f32_16x16x32_f16 v[124:127], v[156:159], v[164:167], v[124:127]
	v_mfma_f32_16x16x32_f16 v[112:115], v[148:151], v[172:175], v[112:115]
	v_mfma_f32_16x16x32_f16 v[108:111], v[156:159], v[172:175], v[108:111]
	v_mfma_f32_16x16x32_f16 v[96:99], v[148:151], v[180:183], v[96:99]
	v_mfma_f32_16x16x32_f16 v[92:95], v[156:159], v[180:183], v[92:95]
	v_mfma_f32_16x16x32_f16 v[80:83], v[148:151], v[188:191], v[80:83]
	v_mfma_f32_16x16x32_f16 v[76:79], v[156:159], v[188:191], v[76:79]
	v_mfma_f32_16x16x32_f16 v[128:131], v[152:155], v[168:171], v[128:131]
	v_mfma_f32_16x16x32_f16 v[124:127], v[160:163], v[168:171], v[124:127]
	v_mfma_f32_16x16x32_f16 v[112:115], v[152:155], v[176:179], v[112:115]
	v_mfma_f32_16x16x32_f16 v[108:111], v[160:163], v[176:179], v[108:111]
	v_mfma_f32_16x16x32_f16 v[96:99], v[152:155], v[184:187], v[96:99]
	v_mfma_f32_16x16x32_f16 v[92:95], v[160:163], v[184:187], v[92:95]
	v_mfma_f32_16x16x32_f16 v[80:83], v[152:155], v[192:195], v[80:83]
	v_mfma_f32_16x16x32_f16 v[76:79], v[160:163], v[192:195], v[76:79]
	s_setprio 0
	s_setprio 1
	v_mfma_f32_16x16x32_f16 v[120:123], v[132:135], v[164:167], v[120:123]
	v_mfma_f32_16x16x32_f16 v[116:119], v[140:143], v[164:167], v[116:119]
	v_mfma_f32_16x16x32_f16 v[104:107], v[132:135], v[172:175], v[104:107]
	v_mfma_f32_16x16x32_f16 v[100:103], v[140:143], v[172:175], v[100:103]
	v_mfma_f32_16x16x32_f16 v[88:91], v[132:135], v[180:183], v[88:91]
	v_mfma_f32_16x16x32_f16 v[84:87], v[140:143], v[180:183], v[84:87]
	v_mfma_f32_16x16x32_f16 v[72:75], v[132:135], v[188:191], v[72:75]
	v_mfma_f32_16x16x32_f16 v[68:71], v[140:143], v[188:191], v[68:71]
	v_mfma_f32_16x16x32_f16 v[120:123], v[136:139], v[168:171], v[120:123]
	v_mfma_f32_16x16x32_f16 v[116:119], v[144:147], v[168:171], v[116:119]
	v_mfma_f32_16x16x32_f16 v[104:107], v[136:139], v[176:179], v[104:107]
	v_mfma_f32_16x16x32_f16 v[100:103], v[144:147], v[176:179], v[100:103]
	v_mfma_f32_16x16x32_f16 v[88:91], v[136:139], v[184:187], v[88:91]
	v_mfma_f32_16x16x32_f16 v[84:87], v[144:147], v[184:187], v[84:87]
	v_mfma_f32_16x16x32_f16 v[72:75], v[136:139], v[192:195], v[72:75]
	v_mfma_f32_16x16x32_f16 v[68:71], v[144:147], v[192:195], v[68:71]
	s_setprio 0
	s_barrier
	s_add_i32 s30, s40, s35
	v_lshl_add_u64 v[2:3], s[26:27], 0, v[216:217]
	s_mov_b32 m0, s30
	ds_read_b128 v[188:191], v243 offset:16384
	ds_read_b128 v[192:195], v243 offset:17408
	ds_read_b128 v[180:183], v243 offset:18432
	ds_read_b128 v[184:187], v243 offset:19456
	ds_read_b128 v[172:175], v243 offset:20480
	ds_read_b128 v[176:179], v243 offset:21504
	ds_read_b128 v[164:167], v243 offset:22528
	ds_read_b128 v[168:171], v243 offset:23552
	global_load_lds_dwordx4 v[2:3], off
	s_add_i32 m0, s30, 0x2000
	s_add_u32 s30, s26, 0x40000
	v_lshl_add_u64 v[226:227], s[26:27], 0, v[220:221]
	s_addc_u32 s31, s27, 0
	s_add_i32 s40, s41, s35
	global_load_lds_dwordx4 v[226:227], off
	s_mov_b32 m0, s40
	v_lshl_add_u64 v[228:229], s[28:29], 0, v[214:215]
	global_load_lds_dwordx4 v216, s[30:31]
	s_add_i32 m0, s40, 0x2000
	v_lshl_add_u64 v[230:231], s[28:29], 0, v[218:219]
	global_load_lds_dwordx4 v220, s[30:31]
	s_mov_b32 m0, s9
	v_cndmask_b32_e64 v0, 0, 1, s[24:25]
	global_load_lds_dwordx4 v[228:229], off
	s_mov_b32 m0, s36
	v_cmp_ne_u32_e64 s[40:41], 1, v0
	global_load_lds_dwordx4 v[230:231], off
	s_waitcnt vmcnt(8)
	s_waitcnt lgkmcnt(0)
	s_andn2_b64 vcc, exec, s[24:25]
	s_barrier
	s_cbranch_vccnz .LBB0_760
	s_setprio 1
	v_mfma_f32_16x16x32_f16 v[64:67], v[148:151], v[188:191], v[64:67]
	v_mfma_f32_16x16x32_f16 v[60:63], v[156:159], v[188:191], v[60:63]
	v_mfma_f32_16x16x32_f16 v[48:51], v[148:151], v[180:183], v[48:51]
	v_mfma_f32_16x16x32_f16 v[44:47], v[156:159], v[180:183], v[44:47]
	v_mfma_f32_16x16x32_f16 v[32:35], v[148:151], v[172:175], v[32:35]
	v_mfma_f32_16x16x32_f16 v[28:31], v[156:159], v[172:175], v[28:31]
	v_mfma_f32_16x16x32_f16 v[16:19], v[148:151], v[164:167], v[16:19]
	v_mfma_f32_16x16x32_f16 v[12:15], v[156:159], v[164:167], v[12:15]
	v_mfma_f32_16x16x32_f16 v[64:67], v[152:155], v[192:195], v[64:67]
	v_mfma_f32_16x16x32_f16 v[60:63], v[160:163], v[192:195], v[60:63]
	v_mfma_f32_16x16x32_f16 v[48:51], v[152:155], v[184:187], v[48:51]
	v_mfma_f32_16x16x32_f16 v[44:47], v[160:163], v[184:187], v[44:47]
	v_mfma_f32_16x16x32_f16 v[32:35], v[152:155], v[176:179], v[32:35]
	v_mfma_f32_16x16x32_f16 v[28:31], v[160:163], v[176:179], v[28:31]
	v_mfma_f32_16x16x32_f16 v[16:19], v[152:155], v[168:171], v[16:19]
	v_mfma_f32_16x16x32_f16 v[12:15], v[160:163], v[168:171], v[12:15]
	s_setprio 0
	s_setprio 1
	v_mfma_f32_16x16x32_f16 v[56:59], v[132:135], v[188:191], v[56:59]
	v_mfma_f32_16x16x32_f16 v[52:55], v[140:143], v[188:191], v[52:55]
	v_mfma_f32_16x16x32_f16 v[40:43], v[132:135], v[180:183], v[40:43]
	v_mfma_f32_16x16x32_f16 v[36:39], v[140:143], v[180:183], v[36:39]
	v_mfma_f32_16x16x32_f16 v[24:27], v[132:135], v[172:175], v[24:27]
	v_mfma_f32_16x16x32_f16 v[20:23], v[140:143], v[172:175], v[20:23]
	v_mfma_f32_16x16x32_f16 v[8:11], v[132:135], v[164:167], v[8:11]
	v_mfma_f32_16x16x32_f16 v[4:7], v[140:143], v[164:167], v[4:7]
	v_mfma_f32_16x16x32_f16 v[56:59], v[136:139], v[192:195], v[56:59]
	v_mfma_f32_16x16x32_f16 v[52:55], v[144:147], v[192:195], v[52:55]
	v_mfma_f32_16x16x32_f16 v[40:43], v[136:139], v[184:187], v[40:43]
	v_mfma_f32_16x16x32_f16 v[36:39], v[144:147], v[184:187], v[36:39]
	v_mfma_f32_16x16x32_f16 v[24:27], v[136:139], v[176:179], v[24:27]
	v_mfma_f32_16x16x32_f16 v[20:23], v[144:147], v[176:179], v[20:23]
	v_mfma_f32_16x16x32_f16 v[8:11], v[136:139], v[168:171], v[8:11]
	v_mfma_f32_16x16x32_f16 v[4:7], v[144:147], v[168:171], v[4:7]
	s_setprio 0
; #define PG8_STAGE(bufoff, gbase, voff) do { _Pragma("unroll") for (int _i = 0; _i < 2; ++_i) \
;         __builtin_amdgcn_global_load_lds((const unsigned*)((const char*)(gbase) + (voff)[_i]), (LAS unsigned*)(lds + (bufoff) + ldsw + _i * 8192), 16, 0, 0); } while (0)
; #define PG8_LDA(dst, b, h) do { _Pragma("unroll") for (int m = 0; m < 4; ++m) _Pragma("unroll") for (int k = 0; k < 2; ++k) dst[m][k] = *(const LAS f16x8*)(lds + PG8_SA(b, h) + aoff + m * 2048 + k * 1024); } while (0)
; #define PG8_LDB(dst, b, h) do { _Pragma("unroll") for (int n = 0; n < 2; ++n) _Pragma("unroll") for (int k = 0; k < 2; ++k) dst[n][k] = *(const LAS f16x8*)(lds + PG8_SB(b, h) + boff + n * 2048 + k * 1024); } while (0)
; #define PG8_MMA(ai, bj, At, Bt) do { __builtin_amdgcn_s_setprio(1); _Pragma("unroll") for (int m = 0; m < 4; ++m) _Pragma("unroll") for (int n = 0; n < 2; ++n) _Pragma("unroll") for (int k = 0; k < 2; ++k) \
;         acc[ai][bj][m][n] = mma16_<Epi::BF16>(Bt[n][k], At[m][k], acc[ai][bj][m][n]); __builtin_amdgcn_s_setprio(0); } while (0)
; #define PG8_WAIT_V(n) asm volatile("s_waitcnt vmcnt(" #n ")" ::: "memory")
; #define PG8_WAIT_L(n) asm volatile("s_waitcnt lgkmcnt(" #n ")" ::: "memory")
; #define PG8_BAR __builtin_amdgcn_s_barrier()
; #define PG8_SCHED __builtin_amdgcn_sched_barrier(0)
;     ...
;             PG8_LDB(B0, 1, 0); PG8_LDB(B1, 1, 1); PG8_SCHED; PG8_LDA(At, 1, 0); PG8_STAGE(PG8_SA(0, 1), a2 + hA, voffA);
;             PG8_WAIT_V(8); PG8_WAIT_L(0); PG8_BAR; PG8_MMA(0, 0, At, B0); PG8_MMA(0, 1, At, B1); PG8_BAR; PG8_SCHED;
;             PG8_LDA(At, 1, 1); PG8_STAGE(PG8_SB(1, 0), b3, voffB); PG8_STAGE(PG8_SB(1, 1), b3 + hB, voffB); PG8_STAGE(PG8_SA(1, 0), a3, voffA);
;             PG8_WAIT_V(8); PG8_WAIT_L(0); PG8_BAR; if (!cur.half) { PG8_MMA(1, 0, At, B0); PG8_MMA(1, 1, At, B1); } PG8_BAR; PG8_SCHED;
.LBB0_760:
	s_barrier
	s_add_i32 s30, 0, 0x18000
	v_add_u32_e32 v0, s30, v233
	s_add_i32 s31, 0, 0x1c000
	ds_read_b128 v[148:151], v0
	ds_read_b128 v[152:155], v0 offset:1024
	ds_read_b128 v[156:159], v0 offset:2048
	ds_read_b128 v[160:163], v0 offset:3072
	v_add_u32_e32 v0, s31, v233
	ds_read_b128 v[132:135], v0
	ds_read_b128 v[136:139], v0 offset:1024
	ds_read_b128 v[140:143], v0 offset:2048
	ds_read_b128 v[144:147], v0 offset:3072
	s_add_u32 s28, s28, 0x1a0000
	s_addc_u32 s29, s29, 0
	s_mov_b32 m0, s37
	s_waitcnt lgkmcnt(0)
	ds_read_b128 v[164:167], v243 offset:32768
	ds_read_b128 v[168:171], v243 offset:33792
	ds_read_b128 v[172:175], v243 offset:34816
	ds_read_b128 v[176:179], v243 offset:35840
	ds_read_b128 v[180:183], v243 offset:36864
	ds_read_b128 v[184:187], v243 offset:37888
	ds_read_b128 v[188:191], v243 offset:38912
	ds_read_b128 v[192:195], v243 offset:39936
	global_load_lds_dwordx4 v214, s[28:29]
	s_mov_b32 m0, s48
	s_nop 0
	global_load_lds_dwordx4 v218, s[28:29]
	s_waitcnt vmcnt(8)
	s_waitcnt lgkmcnt(0)
	s_barrier
	s_setprio 1
	v_mfma_f32_16x16x32_f16 v[128:131], v[148:151], v[164:167], v[128:131]
	v_mfma_f32_16x16x32_f16 v[124:127], v[156:159], v[164:167], v[124:127]
	v_mfma_f32_16x16x32_f16 v[112:115], v[148:151], v[172:175], v[112:115]
	v_mfma_f32_16x16x32_f16 v[108:111], v[156:159], v[172:175], v[108:111]
	v_mfma_f32_16x16x32_f16 v[96:99], v[148:151], v[180:183], v[96:99]
	v_mfma_f32_16x16x32_f16 v[92:95], v[156:159], v[180:183], v[92:95]
	v_mfma_f32_16x16x32_f16 v[80:83], v[148:151], v[188:191], v[80:83]
	v_mfma_f32_16x16x32_f16 v[76:79], v[156:159], v[188:191], v[76:79]
	v_mfma_f32_16x16x32_f16 v[128:131], v[152:155], v[168:171], v[128:131]
	v_mfma_f32_16x16x32_f16 v[124:127], v[160:163], v[168:171], v[124:127]
	v_mfma_f32_16x16x32_f16 v[112:115], v[152:155], v[176:179], v[112:115]
	v_mfma_f32_16x16x32_f16 v[108:111], v[160:163], v[176:179], v[108:111]
	v_mfma_f32_16x16x32_f16 v[96:99], v[152:155], v[184:187], v[96:99]
	v_mfma_f32_16x16x32_f16 v[92:95], v[160:163], v[184:187], v[92:95]
	v_mfma_f32_16x16x32_f16 v[80:83], v[152:155], v[192:195], v[80:83]
	v_mfma_f32_16x16x32_f16 v[76:79], v[160:163], v[192:195], v[76:79]
	s_setprio 0
	s_setprio 1
	v_mfma_f32_16x16x32_f16 v[120:123], v[132:135], v[164:167], v[120:123]
	v_mfma_f32_16x16x32_f16 v[116:119], v[140:143], v[164:167], v[116:119]
	v_mfma_f32_16x16x32_f16 v[104:107], v[132:135], v[172:175], v[104:107]
	v_mfma_f32_16x16x32_f16 v[100:103], v[140:143], v[172:175], v[100:103]
	v_mfma_f32_16x16x32_f16 v[88:91], v[132:135], v[180:183], v[88:91]
	v_mfma_f32_16x16x32_f16 v[84:87], v[140:143], v[180:183], v[84:87]
	v_mfma_f32_16x16x32_f16 v[72:75], v[132:135], v[188:191], v[72:75]
	v_mfma_f32_16x16x32_f16 v[68:71], v[140:143], v[188:191], v[68:71]
	v_mfma_f32_16x16x32_f16 v[120:123], v[136:139], v[168:171], v[120:123]
	v_mfma_f32_16x16x32_f16 v[116:119], v[144:147], v[168:171], v[116:119]
	v_mfma_f32_16x16x32_f16 v[104:107], v[136:139], v[176:179], v[104:107]
	v_mfma_f32_16x16x32_f16 v[100:103], v[144:147], v[176:179], v[100:103]
	v_mfma_f32_16x16x32_f16 v[88:91], v[136:139], v[184:187], v[88:91]
	v_mfma_f32_16x16x32_f16 v[84:87], v[144:147], v[184:187], v[84:87]
	v_mfma_f32_16x16x32_f16 v[72:75], v[136:139], v[192:195], v[72:75]
	v_mfma_f32_16x16x32_f16 v[68:71], v[144:147], v[192:195], v[68:71]
	s_setprio 0
	s_barrier
	s_add_i32 s28, s30, s35
	v_lshl_add_u64 v[2:3], v[2:3], 0, s[96:97]
	s_mov_b32 m0, s28
	ds_read_b128 v[188:191], v243 offset:49152
	ds_read_b128 v[192:195], v243 offset:50176
	ds_read_b128 v[180:183], v243 offset:51200
	ds_read_b128 v[184:187], v243 offset:52224
	ds_read_b128 v[172:175], v243 offset:53248
	ds_read_b128 v[176:179], v243 offset:54272
	ds_read_b128 v[164:167], v243 offset:55296
	ds_read_b128 v[168:171], v243 offset:56320
	global_load_lds_dwordx4 v[2:3], off
	s_add_i32 m0, s28, 0x2000
	s_add_u32 s26, s26, 0x40080
	v_lshl_add_u64 v[2:3], v[226:227], 0, s[96:97]
	s_addc_u32 s27, s27, 0
	s_add_i32 s28, s31, s35
	global_load_lds_dwordx4 v[2:3], off
	s_mov_b32 m0, s28
	s_and_b64 vcc, exec, s[40:41]
	global_load_lds_dwordx4 v216, s[26:27]
	s_add_i32 m0, s28, 0x2000
	s_nop 0
	global_load_lds_dwordx4 v220, s[26:27]
	v_lshl_add_u64 v[2:3], v[228:229], 0, s[96:97]
	s_mov_b32 m0, s49
	s_nop 0
	global_load_lds_dwordx4 v[2:3], off
	v_lshl_add_u64 v[2:3], v[230:231], 0, s[96:97]
	s_mov_b32 m0, s50
	s_nop 0
	global_load_lds_dwordx4 v[2:3], off
	s_waitcnt vmcnt(8)
	s_waitcnt lgkmcnt(0)
	s_barrier
	s_cbranch_vccnz .LBB0_757
	s_setprio 1
	v_mfma_f32_16x16x32_f16 v[64:67], v[148:151], v[188:191], v[64:67]
	v_mfma_f32_16x16x32_f16 v[60:63], v[156:159], v[188:191], v[60:63]
	v_mfma_f32_16x16x32_f16 v[48:51], v[148:151], v[180:183], v[48:51]
	v_mfma_f32_16x16x32_f16 v[44:47], v[156:159], v[180:183], v[44:47]
	v_mfma_f32_16x16x32_f16 v[32:35], v[148:151], v[172:175], v[32:35]
	v_mfma_f32_16x16x32_f16 v[28:31], v[156:159], v[172:175], v[28:31]
	v_mfma_f32_16x16x32_f16 v[16:19], v[148:151], v[164:167], v[16:19]
	v_mfma_f32_16x16x32_f16 v[12:15], v[156:159], v[164:167], v[12:15]
	v_mfma_f32_16x16x32_f16 v[64:67], v[152:155], v[192:195], v[64:67]
	v_mfma_f32_16x16x32_f16 v[60:63], v[160:163], v[192:195], v[60:63]
	v_mfma_f32_16x16x32_f16 v[48:51], v[152:155], v[184:187], v[48:51]
	v_mfma_f32_16x16x32_f16 v[44:47], v[160:163], v[184:187], v[44:47]
	v_mfma_f32_16x16x32_f16 v[32:35], v[152:155], v[176:179], v[32:35]
	v_mfma_f32_16x16x32_f16 v[28:31], v[160:163], v[176:179], v[28:31]
	v_mfma_f32_16x16x32_f16 v[16:19], v[152:155], v[168:171], v[16:19]
	v_mfma_f32_16x16x32_f16 v[12:15], v[160:163], v[168:171], v[12:15]
	s_setprio 0
	s_setprio 1
	v_mfma_f32_16x16x32_f16 v[56:59], v[132:135], v[188:191], v[56:59]
	v_mfma_f32_16x16x32_f16 v[52:55], v[140:143], v[188:191], v[52:55]
	v_mfma_f32_16x16x32_f16 v[40:43], v[132:135], v[180:183], v[40:43]
	v_mfma_f32_16x16x32_f16 v[36:39], v[140:143], v[180:183], v[36:39]
	v_mfma_f32_16x16x32_f16 v[24:27], v[132:135], v[172:175], v[24:27]
	v_mfma_f32_16x16x32_f16 v[20:23], v[140:143], v[172:175], v[20:23]
	v_mfma_f32_16x16x32_f16 v[8:11], v[132:135], v[164:167], v[8:11]
	v_mfma_f32_16x16x32_f16 v[2:5], v[140:143], v[164:167], v[4:7]
	v_mfma_f32_16x16x32_f16 v[56:59], v[136:139], v[192:195], v[56:59]
	v_mfma_f32_16x16x32_f16 v[52:55], v[144:147], v[192:195], v[52:55]
	v_mfma_f32_16x16x32_f16 v[40:43], v[136:139], v[184:187], v[40:43]
	v_mfma_f32_16x16x32_f16 v[36:39], v[144:147], v[184:187], v[36:39]
	v_mfma_f32_16x16x32_f16 v[24:27], v[136:139], v[176:179], v[24:27]
	v_mfma_f32_16x16x32_f16 v[20:23], v[144:147], v[176:179], v[20:23]
	v_mfma_f32_16x16x32_f16 v[8:11], v[136:139], v[168:171], v[8:11]
	v_mfma_f32_16x16x32_f16 v[4:7], v[144:147], v[168:171], v[2:5]
	s_setprio 0
	s_branch .LBB0_757

; #define PG8_STAGE(bufoff, gbase, voff) do { _Pragma("unroll") for (int _i = 0; _i < 2; ++_i) \
;         __builtin_amdgcn_global_load_lds((const unsigned*)((const char*)(gbase) + (voff)[_i]), (LAS unsigned*)(lds + (bufoff) + ldsw + _i * 8192), 16, 0, 0); } while (0)
; #define PG8_LDA(dst, b, h) do { _Pragma("unroll") for (int m = 0; m < 4; ++m) _Pragma("unroll") for (int k = 0; k < 2; ++k) dst[m][k] = *(const LAS f16x8*)(lds + PG8_SA(b, h) + aoff + m * 2048 + k * 1024); } while (0)
; #define PG8_LDB(dst, b, h) do { _Pragma("unroll") for (int n = 0; n < 2; ++n) _Pragma("unroll") for (int k = 0; k < 2; ++k) dst[n][k] = *(const LAS f16x8*)(lds + PG8_SB(b, h) + boff + n * 2048 + k * 1024); } while (0)
; #define PG8_MMA(ai, bj, At, Bt) do { __builtin_amdgcn_s_setprio(1); _Pragma("unroll") for (int m = 0; m < 4; ++m) _Pragma("unroll") for (int n = 0; n < 2; ++n) _Pragma("unroll") for (int k = 0; k < 2; ++k) \
;         acc[ai][bj][m][n] = mma16_<Epi::BF16>(Bt[n][k], At[m][k], acc[ai][bj][m][n]); __builtin_amdgcn_s_setprio(0); } while (0)
; #define PG8_WAIT_V(n) asm volatile("s_waitcnt vmcnt(" #n ")" ::: "memory")
; #define PG8_WAIT_L(n) asm volatile("s_waitcnt lgkmcnt(" #n ")" ::: "memory")
; #define PG8_BAR __builtin_amdgcn_s_barrier()
; #define PG8_SCHED __builtin_amdgcn_sched_barrier(0)
;     ...
;             const bool last = (t == nt - 2);
;             const char* a1 = cA + (size_t)(t + 1) * kstep;
;             const char* a2 = last ? nA : cA + (size_t)(t + 2) * kstep; const char* b2 = last ? nB : cB + (size_t)(t + 2) * kstep;
;             const char* a3 = a2 + kstep; const char* b3 = b2 + kstep;
;             if constexpr (SP2) {
;             PG8_LDB(B0, 0, 0); PG8_LDB(B1, 0, 1); PG8_SCHED; PG8_LDA(At, 0, 0); PG8_STAGE(PG8_SA(1, 1), a1 + hA, voffA);
;             PG8_WAIT_V(8); PG8_WAIT_L(0); PG8_BAR; PG8_MMA(0, 0, At, B0); PG8_MMA(0, 1, At, B1); PG8_BAR; PG8_SCHED;
;             PG8_LDA(At, 0, 1); PG8_STAGE(PG8_SB(0, 0), b2, voffB); PG8_STAGE(PG8_SB(0, 1), b2 + hB, voffB); PG8_STAGE(PG8_SA(0, 0), a2, voffA);
;             PG8_WAIT_V(8); PG8_WAIT_L(0); PG8_BAR; if (!cur.half) { PG8_MMA(1, 0, At, B0); PG8_MMA(1, 1, At, B1); } PG8_BAR; PG8_SCHED;
.LBB0_798:
	s_mov_b64 s[24:25], s[10:11]
	s_add_u32 s10, s24, 0x100
	s_addc_u32 s11, s25, 0
	s_add_i32 s40, 0, 0x10000
	s_cmp_eq_u32 s59, 12
	s_cselect_b32 s23, s51, s11
	s_cselect_b32 s22, s50, s10
	v_add_u32_e32 v0, s40, v233
	s_cselect_b32 s21, s2, s58
	s_cselect_b32 s20, s3, s49
	s_add_i32 s41, 0, 0x14000
	ds_read_b128 v[148:151], v0
	ds_read_b128 v[152:155], v0 offset:1024
	ds_read_b128 v[156:159], v0 offset:2048
	ds_read_b128 v[160:163], v0 offset:3072
	v_add_u32_e32 v0, s41, v233
	ds_read_b128 v[132:135], v0
	ds_read_b128 v[136:139], v0 offset:1024
	ds_read_b128 v[140:143], v0 offset:2048
	ds_read_b128 v[144:147], v0 offset:3072
	s_add_i32 m0, s9, 0xc000
	s_waitcnt lgkmcnt(0)
	ds_read_b128 v[164:167], v243
	ds_read_b128 v[168:171], v243 offset:1024
	ds_read_b128 v[172:175], v243 offset:2048
	ds_read_b128 v[176:179], v243 offset:3072
	ds_read_b128 v[180:183], v243 offset:4096
	ds_read_b128 v[184:187], v243 offset:5120
	ds_read_b128 v[188:191], v243 offset:6144
	ds_read_b128 v[192:195], v243 offset:7168
	global_load_lds_dwordx4 v222, s[24:25]
	s_add_i32 m0, s9, 0xe000
	s_nop 0
	global_load_lds_dwordx4 v224, s[24:25]
	s_waitcnt vmcnt(8)
	s_waitcnt lgkmcnt(0)
	s_barrier
	s_setprio 1
	v_mfma_f32_16x16x32_f16 v[128:131], v[148:151], v[164:167], v[128:131]
	v_mfma_f32_16x16x32_f16 v[124:127], v[156:159], v[164:167], v[124:127]
	v_mfma_f32_16x16x32_f16 v[112:115], v[148:151], v[172:175], v[112:115]
	v_mfma_f32_16x16x32_f16 v[108:111], v[156:159], v[172:175], v[108:111]
	v_mfma_f32_16x16x32_f16 v[96:99], v[148:151], v[180:183], v[96:99]
	v_mfma_f32_16x16x32_f16 v[92:95], v[156:159], v[180:183], v[92:95]
	v_mfma_f32_16x16x32_f16 v[80:83], v[148:151], v[188:191], v[80:83]
	v_mfma_f32_16x16x32_f16 v[76:79], v[156:159], v[188:191], v[76:79]
	v_mfma_f32_16x16x32_f16 v[128:131], v[152:155], v[168:171], v[128:131]
	v_mfma_f32_16x16x32_f16 v[124:127], v[160:163], v[168:171], v[124:127]
	v_mfma_f32_16x16x32_f16 v[112:115], v[152:155], v[176:179], v[112:115]
	v_mfma_f32_16x16x32_f16 v[108:111], v[160:163], v[176:179], v[108:111]
	v_mfma_f32_16x16x32_f16 v[96:99], v[152:155], v[184:187], v[96:99]
	v_mfma_f32_16x16x32_f16 v[92:95], v[160:163], v[184:187], v[92:95]
	v_mfma_f32_16x16x32_f16 v[80:83], v[152:155], v[192:195], v[80:83]
	v_mfma_f32_16x16x32_f16 v[76:79], v[160:163], v[192:195], v[76:79]
	s_setprio 0
	s_setprio 1
	v_mfma_f32_16x16x32_f16 v[120:123], v[132:135], v[164:167], v[120:123]
	v_mfma_f32_16x16x32_f16 v[116:119], v[140:143], v[164:167], v[116:119]
	v_mfma_f32_16x16x32_f16 v[104:107], v[132:135], v[172:175], v[104:107]
	v_mfma_f32_16x16x32_f16 v[100:103], v[140:143], v[172:175], v[100:103]
	v_mfma_f32_16x16x32_f16 v[88:91], v[132:135], v[180:183], v[88:91]
	v_mfma_f32_16x16x32_f16 v[84:87], v[140:143], v[180:183], v[84:87]
	v_mfma_f32_16x16x32_f16 v[72:75], v[132:135], v[188:191], v[72:75]
	v_mfma_f32_16x16x32_f16 v[68:71], v[140:143], v[188:191], v[68:71]
	v_mfma_f32_16x16x32_f16 v[120:123], v[136:139], v[168:171], v[120:123]
	v_mfma_f32_16x16x32_f16 v[116:119], v[144:147], v[168:171], v[116:119]
	v_mfma_f32_16x16x32_f16 v[104:107], v[136:139], v[176:179], v[104:107]
	v_mfma_f32_16x16x32_f16 v[100:103], v[144:147], v[176:179], v[100:103]
	v_mfma_f32_16x16x32_f16 v[88:91], v[136:139], v[184:187], v[88:91]
	v_mfma_f32_16x16x32_f16 v[84:87], v[144:147], v[184:187], v[84:87]
	v_mfma_f32_16x16x32_f16 v[72:75], v[136:139], v[192:195], v[72:75]
	v_mfma_f32_16x16x32_f16 v[68:71], v[144:147], v[192:195], v[68:71]
	s_setprio 0
	s_barrier
	s_add_i32 s24, s40, s27
	v_lshl_add_u64 v[2:3], s[20:21], 0, v[216:217]
	s_mov_b32 m0, s24
	ds_read_b128 v[188:191], v243 offset:16384
	ds_read_b128 v[192:195], v243 offset:17408
	ds_read_b128 v[180:183], v243 offset:18432
	ds_read_b128 v[184:187], v243 offset:19456
	ds_read_b128 v[172:175], v243 offset:20480
	ds_read_b128 v[176:179], v243 offset:21504
	ds_read_b128 v[164:167], v243 offset:22528
	ds_read_b128 v[168:171], v243 offset:23552
	global_load_lds_dwordx4 v[2:3], off
	s_add_i32 m0, s24, 0x2000
	s_add_u32 s24, s20, 0x40000
	v_lshl_add_u64 v[226:227], s[20:21], 0, v[220:221]
	s_addc_u32 s25, s21, 0
	s_add_i32 s40, s41, s27
	global_load_lds_dwordx4 v[226:227], off
	s_mov_b32 m0, s40
	v_lshl_add_u64 v[228:229], s[22:23], 0, v[214:215]
	global_load_lds_dwordx4 v216, s[24:25]
	s_add_i32 m0, s40, 0x2000
	v_lshl_add_u64 v[230:231], s[22:23], 0, v[218:219]
	global_load_lds_dwordx4 v220, s[24:25]
	s_mov_b32 m0, s9
	v_cndmask_b32_e64 v0, 0, 1, s[18:19]
	global_load_lds_dwordx4 v[228:229], off
	s_mov_b32 m0, s28
	v_cmp_ne_u32_e64 s[40:41], 1, v0
	global_load_lds_dwordx4 v[230:231], off
	s_waitcnt vmcnt(8)
	s_waitcnt lgkmcnt(0)
	s_andn2_b64 vcc, exec, s[18:19]
	s_barrier
	s_cbranch_vccnz .LBB0_800
	s_setprio 1
	v_mfma_f32_16x16x32_f16 v[64:67], v[148:151], v[188:191], v[64:67]
	v_mfma_f32_16x16x32_f16 v[60:63], v[156:159], v[188:191], v[60:63]
	v_mfma_f32_16x16x32_f16 v[48:51], v[148:151], v[180:183], v[48:51]
	v_mfma_f32_16x16x32_f16 v[44:47], v[156:159], v[180:183], v[44:47]
	v_mfma_f32_16x16x32_f16 v[32:35], v[148:151], v[172:175], v[32:35]
	v_mfma_f32_16x16x32_f16 v[28:31], v[156:159], v[172:175], v[28:31]
	v_mfma_f32_16x16x32_f16 v[16:19], v[148:151], v[164:167], v[16:19]
	v_mfma_f32_16x16x32_f16 v[12:15], v[156:159], v[164:167], v[12:15]
	v_mfma_f32_16x16x32_f16 v[64:67], v[152:155], v[192:195], v[64:67]
	v_mfma_f32_16x16x32_f16 v[60:63], v[160:163], v[192:195], v[60:63]
	v_mfma_f32_16x16x32_f16 v[48:51], v[152:155], v[184:187], v[48:51]
	v_mfma_f32_16x16x32_f16 v[44:47], v[160:163], v[184:187], v[44:47]
	v_mfma_f32_16x16x32_f16 v[32:35], v[152:155], v[176:179], v[32:35]
	v_mfma_f32_16x16x32_f16 v[28:31], v[160:163], v[176:179], v[28:31]
	v_mfma_f32_16x16x32_f16 v[16:19], v[152:155], v[168:171], v[16:19]
	v_mfma_f32_16x16x32_f16 v[12:15], v[160:163], v[168:171], v[12:15]
	s_setprio 0
	s_setprio 1
	v_mfma_f32_16x16x32_f16 v[56:59], v[132:135], v[188:191], v[56:59]
	v_mfma_f32_16x16x32_f16 v[52:55], v[140:143], v[188:191], v[52:55]
	v_mfma_f32_16x16x32_f16 v[40:43], v[132:135], v[180:183], v[40:43]
	v_mfma_f32_16x16x32_f16 v[36:39], v[140:143], v[180:183], v[36:39]
	v_mfma_f32_16x16x32_f16 v[24:27], v[132:135], v[172:175], v[24:27]
	v_mfma_f32_16x16x32_f16 v[20:23], v[140:143], v[172:175], v[20:23]
	v_mfma_f32_16x16x32_f16 v[8:11], v[132:135], v[164:167], v[8:11]
	v_mfma_f32_16x16x32_f16 v[4:7], v[140:143], v[164:167], v[4:7]
	v_mfma_f32_16x16x32_f16 v[56:59], v[136:139], v[192:195], v[56:59]
	v_mfma_f32_16x16x32_f16 v[52:55], v[144:147], v[192:195], v[52:55]
	v_mfma_f32_16x16x32_f16 v[40:43], v[136:139], v[184:187], v[40:43]
	v_mfma_f32_16x16x32_f16 v[36:39], v[144:147], v[184:187], v[36:39]
	v_mfma_f32_16x16x32_f16 v[24:27], v[136:139], v[176:179], v[24:27]
	v_mfma_f32_16x16x32_f16 v[20:23], v[144:147], v[176:179], v[20:23]
	v_mfma_f32_16x16x32_f16 v[8:11], v[136:139], v[168:171], v[8:11]
	v_mfma_f32_16x16x32_f16 v[4:7], v[144:147], v[168:171], v[4:7]
	s_setprio 0
; #define PG8_STAGE(bufoff, gbase, voff) do { _Pragma("unroll") for (int _i = 0; _i < 2; ++_i) \
;         __builtin_amdgcn_global_load_lds((const unsigned*)((const char*)(gbase) + (voff)[_i]), (LAS unsigned*)(lds + (bufoff) + ldsw + _i * 8192), 16, 0, 0); } while (0)
; #define PG8_LDA(dst, b, h) do { _Pragma("unroll") for (int m = 0; m < 4; ++m) _Pragma("unroll") for (int k = 0; k < 2; ++k) dst[m][k] = *(const LAS f16x8*)(lds + PG8_SA(b, h) + aoff + m * 2048 + k * 1024); } while (0)
; #define PG8_LDB(dst, b, h) do { _Pragma("unroll") for (int n = 0; n < 2; ++n) _Pragma("unroll") for (int k = 0; k < 2; ++k) dst[n][k] = *(const LAS f16x8*)(lds + PG8_SB(b, h) + boff + n * 2048 + k * 1024); } while (0)
; #define PG8_MMA(ai, bj, At, Bt) do { __builtin_amdgcn_s_setprio(1); _Pragma("unroll") for (int m = 0; m < 4; ++m) _Pragma("unroll") for (int n = 0; n < 2; ++n) _Pragma("unroll") for (int k = 0; k < 2; ++k) \
;         acc[ai][bj][m][n] = mma16_<Epi::BF16>(Bt[n][k], At[m][k], acc[ai][bj][m][n]); __builtin_amdgcn_s_setprio(0); } while (0)
; #define PG8_WAIT_V(n) asm volatile("s_waitcnt vmcnt(" #n ")" ::: "memory")
; #define PG8_WAIT_L(n) asm volatile("s_waitcnt lgkmcnt(" #n ")" ::: "memory")
; #define PG8_BAR __builtin_amdgcn_s_barrier()
; #define PG8_SCHED __builtin_amdgcn_sched_barrier(0)
;     ...
;             PG8_LDB(B0, 1, 0); PG8_LDB(B1, 1, 1); PG8_SCHED; PG8_LDA(At, 1, 0); PG8_STAGE(PG8_SA(0, 1), a2 + hA, voffA);
;             PG8_WAIT_V(8); PG8_WAIT_L(0); PG8_BAR; PG8_MMA(0, 0, At, B0); PG8_MMA(0, 1, At, B1); PG8_BAR; PG8_SCHED;
;             PG8_LDA(At, 1, 1); PG8_STAGE(PG8_SB(1, 0), b3, voffB); PG8_STAGE(PG8_SB(1, 1), b3 + hB, voffB); PG8_STAGE(PG8_SA(1, 0), a3, voffA);
;             PG8_WAIT_V(8); PG8_WAIT_L(0); PG8_BAR; if (!cur.half) { PG8_MMA(1, 0, At, B0); PG8_MMA(1, 1, At, B1); } PG8_BAR; PG8_SCHED;
.LBB0_800:
	s_barrier
	s_add_i32 s24, 0, 0x18000
	v_add_u32_e32 v0, s24, v233
	s_add_i32 s25, 0, 0x1c000
	ds_read_b128 v[148:151], v0
	ds_read_b128 v[152:155], v0 offset:1024
	ds_read_b128 v[156:159], v0 offset:2048
	ds_read_b128 v[160:163], v0 offset:3072
	v_add_u32_e32 v0, s25, v233
	ds_read_b128 v[132:135], v0
	ds_read_b128 v[136:139], v0 offset:1024
	ds_read_b128 v[140:143], v0 offset:2048
	ds_read_b128 v[144:147], v0 offset:3072
	s_add_u32 s22, s22, 0x1a0000
	s_addc_u32 s23, s23, 0
	s_mov_b32 m0, s29
	s_waitcnt lgkmcnt(0)
	ds_read_b128 v[164:167], v243 offset:32768
	ds_read_b128 v[168:171], v243 offset:33792
	ds_read_b128 v[172:175], v243 offset:34816
	ds_read_b128 v[176:179], v243 offset:35840
	ds_read_b128 v[180:183], v243 offset:36864
	ds_read_b128 v[184:187], v243 offset:37888
	ds_read_b128 v[188:191], v243 offset:38912
	ds_read_b128 v[192:195], v243 offset:39936
	global_load_lds_dwordx4 v214, s[22:23]
	s_mov_b32 m0, s30
	s_nop 0
	global_load_lds_dwordx4 v218, s[22:23]
	s_waitcnt vmcnt(8)
	s_waitcnt lgkmcnt(0)
	s_barrier
	s_setprio 1
	v_mfma_f32_16x16x32_f16 v[128:131], v[148:151], v[164:167], v[128:131]
	v_mfma_f32_16x16x32_f16 v[124:127], v[156:159], v[164:167], v[124:127]
	v_mfma_f32_16x16x32_f16 v[112:115], v[148:151], v[172:175], v[112:115]
	v_mfma_f32_16x16x32_f16 v[108:111], v[156:159], v[172:175], v[108:111]
	v_mfma_f32_16x16x32_f16 v[96:99], v[148:151], v[180:183], v[96:99]
	v_mfma_f32_16x16x32_f16 v[92:95], v[156:159], v[180:183], v[92:95]
	v_mfma_f32_16x16x32_f16 v[80:83], v[148:151], v[188:191], v[80:83]
	v_mfma_f32_16x16x32_f16 v[76:79], v[156:159], v[188:191], v[76:79]
	v_mfma_f32_16x16x32_f16 v[128:131], v[152:155], v[168:171], v[128:131]
	v_mfma_f32_16x16x32_f16 v[124:127], v[160:163], v[168:171], v[124:127]
	v_mfma_f32_16x16x32_f16 v[112:115], v[152:155], v[176:179], v[112:115]
	v_mfma_f32_16x16x32_f16 v[108:111], v[160:163], v[176:179], v[108:111]
	v_mfma_f32_16x16x32_f16 v[96:99], v[152:155], v[184:187], v[96:99]
	v_mfma_f32_16x16x32_f16 v[92:95], v[160:163], v[184:187], v[92:95]
	v_mfma_f32_16x16x32_f16 v[80:83], v[152:155], v[192:195], v[80:83]
	v_mfma_f32_16x16x32_f16 v[76:79], v[160:163], v[192:195], v[76:79]
	s_setprio 0
	s_setprio 1
	v_mfma_f32_16x16x32_f16 v[120:123], v[132:135], v[164:167], v[120:123]
	v_mfma_f32_16x16x32_f16 v[116:119], v[140:143], v[164:167], v[116:119]
	v_mfma_f32_16x16x32_f16 v[104:107], v[132:135], v[172:175], v[104:107]
	v_mfma_f32_16x16x32_f16 v[100:103], v[140:143], v[172:175], v[100:103]
	v_mfma_f32_16x16x32_f16 v[88:91], v[132:135], v[180:183], v[88:91]
	v_mfma_f32_16x16x32_f16 v[84:87], v[140:143], v[180:183], v[84:87]
	v_mfma_f32_16x16x32_f16 v[72:75], v[132:135], v[188:191], v[72:75]
	v_mfma_f32_16x16x32_f16 v[68:71], v[140:143], v[188:191], v[68:71]
	v_mfma_f32_16x16x32_f16 v[120:123], v[136:139], v[168:171], v[120:123]
	v_mfma_f32_16x16x32_f16 v[116:119], v[144:147], v[168:171], v[116:119]
	v_mfma_f32_16x16x32_f16 v[104:107], v[136:139], v[176:179], v[104:107]
	v_mfma_f32_16x16x32_f16 v[100:103], v[144:147], v[176:179], v[100:103]
	v_mfma_f32_16x16x32_f16 v[88:91], v[136:139], v[184:187], v[88:91]
	v_mfma_f32_16x16x32_f16 v[84:87], v[144:147], v[184:187], v[84:87]
	v_mfma_f32_16x16x32_f16 v[72:75], v[136:139], v[192:195], v[72:75]
	v_mfma_f32_16x16x32_f16 v[68:71], v[144:147], v[192:195], v[68:71]
	s_setprio 0
	s_barrier
	s_add_i32 s22, s24, s27
	v_lshl_add_u64 v[2:3], v[2:3], 0, s[96:97]
	s_mov_b32 m0, s22
	ds_read_b128 v[188:191], v243 offset:49152
	ds_read_b128 v[192:195], v243 offset:50176
	ds_read_b128 v[180:183], v243 offset:51200
	ds_read_b128 v[184:187], v243 offset:52224
	ds_read_b128 v[172:175], v243 offset:53248
	ds_read_b128 v[176:179], v243 offset:54272
	ds_read_b128 v[164:167], v243 offset:55296
	ds_read_b128 v[168:171], v243 offset:56320
	global_load_lds_dwordx4 v[2:3], off
	s_add_i32 m0, s22, 0x2000
	s_add_u32 s20, s20, 0x40080
	v_lshl_add_u64 v[2:3], v[226:227], 0, s[96:97]
	s_addc_u32 s21, s21, 0
	s_add_i32 s22, s25, s27
	global_load_lds_dwordx4 v[2:3], off
	s_mov_b32 m0, s22
	s_and_b64 vcc, exec, s[40:41]
	global_load_lds_dwordx4 v216, s[20:21]
	s_add_i32 m0, s22, 0x2000
	s_nop 0
	global_load_lds_dwordx4 v220, s[20:21]
	v_lshl_add_u64 v[2:3], v[228:229], 0, s[96:97]
	s_mov_b32 m0, s31
	s_nop 0
	global_load_lds_dwordx4 v[2:3], off
	v_lshl_add_u64 v[2:3], v[230:231], 0, s[96:97]
	s_mov_b32 m0, s34
	s_nop 0
	global_load_lds_dwordx4 v[2:3], off
	s_waitcnt vmcnt(8)
	s_waitcnt lgkmcnt(0)
	s_barrier
	s_cbranch_vccnz .LBB0_797
	s_setprio 1
	v_mfma_f32_16x16x32_f16 v[64:67], v[148:151], v[188:191], v[64:67]
	v_mfma_f32_16x16x32_f16 v[60:63], v[156:159], v[188:191], v[60:63]
	v_mfma_f32_16x16x32_f16 v[48:51], v[148:151], v[180:183], v[48:51]
	v_mfma_f32_16x16x32_f16 v[44:47], v[156:159], v[180:183], v[44:47]
	v_mfma_f32_16x16x32_f16 v[32:35], v[148:151], v[172:175], v[32:35]
	v_mfma_f32_16x16x32_f16 v[28:31], v[156:159], v[172:175], v[28:31]
	v_mfma_f32_16x16x32_f16 v[16:19], v[148:151], v[164:167], v[16:19]
	v_mfma_f32_16x16x32_f16 v[12:15], v[156:159], v[164:167], v[12:15]
	v_mfma_f32_16x16x32_f16 v[64:67], v[152:155], v[192:195], v[64:67]
	v_mfma_f32_16x16x32_f16 v[60:63], v[160:163], v[192:195], v[60:63]
	v_mfma_f32_16x16x32_f16 v[48:51], v[152:155], v[184:187], v[48:51]
	v_mfma_f32_16x16x32_f16 v[44:47], v[160:163], v[184:187], v[44:47]
	v_mfma_f32_16x16x32_f16 v[32:35], v[152:155], v[176:179], v[32:35]
	v_mfma_f32_16x16x32_f16 v[28:31], v[160:163], v[176:179], v[28:31]
	v_mfma_f32_16x16x32_f16 v[16:19], v[152:155], v[168:171], v[16:19]
	v_mfma_f32_16x16x32_f16 v[12:15], v[160:163], v[168:171], v[12:15]
	s_setprio 0
	s_setprio 1
	v_mfma_f32_16x16x32_f16 v[56:59], v[132:135], v[188:191], v[56:59]
	v_mfma_f32_16x16x32_f16 v[52:55], v[140:143], v[188:191], v[52:55]
	v_mfma_f32_16x16x32_f16 v[40:43], v[132:135], v[180:183], v[40:43]
	v_mfma_f32_16x16x32_f16 v[36:39], v[140:143], v[180:183], v[36:39]
	v_mfma_f32_16x16x32_f16 v[24:27], v[132:135], v[172:175], v[24:27]
	v_mfma_f32_16x16x32_f16 v[20:23], v[140:143], v[172:175], v[20:23]
	v_mfma_f32_16x16x32_f16 v[8:11], v[132:135], v[164:167], v[8:11]
	v_mfma_f32_16x16x32_f16 v[2:5], v[140:143], v[164:167], v[4:7]
	v_mfma_f32_16x16x32_f16 v[56:59], v[136:139], v[192:195], v[56:59]
	v_mfma_f32_16x16x32_f16 v[52:55], v[144:147], v[192:195], v[52:55]
	v_mfma_f32_16x16x32_f16 v[40:43], v[136:139], v[184:187], v[40:43]
	v_mfma_f32_16x16x32_f16 v[36:39], v[144:147], v[184:187], v[36:39]
	v_mfma_f32_16x16x32_f16 v[24:27], v[136:139], v[176:179], v[24:27]
	v_mfma_f32_16x16x32_f16 v[20:23], v[144:147], v[176:179], v[20:23]
	v_mfma_f32_16x16x32_f16 v[8:11], v[136:139], v[168:171], v[8:11]
	v_mfma_f32_16x16x32_f16 v[4:7], v[144:147], v[168:171], v[2:5]
	s_setprio 0
	s_branch .LBB0_797

; #define PG8_STAGE(bufoff, gbase, voff) do { _Pragma("unroll") for (int _i = 0; _i < 2; ++_i) \
;         __builtin_amdgcn_global_load_lds((const unsigned*)((const char*)(gbase) + (voff)[_i]), (LAS unsigned*)(lds + (bufoff) + ldsw + _i * 8192), 16, 0, 0); } while (0)
; #define PG8_LDA(dst, b, h) do { _Pragma("unroll") for (int m = 0; m < 4; ++m) _Pragma("unroll") for (int k = 0; k < 2; ++k) dst[m][k] = *(const LAS f16x8*)(lds + PG8_SA(b, h) + aoff + m * 2048 + k * 1024); } while (0)
; #define PG8_LDB(dst, b, h) do { _Pragma("unroll") for (int n = 0; n < 2; ++n) _Pragma("unroll") for (int k = 0; k < 2; ++k) dst[n][k] = *(const LAS f16x8*)(lds + PG8_SB(b, h) + boff + n * 2048 + k * 1024); } while (0)
; #define PG8_MMA(ai, bj, At, Bt) do { __builtin_amdgcn_s_setprio(1); _Pragma("unroll") for (int m = 0; m < 4; ++m) _Pragma("unroll") for (int n = 0; n < 2; ++n) _Pragma("unroll") for (int k = 0; k < 2; ++k) \
;         acc[ai][bj][m][n] = mma16_<Epi::BF16>(Bt[n][k], At[m][k], acc[ai][bj][m][n]); __builtin_amdgcn_s_setprio(0); } while (0)
; #define PG8_WAIT_V(n) asm volatile("s_waitcnt vmcnt(" #n ")" ::: "memory")
; #define PG8_WAIT_L(n) asm volatile("s_waitcnt lgkmcnt(" #n ")" ::: "memory")
; #define PG8_BAR __builtin_amdgcn_s_barrier()
; #define PG8_SCHED __builtin_amdgcn_sched_barrier(0)
;     ...
;             const bool last = (t == nt - 2);
;             const char* a1 = cA + (size_t)(t + 1) * kstep;
;             const char* a2 = last ? nA : cA + (size_t)(t + 2) * kstep; const char* b2 = last ? nB : cB + (size_t)(t + 2) * kstep;
;             const char* a3 = a2 + kstep; const char* b3 = b2 + kstep;
;             if constexpr (SP2) {
;             PG8_LDB(B0, 0, 0); PG8_LDB(B1, 0, 1); PG8_SCHED; PG8_LDA(At, 0, 0); PG8_STAGE(PG8_SA(1, 1), a1 + hA, voffA);
;             PG8_WAIT_V(8); PG8_WAIT_L(0); PG8_BAR; PG8_MMA(0, 0, At, B0); PG8_MMA(0, 1, At, B1); PG8_BAR; PG8_SCHED;
;             PG8_LDA(At, 0, 1); PG8_STAGE(PG8_SB(0, 0), b2, voffB); PG8_STAGE(PG8_SB(0, 1), b2 + hB, voffB); PG8_STAGE(PG8_SA(0, 0), a2, voffA);
;             PG8_WAIT_V(8); PG8_WAIT_L(0); PG8_BAR; if (!cur.half) { PG8_MMA(1, 0, At, B0); PG8_MMA(1, 1, At, B1); } PG8_BAR; PG8_SCHED;
.LBB0_886:
	s_add_u32 s25, s36, 0xfffc0080
	s_addc_u32 s27, s37, -1
	s_add_i32 s40, 0, 0x10000
	s_cmp_eq_u32 s14, 12
	s_cselect_b32 s45, s29, s27
	s_cselect_b32 s44, s28, s25
	s_waitcnt lgkmcnt(0)
	v_add_u32_e32 v106, s40, v244
	s_cselect_b32 s43, s2, s11
	s_cselect_b32 s42, s3, s9
	s_add_i32 s25, 0, 0x14000
	ds_read_b128 v[154:157], v106
	ds_read_b128 v[158:161], v106 offset:1024
	ds_read_b128 v[162:165], v106 offset:2048
	ds_read_b128 v[166:169], v106 offset:3072
	v_add_u32_e32 v106, s25, v244
	ds_read_b128 v[138:141], v106
	ds_read_b128 v[142:145], v106 offset:1024
	ds_read_b128 v[146:149], v106 offset:2048
	ds_read_b128 v[150:153], v106 offset:3072
	s_add_i32 m0, s51, 0xc000
	ds_read_b128 v[170:173], v245
	ds_read_b128 v[174:177], v245 offset:1024
	ds_read_b128 v[178:181], v245 offset:2048
	ds_read_b128 v[182:185], v245 offset:3072
	ds_read_b128 v[186:189], v245 offset:4096
	ds_read_b128 v[190:193], v245 offset:5120
	ds_read_b128 v[226:229], v245 offset:6144
	ds_read_b128 v[230:233], v245 offset:7168
	global_load_lds_dwordx4 v222, s[36:37]
	s_add_i32 m0, s51, 0xe000
	s_nop 0
	global_load_lds_dwordx4 v224, s[36:37]
	s_waitcnt vmcnt(8)
	s_waitcnt lgkmcnt(0)
	s_barrier
	s_setprio 1
	v_mfma_f32_16x16x32_bf16 v[106:109], v[154:157], v[170:173], v[134:137]
	v_mfma_f32_16x16x32_bf16 v[110:113], v[162:165], v[170:173], v[130:133]
	v_mfma_f32_16x16x32_bf16 v[126:129], v[154:157], v[178:181], v[126:129]
	v_mfma_f32_16x16x32_bf16 v[122:125], v[162:165], v[178:181], v[122:125]
	v_mfma_f32_16x16x32_bf16 v[118:121], v[154:157], v[186:189], v[118:121]
	v_mfma_f32_16x16x32_bf16 v[114:117], v[162:165], v[186:189], v[114:117]
	v_mfma_f32_16x16x32_bf16 v[102:105], v[154:157], v[226:229], v[102:105]
	v_mfma_f32_16x16x32_bf16 v[98:101], v[162:165], v[226:229], v[98:101]
	v_mfma_f32_16x16x32_bf16 v[106:109], v[158:161], v[174:177], v[106:109]
	v_mfma_f32_16x16x32_bf16 v[110:113], v[166:169], v[174:177], v[110:113]
	v_mfma_f32_16x16x32_bf16 v[126:129], v[158:161], v[182:185], v[126:129]
	v_mfma_f32_16x16x32_bf16 v[122:125], v[166:169], v[182:185], v[122:125]
	v_mfma_f32_16x16x32_bf16 v[118:121], v[158:161], v[190:193], v[118:121]
	v_mfma_f32_16x16x32_bf16 v[114:117], v[166:169], v[190:193], v[114:117]
	v_mfma_f32_16x16x32_bf16 v[102:105], v[158:161], v[230:233], v[102:105]
	v_mfma_f32_16x16x32_bf16 v[98:101], v[166:169], v[230:233], v[98:101]
	s_setprio 0
	s_setprio 1
	v_mfma_f32_16x16x32_bf16 v[70:73], v[138:141], v[170:173], v[70:73]
	v_mfma_f32_16x16x32_bf16 v[66:69], v[146:149], v[170:173], v[66:69]
	v_mfma_f32_16x16x32_bf16 v[58:61], v[138:141], v[178:181], v[58:61]
	v_mfma_f32_16x16x32_bf16 v[50:53], v[146:149], v[178:181], v[50:53]
	v_mfma_f32_16x16x32_bf16 v[46:49], v[138:141], v[186:189], v[46:49]
	v_mfma_f32_16x16x32_bf16 v[42:45], v[146:149], v[186:189], v[42:45]
	v_mfma_f32_16x16x32_bf16 v[38:41], v[138:141], v[226:229], v[38:41]
	v_mfma_f32_16x16x32_bf16 v[34:37], v[146:149], v[226:229], v[34:37]
	v_mfma_f32_16x16x32_bf16 v[70:73], v[142:145], v[174:177], v[70:73]
	v_mfma_f32_16x16x32_bf16 v[66:69], v[150:153], v[174:177], v[66:69]
	v_mfma_f32_16x16x32_bf16 v[58:61], v[142:145], v[182:185], v[58:61]
	v_mfma_f32_16x16x32_bf16 v[50:53], v[150:153], v[182:185], v[50:53]
	v_mfma_f32_16x16x32_bf16 v[46:49], v[142:145], v[190:193], v[46:49]
	v_mfma_f32_16x16x32_bf16 v[42:45], v[150:153], v[190:193], v[42:45]
	v_mfma_f32_16x16x32_bf16 v[38:41], v[142:145], v[230:233], v[38:41]
	v_mfma_f32_16x16x32_bf16 v[34:37], v[150:153], v[230:233], v[34:37]
	s_setprio 0
	s_barrier
	s_add_i32 s27, s40, s50
	v_lshl_add_u64 v[226:227], s[42:43], 0, v[214:215]
	s_mov_b32 m0, s27
	ds_read_b128 v[186:189], v245 offset:16384
	ds_read_b128 v[190:193], v245 offset:17408
	ds_read_b128 v[178:181], v245 offset:18432
	ds_read_b128 v[182:185], v245 offset:19456
	ds_read_b128 v[170:173], v245 offset:20480
	ds_read_b128 v[174:177], v245 offset:21504
	ds_read_b128 v[130:133], v245 offset:22528
	ds_read_b128 v[134:137], v245 offset:23552
	global_load_lds_dwordx4 v[226:227], off
	s_add_i32 m0, s27, 0x2000
	s_add_u32 s40, s42, 0x40000
	v_lshl_add_u64 v[228:229], s[42:43], 0, v[218:219]
	s_addc_u32 s41, s43, 0
	s_add_i32 s25, s25, s50
	global_load_lds_dwordx4 v[228:229], off
	s_mov_b32 m0, s25
	v_lshl_add_u64 v[230:231], s[44:45], 0, v[194:195]
	global_load_lds_dwordx4 v214, s[40:41]
	s_add_i32 m0, s25, 0x2000
	v_lshl_add_u64 v[232:233], s[44:45], 0, v[216:217]
	global_load_lds_dwordx4 v218, s[40:41]
	s_mov_b32 m0, s51
	v_cndmask_b32_e64 v200, 0, 1, s[34:35]
	global_load_lds_dwordx4 v[230:231], off
	s_mov_b32 m0, s52
	v_cmp_ne_u32_e64 s[40:41], 1, v200
	global_load_lds_dwordx4 v[232:233], off
	s_waitcnt vmcnt(8)
	s_waitcnt lgkmcnt(0)
	s_andn2_b64 vcc, exec, s[34:35]
	s_barrier
	s_cbranch_vccnz .LBB0_888
	s_setprio 1
	v_mfma_f32_16x16x32_bf16 v[94:97], v[154:157], v[186:189], v[94:97]
	v_mfma_f32_16x16x32_bf16 v[90:93], v[162:165], v[186:189], v[90:93]
	v_mfma_f32_16x16x32_bf16 v[86:89], v[154:157], v[178:181], v[86:89]
	v_mfma_f32_16x16x32_bf16 v[82:85], v[162:165], v[178:181], v[82:85]
	v_mfma_f32_16x16x32_bf16 v[78:81], v[154:157], v[170:173], v[78:81]
	v_mfma_f32_16x16x32_bf16 v[74:77], v[162:165], v[170:173], v[74:77]
	v_mfma_f32_16x16x32_bf16 v[62:65], v[154:157], v[130:133], v[62:65]
	v_mfma_f32_16x16x32_bf16 v[54:57], v[162:165], v[130:133], v[54:57]
	v_mfma_f32_16x16x32_bf16 v[94:97], v[158:161], v[190:193], v[94:97]
	v_mfma_f32_16x16x32_bf16 v[90:93], v[166:169], v[190:193], v[90:93]
	v_mfma_f32_16x16x32_bf16 v[86:89], v[158:161], v[182:185], v[86:89]
	v_mfma_f32_16x16x32_bf16 v[82:85], v[166:169], v[182:185], v[82:85]
	v_mfma_f32_16x16x32_bf16 v[78:81], v[158:161], v[174:177], v[78:81]
	v_mfma_f32_16x16x32_bf16 v[74:77], v[166:169], v[174:177], v[74:77]
	v_mfma_f32_16x16x32_bf16 v[62:65], v[158:161], v[134:137], v[62:65]
	v_mfma_f32_16x16x32_bf16 v[54:57], v[166:169], v[134:137], v[54:57]
	s_setprio 0
	s_setprio 1
	v_mfma_f32_16x16x32_bf16 v[30:33], v[138:141], v[186:189], v[30:33]
	v_mfma_f32_16x16x32_bf16 v[26:29], v[146:149], v[186:189], v[26:29]
	v_mfma_f32_16x16x32_bf16 v[22:25], v[138:141], v[178:181], v[22:25]
	v_mfma_f32_16x16x32_bf16 v[18:21], v[146:149], v[178:181], v[18:21]
	v_mfma_f32_16x16x32_bf16 v[14:17], v[138:141], v[170:173], v[14:17]
	v_mfma_f32_16x16x32_bf16 v[10:13], v[146:149], v[170:173], v[10:13]
	v_mfma_f32_16x16x32_bf16 v[6:9], v[138:141], v[130:133], v[6:9]
	v_mfma_f32_16x16x32_bf16 v[2:5], v[146:149], v[130:133], v[2:5]
	v_mfma_f32_16x16x32_bf16 v[30:33], v[142:145], v[190:193], v[30:33]
	v_mfma_f32_16x16x32_bf16 v[26:29], v[150:153], v[190:193], v[26:29]
	v_mfma_f32_16x16x32_bf16 v[22:25], v[142:145], v[182:185], v[22:25]
	v_mfma_f32_16x16x32_bf16 v[18:21], v[150:153], v[182:185], v[18:21]
	v_mfma_f32_16x16x32_bf16 v[14:17], v[142:145], v[174:177], v[14:17]
	v_mfma_f32_16x16x32_bf16 v[10:13], v[150:153], v[174:177], v[10:13]
	v_mfma_f32_16x16x32_bf16 v[6:9], v[142:145], v[134:137], v[6:9]
	v_mfma_f32_16x16x32_bf16 v[2:5], v[150:153], v[134:137], v[2:5]
	s_setprio 0
; #define PG8_STAGE(bufoff, gbase, voff) do { _Pragma("unroll") for (int _i = 0; _i < 2; ++_i) \
;         __builtin_amdgcn_global_load_lds((const unsigned*)((const char*)(gbase) + (voff)[_i]), (LAS unsigned*)(lds + (bufoff) + ldsw + _i * 8192), 16, 0, 0); } while (0)
; #define PG8_LDA(dst, b, h) do { _Pragma("unroll") for (int m = 0; m < 4; ++m) _Pragma("unroll") for (int k = 0; k < 2; ++k) dst[m][k] = *(const LAS f16x8*)(lds + PG8_SA(b, h) + aoff + m * 2048 + k * 1024); } while (0)
; #define PG8_LDB(dst, b, h) do { _Pragma("unroll") for (int n = 0; n < 2; ++n) _Pragma("unroll") for (int k = 0; k < 2; ++k) dst[n][k] = *(const LAS f16x8*)(lds + PG8_SB(b, h) + boff + n * 2048 + k * 1024); } while (0)
; #define PG8_MMA(ai, bj, At, Bt) do { __builtin_amdgcn_s_setprio(1); _Pragma("unroll") for (int m = 0; m < 4; ++m) _Pragma("unroll") for (int n = 0; n < 2; ++n) _Pragma("unroll") for (int k = 0; k < 2; ++k) \
;         acc[ai][bj][m][n] = mma16_<Epi::BF16>(Bt[n][k], At[m][k], acc[ai][bj][m][n]); __builtin_amdgcn_s_setprio(0); } while (0)
; #define PG8_WAIT_V(n) asm volatile("s_waitcnt vmcnt(" #n ")" ::: "memory")
; #define PG8_WAIT_L(n) asm volatile("s_waitcnt lgkmcnt(" #n ")" ::: "memory")
; #define PG8_BAR __builtin_amdgcn_s_barrier()
; #define PG8_SCHED __builtin_amdgcn_sched_barrier(0)
;     ...
;             PG8_LDB(B0, 1, 0); PG8_LDB(B1, 1, 1); PG8_SCHED; PG8_LDA(At, 1, 0); PG8_STAGE(PG8_SA(0, 1), a2 + hA, voffA);
;             PG8_WAIT_V(8); PG8_WAIT_L(0); PG8_BAR; PG8_MMA(0, 0, At, B0); PG8_MMA(0, 1, At, B1); PG8_BAR; PG8_SCHED;
;             PG8_LDA(At, 1, 1); PG8_STAGE(PG8_SB(1, 0), b3, voffB); PG8_STAGE(PG8_SB(1, 1), b3 + hB, voffB); PG8_STAGE(PG8_SA(1, 0), a3, voffA);
;             PG8_WAIT_V(8); PG8_WAIT_L(0); PG8_BAR; if (!cur.half) { PG8_MMA(1, 0, At, B0); PG8_MMA(1, 1, At, B1); } PG8_BAR; PG8_SCHED;
.LBB0_888:
	s_barrier
	s_add_i32 s25, 0, 0x18000
	s_waitcnt lgkmcnt(0)
	v_add_u32_e32 v130, s25, v244
	s_add_i32 s27, 0, 0x1c000
	ds_read_b128 v[154:157], v130
	ds_read_b128 v[158:161], v130 offset:1024
	ds_read_b128 v[162:165], v130 offset:2048
	ds_read_b128 v[166:169], v130 offset:3072
	v_add_u32_e32 v130, s27, v244
	ds_read_b128 v[138:141], v130
	ds_read_b128 v[142:145], v130 offset:1024
	ds_read_b128 v[146:149], v130 offset:2048
	ds_read_b128 v[150:153], v130 offset:3072
	s_add_u32 s44, s44, 0x40000
	s_addc_u32 s45, s45, 0
	s_mov_b32 m0, s53
	ds_read_b128 v[170:173], v245 offset:32768
	ds_read_b128 v[174:177], v245 offset:33792
	ds_read_b128 v[178:181], v245 offset:34816
	ds_read_b128 v[182:185], v245 offset:35840
	ds_read_b128 v[186:189], v245 offset:36864
	ds_read_b128 v[190:193], v245 offset:37888
	ds_read_b128 v[246:249], v245 offset:38912
	ds_read_b128 v[200:203], v245 offset:39936
	global_load_lds_dwordx4 v194, s[44:45]
	s_mov_b32 m0, s54
	s_nop 0
	global_load_lds_dwordx4 v216, s[44:45]
	s_waitcnt vmcnt(8)
	s_waitcnt lgkmcnt(0)
	s_barrier
	s_setprio 1
	v_mfma_f32_16x16x32_bf16 v[106:109], v[154:157], v[170:173], v[106:109]
	v_mfma_f32_16x16x32_bf16 v[134:137], v[158:161], v[174:177], v[106:109]
	v_mfma_f32_16x16x32_bf16 v[106:109], v[162:165], v[170:173], v[110:113]
	v_mfma_f32_16x16x32_bf16 v[130:133], v[166:169], v[174:177], v[106:109]
	v_mfma_f32_16x16x32_bf16 v[106:109], v[154:157], v[178:181], v[126:129]
	v_mfma_f32_16x16x32_bf16 v[126:129], v[158:161], v[182:185], v[106:109]
	v_mfma_f32_16x16x32_bf16 v[106:109], v[162:165], v[178:181], v[122:125]
	v_mfma_f32_16x16x32_bf16 v[122:125], v[166:169], v[182:185], v[106:109]
	v_mfma_f32_16x16x32_bf16 v[106:109], v[154:157], v[186:189], v[118:121]
	v_mfma_f32_16x16x32_bf16 v[118:121], v[158:161], v[190:193], v[106:109]
	v_mfma_f32_16x16x32_bf16 v[106:109], v[162:165], v[186:189], v[114:117]
	v_mfma_f32_16x16x32_bf16 v[102:105], v[154:157], v[246:249], v[102:105]
	v_mfma_f32_16x16x32_bf16 v[98:101], v[162:165], v[246:249], v[98:101]
	v_mfma_f32_16x16x32_bf16 v[114:117], v[166:169], v[190:193], v[106:109]
	v_mfma_f32_16x16x32_bf16 v[102:105], v[158:161], v[200:203], v[102:105]
	v_mfma_f32_16x16x32_bf16 v[98:101], v[166:169], v[200:203], v[98:101]
	s_setprio 0
	s_setprio 1
	v_mfma_f32_16x16x32_bf16 v[70:73], v[138:141], v[170:173], v[70:73]
	v_mfma_f32_16x16x32_bf16 v[66:69], v[146:149], v[170:173], v[66:69]
	v_mfma_f32_16x16x32_bf16 v[58:61], v[138:141], v[178:181], v[58:61]
	v_mfma_f32_16x16x32_bf16 v[50:53], v[146:149], v[178:181], v[50:53]
	v_mfma_f32_16x16x32_bf16 v[46:49], v[138:141], v[186:189], v[46:49]
	v_mfma_f32_16x16x32_bf16 v[42:45], v[146:149], v[186:189], v[42:45]
	v_mfma_f32_16x16x32_bf16 v[38:41], v[138:141], v[246:249], v[38:41]
	v_mfma_f32_16x16x32_bf16 v[34:37], v[146:149], v[246:249], v[34:37]
	v_mfma_f32_16x16x32_bf16 v[70:73], v[142:145], v[174:177], v[70:73]
	v_mfma_f32_16x16x32_bf16 v[66:69], v[150:153], v[174:177], v[66:69]
	v_mfma_f32_16x16x32_bf16 v[58:61], v[142:145], v[182:185], v[58:61]
	v_mfma_f32_16x16x32_bf16 v[50:53], v[150:153], v[182:185], v[50:53]
	v_mfma_f32_16x16x32_bf16 v[46:49], v[142:145], v[190:193], v[46:49]
	v_mfma_f32_16x16x32_bf16 v[42:45], v[150:153], v[190:193], v[42:45]
	v_mfma_f32_16x16x32_bf16 v[38:41], v[142:145], v[200:203], v[38:41]
	v_mfma_f32_16x16x32_bf16 v[34:37], v[150:153], v[200:203], v[34:37]
	s_setprio 0
	s_barrier
	s_add_i32 s25, s25, s50
	v_lshl_add_u64 v[200:201], v[226:227], 0, s[96:97]
	s_mov_b32 m0, s25
	ds_read_b128 v[186:189], v245 offset:49152
	ds_read_b128 v[190:193], v245 offset:50176
	ds_read_b128 v[178:181], v245 offset:51200
	ds_read_b128 v[182:185], v245 offset:52224
	ds_read_b128 v[170:173], v245 offset:53248
	ds_read_b128 v[174:177], v245 offset:54272
	ds_read_b128 v[106:109], v245 offset:55296
	ds_read_b128 v[110:113], v245 offset:56320
	global_load_lds_dwordx4 v[200:201], off
	s_add_i32 m0, s25, 0x2000
	s_add_u32 s42, s42, 0x40080
	v_lshl_add_u64 v[200:201], v[228:229], 0, s[96:97]
	s_addc_u32 s43, s43, 0
	s_add_i32 s25, s27, s50
	global_load_lds_dwordx4 v[200:201], off
	s_mov_b32 m0, s25
	s_and_b64 vcc, exec, s[40:41]
	global_load_lds_dwordx4 v214, s[42:43]
	s_add_i32 m0, s25, 0x2000
	s_nop 0
	global_load_lds_dwordx4 v218, s[42:43]
	v_lshl_add_u64 v[200:201], v[230:231], 0, s[96:97]
	s_mov_b32 m0, s57
	s_nop 0
	global_load_lds_dwordx4 v[200:201], off
	v_lshl_add_u64 v[200:201], v[232:233], 0, s[96:97]
	s_mov_b32 m0, s58
	s_nop 0
	global_load_lds_dwordx4 v[200:201], off
	s_waitcnt vmcnt(8)
	s_waitcnt lgkmcnt(0)
	s_barrier
	s_cbranch_vccnz .LBB0_885
	s_setprio 1
	v_mfma_f32_16x16x32_bf16 v[94:97], v[154:157], v[186:189], v[94:97]
	v_mfma_f32_16x16x32_bf16 v[90:93], v[162:165], v[186:189], v[90:93]
	v_mfma_f32_16x16x32_bf16 v[86:89], v[154:157], v[178:181], v[86:89]
	v_mfma_f32_16x16x32_bf16 v[82:85], v[162:165], v[178:181], v[82:85]
	v_mfma_f32_16x16x32_bf16 v[78:81], v[154:157], v[170:173], v[78:81]
	v_mfma_f32_16x16x32_bf16 v[74:77], v[162:165], v[170:173], v[74:77]
	v_mfma_f32_16x16x32_bf16 v[62:65], v[154:157], v[106:109], v[62:65]
	v_mfma_f32_16x16x32_bf16 v[54:57], v[162:165], v[106:109], v[54:57]
	v_mfma_f32_16x16x32_bf16 v[94:97], v[158:161], v[190:193], v[94:97]
	v_mfma_f32_16x16x32_bf16 v[90:93], v[166:169], v[190:193], v[90:93]
	v_mfma_f32_16x16x32_bf16 v[86:89], v[158:161], v[182:185], v[86:89]
	v_mfma_f32_16x16x32_bf16 v[82:85], v[166:169], v[182:185], v[82:85]
	v_mfma_f32_16x16x32_bf16 v[78:81], v[158:161], v[174:177], v[78:81]
	v_mfma_f32_16x16x32_bf16 v[74:77], v[166:169], v[174:177], v[74:77]
	v_mfma_f32_16x16x32_bf16 v[62:65], v[158:161], v[110:113], v[62:65]
	v_mfma_f32_16x16x32_bf16 v[54:57], v[166:169], v[110:113], v[54:57]
	s_setprio 0
	s_setprio 1
	v_mfma_f32_16x16x32_bf16 v[30:33], v[138:141], v[186:189], v[30:33]
	v_mfma_f32_16x16x32_bf16 v[26:29], v[146:149], v[186:189], v[26:29]
	v_mfma_f32_16x16x32_bf16 v[22:25], v[138:141], v[178:181], v[22:25]
	v_mfma_f32_16x16x32_bf16 v[18:21], v[146:149], v[178:181], v[18:21]
	v_mfma_f32_16x16x32_bf16 v[14:17], v[138:141], v[170:173], v[14:17]
	v_mfma_f32_16x16x32_bf16 v[10:13], v[146:149], v[170:173], v[10:13]
	v_mfma_f32_16x16x32_bf16 v[6:9], v[138:141], v[106:109], v[6:9]
	v_mfma_f32_16x16x32_bf16 v[2:5], v[146:149], v[106:109], v[2:5]
	v_mfma_f32_16x16x32_bf16 v[30:33], v[142:145], v[190:193], v[30:33]
	v_mfma_f32_16x16x32_bf16 v[26:29], v[150:153], v[190:193], v[26:29]
	v_mfma_f32_16x16x32_bf16 v[22:25], v[142:145], v[182:185], v[22:25]
	v_mfma_f32_16x16x32_bf16 v[18:21], v[150:153], v[182:185], v[18:21]
	v_mfma_f32_16x16x32_bf16 v[14:17], v[142:145], v[174:177], v[14:17]
	v_mfma_f32_16x16x32_bf16 v[10:13], v[150:153], v[174:177], v[10:13]
	v_mfma_f32_16x16x32_bf16 v[6:9], v[142:145], v[110:113], v[6:9]
	v_mfma_f32_16x16x32_bf16 v[2:5], v[150:153], v[110:113], v[2:5]
	s_setprio 0
	s_branch .LBB0_885

; #define PG8_STAGE(bufoff, gbase, voff) do { _Pragma("unroll") for (int _i = 0; _i < 2; ++_i) \
;         __builtin_amdgcn_global_load_lds((const unsigned*)((const char*)(gbase) + (voff)[_i]), (LAS unsigned*)(lds + (bufoff) + ldsw + _i * 8192), 16, 0, 0); } while (0)
; #define PG8_LDA(dst, b, h) do { _Pragma("unroll") for (int m = 0; m < 4; ++m) _Pragma("unroll") for (int k = 0; k < 2; ++k) dst[m][k] = *(const LAS f16x8*)(lds + PG8_SA(b, h) + aoff + m * 2048 + k * 1024); } while (0)
; #define PG8_LDB(dst, b, h) do { _Pragma("unroll") for (int n = 0; n < 2; ++n) _Pragma("unroll") for (int k = 0; k < 2; ++k) dst[n][k] = *(const LAS f16x8*)(lds + PG8_SB(b, h) + boff + n * 2048 + k * 1024); } while (0)
; #define PG8_MMA(ai, bj, At, Bt) do { __builtin_amdgcn_s_setprio(1); _Pragma("unroll") for (int m = 0; m < 4; ++m) _Pragma("unroll") for (int n = 0; n < 2; ++n) _Pragma("unroll") for (int k = 0; k < 2; ++k) \
;         acc[ai][bj][m][n] = mma16_<Epi::BF16>(Bt[n][k], At[m][k], acc[ai][bj][m][n]); __builtin_amdgcn_s_setprio(0); } while (0)
; #define PG8_WAIT_V(n) asm volatile("s_waitcnt vmcnt(" #n ")" ::: "memory")
; #define PG8_WAIT_L(n) asm volatile("s_waitcnt lgkmcnt(" #n ")" ::: "memory")
; #define PG8_BAR __builtin_amdgcn_s_barrier()
; #define PG8_SCHED __builtin_amdgcn_sched_barrier(0)
;     ...
;             const bool last = (t == nt - 2);
;             const char* a1 = cA + (size_t)(t + 1) * kstep;
;             const char* a2 = last ? nA : cA + (size_t)(t + 2) * kstep; const char* b2 = last ? nB : cB + (size_t)(t + 2) * kstep;
;             const char* a3 = a2 + kstep; const char* b3 = b2 + kstep;
;             if constexpr (SP2) {
;             PG8_LDB(B0, 0, 0); PG8_LDB(B1, 0, 1); PG8_SCHED; PG8_LDA(At, 0, 0); PG8_STAGE(PG8_SA(1, 1), a1 + hA, voffA);
;             PG8_WAIT_V(8); PG8_WAIT_L(0); PG8_BAR; PG8_MMA(0, 0, At, B0); PG8_MMA(0, 1, At, B1); PG8_BAR; PG8_SCHED;
;             PG8_LDA(At, 0, 1); PG8_STAGE(PG8_SB(0, 0), b2, voffB); PG8_STAGE(PG8_SB(0, 1), b2 + hB, voffB); PG8_STAGE(PG8_SA(0, 0), a2, voffA);
.LBB0_1018:
	s_add_u32 s34, s30, 0xfffc0080
	s_addc_u32 s35, s31, -1
	s_add_i32 s54, 0, 0x10000
	s_cmp_eq_u32 s53, 12
	s_cselect_b32 s37, s2, s35
	s_cselect_b32 s36, s3, s34
	s_cselect_b32 s35, s19, s52
	s_cselect_b32 s34, s21, s51
	s_add_i32 s56, 0, 0x14000
	v_add_u32_e32 v156, s54, v141
	v_add_u32_e32 v172, s56, v141
	ds_read_b128 v[144:147], v156
	ds_read_b128 v[148:151], v156 offset:1024
	ds_read_b128 v[152:155], v156 offset:2048
	ds_read_b128 v[156:159], v156 offset:3072
	ds_read_b128 v[160:163], v172
	ds_read_b128 v[164:167], v172 offset:1024
	ds_read_b128 v[168:171], v172 offset:2048
	ds_read_b128 v[172:175], v172 offset:3072
	s_add_i32 m0, s27, 0xc000
	ds_read_b128 v[176:179], v143
	ds_read_b128 v[180:183], v143 offset:1024
	ds_read_b128 v[184:187], v143 offset:2048
	ds_read_b128 v[188:191], v143 offset:3072
	ds_read_b128 v[192:195], v143 offset:4096
	ds_read_b128 v[200:203], v143 offset:5120
	ds_read_b128 v[214:217], v143 offset:6144
	ds_read_b128 v[218:221], v143 offset:7168
	global_load_lds_dwordx4 v136, s[30:31]
	s_add_i32 m0, s27, 0xe000
	s_nop 0
	global_load_lds_dwordx4 v138, s[30:31]
	s_waitcnt vmcnt(8)
	s_waitcnt lgkmcnt(0)
	s_barrier
	s_setprio 1
	v_mfma_f32_16x16x32_bf16 v[126:129], v[144:147], v[176:179], v[126:129]
	v_mfma_f32_16x16x32_bf16 v[118:121], v[152:155], v[176:179], v[118:121]
	v_mfma_f32_16x16x32_bf16 v[110:113], v[144:147], v[184:187], v[110:113]
	v_mfma_f32_16x16x32_bf16 v[102:105], v[152:155], v[184:187], v[102:105]
	v_mfma_f32_16x16x32_bf16 v[94:97], v[144:147], v[192:195], v[94:97]
	v_mfma_f32_16x16x32_bf16 v[86:89], v[152:155], v[192:195], v[86:89]
	v_mfma_f32_16x16x32_bf16 v[78:81], v[144:147], v[214:217], v[78:81]
	v_mfma_f32_16x16x32_bf16 v[70:73], v[152:155], v[214:217], v[70:73]
	v_mfma_f32_16x16x32_bf16 v[126:129], v[148:151], v[180:183], v[126:129]
	v_mfma_f32_16x16x32_bf16 v[118:121], v[156:159], v[180:183], v[118:121]
	v_mfma_f32_16x16x32_bf16 v[110:113], v[148:151], v[188:191], v[110:113]
	v_mfma_f32_16x16x32_bf16 v[102:105], v[156:159], v[188:191], v[102:105]
	v_mfma_f32_16x16x32_bf16 v[94:97], v[148:151], v[200:203], v[94:97]
	v_mfma_f32_16x16x32_bf16 v[86:89], v[156:159], v[200:203], v[86:89]
	v_mfma_f32_16x16x32_bf16 v[78:81], v[148:151], v[218:221], v[78:81]
	v_mfma_f32_16x16x32_bf16 v[70:73], v[156:159], v[218:221], v[70:73]
	s_setprio 0
	s_setprio 1
	v_mfma_f32_16x16x32_bf16 v[122:125], v[160:163], v[176:179], v[122:125]
	v_mfma_f32_16x16x32_bf16 v[114:117], v[168:171], v[176:179], v[114:117]
	v_mfma_f32_16x16x32_bf16 v[106:109], v[160:163], v[184:187], v[106:109]
	v_mfma_f32_16x16x32_bf16 v[98:101], v[168:171], v[184:187], v[98:101]
	v_mfma_f32_16x16x32_bf16 v[90:93], v[160:163], v[192:195], v[90:93]
	v_mfma_f32_16x16x32_bf16 v[82:85], v[168:171], v[192:195], v[82:85]
	v_mfma_f32_16x16x32_bf16 v[74:77], v[160:163], v[214:217], v[74:77]
	v_mfma_f32_16x16x32_bf16 v[66:69], v[168:171], v[214:217], v[66:69]
	v_mfma_f32_16x16x32_bf16 v[122:125], v[164:167], v[180:183], v[122:125]
	v_mfma_f32_16x16x32_bf16 v[114:117], v[172:175], v[180:183], v[114:117]
	v_mfma_f32_16x16x32_bf16 v[106:109], v[164:167], v[188:191], v[106:109]
	v_mfma_f32_16x16x32_bf16 v[98:101], v[172:175], v[188:191], v[98:101]
	v_mfma_f32_16x16x32_bf16 v[90:93], v[164:167], v[200:203], v[90:93]
	v_mfma_f32_16x16x32_bf16 v[82:85], v[172:175], v[200:203], v[82:85]
	v_mfma_f32_16x16x32_bf16 v[74:77], v[164:167], v[218:221], v[74:77]
	v_mfma_f32_16x16x32_bf16 v[66:69], v[172:175], v[218:221], v[66:69]
	s_setprio 0
	s_barrier
	s_add_i32 s54, s54, s40
	v_lshl_add_u64 v[222:223], s[34:35], 0, v[0:1]
	s_mov_b32 m0, s54
	ds_read_b128 v[176:179], v143 offset:16384
	ds_read_b128 v[180:183], v143 offset:17408
	ds_read_b128 v[184:187], v143 offset:18432
	ds_read_b128 v[188:191], v143 offset:19456
	ds_read_b128 v[192:195], v143 offset:20480
	ds_read_b128 v[200:203], v143 offset:21504
	ds_read_b128 v[214:217], v143 offset:22528
	ds_read_b128 v[218:221], v143 offset:23552
	global_load_lds_dwordx4 v[222:223], off
	s_add_i32 m0, s54, 0x2000
	s_add_u32 s54, s34, 0x40000
	v_lshl_add_u64 v[224:225], s[34:35], 0, v[130:131]
	s_addc_u32 s55, s35, 0
	s_add_i32 s56, s56, s40
	global_load_lds_dwordx4 v[224:225], off
	s_mov_b32 m0, s56
	v_lshl_add_u64 v[228:229], s[36:37], 0, v[132:133]
	global_load_lds_dwordx4 v0, s[54:55]
	s_add_i32 m0, s56, 0x2000
	s_nop 0
	global_load_lds_dwordx4 v130, s[54:55]
	v_lshl_add_u64 v[226:227], s[36:37], 0, v[134:135]
	s_mov_b32 m0, s27
	s_nop 0
	global_load_lds_dwordx4 v[226:227], off
	s_mov_b32 m0, s29
	s_nop 0
	global_load_lds_dwordx4 v[228:229], off
	s_waitcnt vmcnt(8)
	s_waitcnt lgkmcnt(0)
	s_barrier
; #define PG8_STAGE(bufoff, gbase, voff) do { _Pragma("unroll") for (int _i = 0; _i < 2; ++_i) \
;         __builtin_amdgcn_global_load_lds((const unsigned*)((const char*)(gbase) + (voff)[_i]), (LAS unsigned*)(lds + (bufoff) + ldsw + _i * 8192), 16, 0, 0); } while (0)
; #define PG8_LDA(dst, b, h) do { _Pragma("unroll") for (int m = 0; m < 4; ++m) _Pragma("unroll") for (int k = 0; k < 2; ++k) dst[m][k] = *(const LAS f16x8*)(lds + PG8_SA(b, h) + aoff + m * 2048 + k * 1024); } while (0)
; #define PG8_LDB(dst, b, h) do { _Pragma("unroll") for (int n = 0; n < 2; ++n) _Pragma("unroll") for (int k = 0; k < 2; ++k) dst[n][k] = *(const LAS f16x8*)(lds + PG8_SB(b, h) + boff + n * 2048 + k * 1024); } while (0)
; #define PG8_MMA(ai, bj, At, Bt) do { __builtin_amdgcn_s_setprio(1); _Pragma("unroll") for (int m = 0; m < 4; ++m) _Pragma("unroll") for (int n = 0; n < 2; ++n) _Pragma("unroll") for (int k = 0; k < 2; ++k) \
;         acc[ai][bj][m][n] = mma16_<Epi::BF16>(Bt[n][k], At[m][k], acc[ai][bj][m][n]); __builtin_amdgcn_s_setprio(0); } while (0)
; #define PG8_WAIT_V(n) asm volatile("s_waitcnt vmcnt(" #n ")" ::: "memory")
; #define PG8_WAIT_L(n) asm volatile("s_waitcnt lgkmcnt(" #n ")" ::: "memory")
; #define PG8_BAR __builtin_amdgcn_s_barrier()
; #define PG8_SCHED __builtin_amdgcn_sched_barrier(0)
;     ...
;             PG8_WAIT_V(8); PG8_WAIT_L(0); PG8_BAR; if (!cur.half) { PG8_MMA(1, 0, At, B0); PG8_MMA(1, 1, At, B1); } PG8_BAR; PG8_SCHED;
;             PG8_LDB(B0, 1, 0); PG8_LDB(B1, 1, 1); PG8_SCHED; PG8_LDA(At, 1, 0); PG8_STAGE(PG8_SA(0, 1), a2 + hA, voffA);
;             PG8_WAIT_V(8); PG8_WAIT_L(0); PG8_BAR; PG8_MMA(0, 0, At, B0); PG8_MMA(0, 1, At, B1); PG8_BAR; PG8_SCHED;
	s_setprio 1
	v_mfma_f32_16x16x32_bf16 v[62:65], v[144:147], v[176:179], v[62:65]
	v_mfma_f32_16x16x32_bf16 v[54:57], v[152:155], v[176:179], v[54:57]
	v_mfma_f32_16x16x32_bf16 v[46:49], v[144:147], v[184:187], v[46:49]
	v_mfma_f32_16x16x32_bf16 v[38:41], v[152:155], v[184:187], v[38:41]
	v_mfma_f32_16x16x32_bf16 v[30:33], v[144:147], v[192:195], v[30:33]
	v_mfma_f32_16x16x32_bf16 v[22:25], v[152:155], v[192:195], v[22:25]
	v_mfma_f32_16x16x32_bf16 v[14:17], v[144:147], v[214:217], v[14:17]
	v_mfma_f32_16x16x32_bf16 v[6:9], v[152:155], v[214:217], v[6:9]
	v_mfma_f32_16x16x32_bf16 v[62:65], v[148:151], v[180:183], v[62:65]
	v_mfma_f32_16x16x32_bf16 v[54:57], v[156:159], v[180:183], v[54:57]
	v_mfma_f32_16x16x32_bf16 v[46:49], v[148:151], v[188:191], v[46:49]
	v_mfma_f32_16x16x32_bf16 v[38:41], v[156:159], v[188:191], v[38:41]
	v_mfma_f32_16x16x32_bf16 v[30:33], v[148:151], v[200:203], v[30:33]
	v_mfma_f32_16x16x32_bf16 v[22:25], v[156:159], v[200:203], v[22:25]
	v_mfma_f32_16x16x32_bf16 v[14:17], v[148:151], v[218:221], v[14:17]
	v_mfma_f32_16x16x32_bf16 v[6:9], v[156:159], v[218:221], v[6:9]
	s_setprio 0
	s_setprio 1
	v_mfma_f32_16x16x32_bf16 v[58:61], v[160:163], v[176:179], v[58:61]
	v_mfma_f32_16x16x32_bf16 v[50:53], v[168:171], v[176:179], v[50:53]
	v_mfma_f32_16x16x32_bf16 v[42:45], v[160:163], v[184:187], v[42:45]
	v_mfma_f32_16x16x32_bf16 v[34:37], v[168:171], v[184:187], v[34:37]
	v_mfma_f32_16x16x32_bf16 v[26:29], v[160:163], v[192:195], v[26:29]
	v_mfma_f32_16x16x32_bf16 v[18:21], v[168:171], v[192:195], v[18:21]
	v_mfma_f32_16x16x32_bf16 v[10:13], v[160:163], v[214:217], v[10:13]
	v_mfma_f32_16x16x32_bf16 v[2:5], v[168:171], v[214:217], v[2:5]
	v_mfma_f32_16x16x32_bf16 v[58:61], v[164:167], v[180:183], v[58:61]
	v_mfma_f32_16x16x32_bf16 v[50:53], v[172:175], v[180:183], v[50:53]
	v_mfma_f32_16x16x32_bf16 v[42:45], v[164:167], v[188:191], v[42:45]
	v_mfma_f32_16x16x32_bf16 v[34:37], v[172:175], v[188:191], v[34:37]
	v_mfma_f32_16x16x32_bf16 v[26:29], v[164:167], v[200:203], v[26:29]
	v_mfma_f32_16x16x32_bf16 v[18:21], v[172:175], v[200:203], v[18:21]
	v_mfma_f32_16x16x32_bf16 v[10:13], v[164:167], v[218:221], v[10:13]
	v_mfma_f32_16x16x32_bf16 v[2:5], v[172:175], v[218:221], v[2:5]
	s_setprio 0
	s_barrier
	s_add_i32 s54, 0, 0x18000
	s_add_i32 s55, 0, 0x1c000
	v_add_u32_e32 v156, s54, v141
	v_add_u32_e32 v172, s55, v141
	ds_read_b128 v[144:147], v156
	ds_read_b128 v[148:151], v156 offset:1024
	ds_read_b128 v[152:155], v156 offset:2048
	ds_read_b128 v[156:159], v156 offset:3072
	ds_read_b128 v[160:163], v172
	ds_read_b128 v[164:167], v172 offset:1024
	ds_read_b128 v[168:171], v172 offset:2048
	ds_read_b128 v[172:175], v172 offset:3072
	s_add_u32 s36, s36, 0x40000
	s_addc_u32 s37, s37, 0
	s_mov_b32 m0, s43
	ds_read_b128 v[176:179], v143 offset:32768
	ds_read_b128 v[180:183], v143 offset:33792
	ds_read_b128 v[184:187], v143 offset:34816
	ds_read_b128 v[188:191], v143 offset:35840
	ds_read_b128 v[192:195], v143 offset:36864
	ds_read_b128 v[200:203], v143 offset:37888
	ds_read_b128 v[214:217], v143 offset:38912
	ds_read_b128 v[218:221], v143 offset:39936
	global_load_lds_dwordx4 v134, s[36:37]
	s_mov_b32 m0, s44
	s_nop 0
	global_load_lds_dwordx4 v132, s[36:37]
	s_waitcnt vmcnt(8)
	s_waitcnt lgkmcnt(0)
	s_barrier
	s_setprio 1
	v_mfma_f32_16x16x32_bf16 v[126:129], v[144:147], v[176:179], v[126:129]
	v_mfma_f32_16x16x32_bf16 v[118:121], v[152:155], v[176:179], v[118:121]
	v_mfma_f32_16x16x32_bf16 v[110:113], v[144:147], v[184:187], v[110:113]
	v_mfma_f32_16x16x32_bf16 v[102:105], v[152:155], v[184:187], v[102:105]
	v_mfma_f32_16x16x32_bf16 v[94:97], v[144:147], v[192:195], v[94:97]
	v_mfma_f32_16x16x32_bf16 v[86:89], v[152:155], v[192:195], v[86:89]
	v_mfma_f32_16x16x32_bf16 v[78:81], v[144:147], v[214:217], v[78:81]
	v_mfma_f32_16x16x32_bf16 v[70:73], v[152:155], v[214:217], v[70:73]
	v_mfma_f32_16x16x32_bf16 v[126:129], v[148:151], v[180:183], v[126:129]
	v_mfma_f32_16x16x32_bf16 v[118:121], v[156:159], v[180:183], v[118:121]
	v_mfma_f32_16x16x32_bf16 v[110:113], v[148:151], v[188:191], v[110:113]
	v_mfma_f32_16x16x32_bf16 v[102:105], v[156:159], v[188:191], v[102:105]
	v_mfma_f32_16x16x32_bf16 v[94:97], v[148:151], v[200:203], v[94:97]
	v_mfma_f32_16x16x32_bf16 v[86:89], v[156:159], v[200:203], v[86:89]
	v_mfma_f32_16x16x32_bf16 v[78:81], v[148:151], v[218:221], v[78:81]
	v_mfma_f32_16x16x32_bf16 v[70:73], v[156:159], v[218:221], v[70:73]
	s_setprio 0
	s_setprio 1
	v_mfma_f32_16x16x32_bf16 v[122:125], v[160:163], v[176:179], v[122:125]
	v_mfma_f32_16x16x32_bf16 v[114:117], v[168:171], v[176:179], v[114:117]
	v_mfma_f32_16x16x32_bf16 v[106:109], v[160:163], v[184:187], v[106:109]
	v_mfma_f32_16x16x32_bf16 v[98:101], v[168:171], v[184:187], v[98:101]
	v_mfma_f32_16x16x32_bf16 v[90:93], v[160:163], v[192:195], v[90:93]
	v_mfma_f32_16x16x32_bf16 v[82:85], v[168:171], v[192:195], v[82:85]
	v_mfma_f32_16x16x32_bf16 v[74:77], v[160:163], v[214:217], v[74:77]
	v_mfma_f32_16x16x32_bf16 v[66:69], v[168:171], v[214:217], v[66:69]
	v_mfma_f32_16x16x32_bf16 v[122:125], v[164:167], v[180:183], v[122:125]
	v_mfma_f32_16x16x32_bf16 v[114:117], v[172:175], v[180:183], v[114:117]
	v_mfma_f32_16x16x32_bf16 v[106:109], v[164:167], v[188:191], v[106:109]
	v_mfma_f32_16x16x32_bf16 v[98:101], v[172:175], v[188:191], v[98:101]
	v_mfma_f32_16x16x32_bf16 v[90:93], v[164:167], v[200:203], v[90:93]
	v_mfma_f32_16x16x32_bf16 v[82:85], v[172:175], v[200:203], v[82:85]
	v_mfma_f32_16x16x32_bf16 v[74:77], v[164:167], v[218:221], v[74:77]
	v_mfma_f32_16x16x32_bf16 v[66:69], v[172:175], v[218:221], v[66:69]
	s_setprio 0
	s_barrier
; #define PG8_STAGE(bufoff, gbase, voff) do { _Pragma("unroll") for (int _i = 0; _i < 2; ++_i) \
;         __builtin_amdgcn_global_load_lds((const unsigned*)((const char*)(gbase) + (voff)[_i]), (LAS unsigned*)(lds + (bufoff) + ldsw + _i * 8192), 16, 0, 0); } while (0)
; #define PG8_LDA(dst, b, h) do { _Pragma("unroll") for (int m = 0; m < 4; ++m) _Pragma("unroll") for (int k = 0; k < 2; ++k) dst[m][k] = *(const LAS f16x8*)(lds + PG8_SA(b, h) + aoff + m * 2048 + k * 1024); } while (0)
; #define PG8_MMA(ai, bj, At, Bt) do { __builtin_amdgcn_s_setprio(1); _Pragma("unroll") for (int m = 0; m < 4; ++m) _Pragma("unroll") for (int n = 0; n < 2; ++n) _Pragma("unroll") for (int k = 0; k < 2; ++k) \
;         acc[ai][bj][m][n] = mma16_<Epi::BF16>(Bt[n][k], At[m][k], acc[ai][bj][m][n]); __builtin_amdgcn_s_setprio(0); } while (0)
; #define PG8_WAIT_V(n) asm volatile("s_waitcnt vmcnt(" #n ")" ::: "memory")
; #define PG8_WAIT_L(n) asm volatile("s_waitcnt lgkmcnt(" #n ")" ::: "memory")
; #define PG8_BAR __builtin_amdgcn_s_barrier()
; #define PG8_SCHED __builtin_amdgcn_sched_barrier(0)
;     ...
;         for (int t = 0; t < nt; t += 2) {
;     ...
;             PG8_LDA(At, 1, 1); PG8_STAGE(PG8_SB(1, 0), b3, voffB); PG8_STAGE(PG8_SB(1, 1), b3 + hB, voffB); PG8_STAGE(PG8_SA(1, 0), a3, voffA);
;             PG8_WAIT_V(8); PG8_WAIT_L(0); PG8_BAR; if (!cur.half) { PG8_MMA(1, 0, At, B0); PG8_MMA(1, 1, At, B1); } PG8_BAR; PG8_SCHED;
	s_add_i32 s36, s54, s40
	v_lshl_add_u64 v[222:223], v[222:223], 0, s[96:97]
	s_mov_b32 m0, s36
	ds_read_b128 v[176:179], v143 offset:49152
	ds_read_b128 v[180:183], v143 offset:50176
	ds_read_b128 v[184:187], v143 offset:51200
	ds_read_b128 v[188:191], v143 offset:52224
	ds_read_b128 v[192:195], v143 offset:53248
	ds_read_b128 v[200:203], v143 offset:54272
	ds_read_b128 v[214:217], v143 offset:55296
	ds_read_b128 v[218:221], v143 offset:56320
	global_load_lds_dwordx4 v[222:223], off
	s_add_i32 m0, s36, 0x2000
	s_add_u32 s34, s34, 0x40080
	v_lshl_add_u64 v[222:223], v[224:225], 0, s[96:97]
	s_addc_u32 s35, s35, 0
	s_add_i32 s36, s55, s40
	global_load_lds_dwordx4 v[222:223], off
	s_mov_b32 m0, s36
	s_nop 0
	global_load_lds_dwordx4 v0, s[34:35]
	s_add_i32 m0, s36, 0x2000
	s_nop 0
	global_load_lds_dwordx4 v130, s[34:35]
	v_lshl_add_u64 v[222:223], v[226:227], 0, s[96:97]
	s_mov_b32 m0, s45
	s_nop 0
	global_load_lds_dwordx4 v[222:223], off
	v_lshl_add_u64 v[222:223], v[228:229], 0, s[96:97]
	s_mov_b32 m0, s47
	s_nop 0
	global_load_lds_dwordx4 v[222:223], off
	s_waitcnt vmcnt(8)
	s_waitcnt lgkmcnt(0)
	s_barrier
	s_setprio 1
	v_mfma_f32_16x16x32_bf16 v[62:65], v[144:147], v[176:179], v[62:65]
	v_mfma_f32_16x16x32_bf16 v[54:57], v[152:155], v[176:179], v[54:57]
	v_mfma_f32_16x16x32_bf16 v[46:49], v[144:147], v[184:187], v[46:49]
	v_mfma_f32_16x16x32_bf16 v[38:41], v[152:155], v[184:187], v[38:41]
	v_mfma_f32_16x16x32_bf16 v[30:33], v[144:147], v[192:195], v[30:33]
	v_mfma_f32_16x16x32_bf16 v[22:25], v[152:155], v[192:195], v[22:25]
	v_mfma_f32_16x16x32_bf16 v[14:17], v[144:147], v[214:217], v[14:17]
	v_mfma_f32_16x16x32_bf16 v[6:9], v[152:155], v[214:217], v[6:9]
	v_mfma_f32_16x16x32_bf16 v[62:65], v[148:151], v[180:183], v[62:65]
	v_mfma_f32_16x16x32_bf16 v[54:57], v[156:159], v[180:183], v[54:57]
	v_mfma_f32_16x16x32_bf16 v[46:49], v[148:151], v[188:191], v[46:49]
	v_mfma_f32_16x16x32_bf16 v[38:41], v[156:159], v[188:191], v[38:41]
	v_mfma_f32_16x16x32_bf16 v[30:33], v[148:151], v[200:203], v[30:33]
	v_mfma_f32_16x16x32_bf16 v[22:25], v[156:159], v[200:203], v[22:25]
	v_mfma_f32_16x16x32_bf16 v[14:17], v[148:151], v[218:221], v[14:17]
	v_mfma_f32_16x16x32_bf16 v[6:9], v[156:159], v[218:221], v[6:9]
	s_setprio 0
	s_setprio 1
	v_mfma_f32_16x16x32_bf16 v[58:61], v[160:163], v[176:179], v[58:61]
	v_mfma_f32_16x16x32_bf16 v[50:53], v[168:171], v[176:179], v[50:53]
	v_mfma_f32_16x16x32_bf16 v[42:45], v[160:163], v[184:187], v[42:45]
	v_mfma_f32_16x16x32_bf16 v[34:37], v[168:171], v[184:187], v[34:37]
	v_mfma_f32_16x16x32_bf16 v[26:29], v[160:163], v[192:195], v[26:29]
	v_mfma_f32_16x16x32_bf16 v[18:21], v[168:171], v[192:195], v[18:21]
	v_mfma_f32_16x16x32_bf16 v[10:13], v[160:163], v[214:217], v[10:13]
	v_mfma_f32_16x16x32_bf16 v[2:5], v[168:171], v[214:217], v[2:5]
	v_mfma_f32_16x16x32_bf16 v[58:61], v[164:167], v[180:183], v[58:61]
	v_mfma_f32_16x16x32_bf16 v[50:53], v[172:175], v[180:183], v[50:53]
	v_mfma_f32_16x16x32_bf16 v[42:45], v[164:167], v[188:191], v[42:45]
	v_mfma_f32_16x16x32_bf16 v[34:37], v[172:175], v[188:191], v[34:37]
	v_mfma_f32_16x16x32_bf16 v[26:29], v[164:167], v[200:203], v[26:29]
	v_mfma_f32_16x16x32_bf16 v[18:21], v[172:175], v[200:203], v[18:21]
	v_mfma_f32_16x16x32_bf16 v[10:13], v[164:167], v[218:221], v[10:13]
	v_mfma_f32_16x16x32_bf16 v[2:5], v[172:175], v[218:221], v[2:5]
	s_setprio 0
	s_barrier
	s_add_i32 s53, s53, 2
	s_add_u32 s30, s30, 0x100
	s_addc_u32 s31, s31, 0
	s_add_u32 s51, s51, 0x100
	s_addc_u32 s52, s52, 0
	s_cmp_gt_u32 s53, 13
	s_cbranch_scc0 .LBB0_1018
	s_and_b64 vcc, exec, s[10:11]
	s_cbranch_vccz .LBB0_1021
	s_barrier

; #define PG8_STAGE(bufoff, gbase, voff) do { _Pragma("unroll") for (int _i = 0; _i < 2; ++_i) \
;         __builtin_amdgcn_global_load_lds((const unsigned*)((const char*)(gbase) + (voff)[_i]), (LAS unsigned*)(lds + (bufoff) + ldsw + _i * 8192), 16, 0, 0); } while (0)
; #define PG8_LDA(dst, b, h) do { _Pragma("unroll") for (int m = 0; m < 4; ++m) _Pragma("unroll") for (int k = 0; k < 2; ++k) dst[m][k] = *(const LAS f16x8*)(lds + PG8_SA(b, h) + aoff + m * 2048 + k * 1024); } while (0)
; #define PG8_LDB(dst, b, h) do { _Pragma("unroll") for (int n = 0; n < 2; ++n) _Pragma("unroll") for (int k = 0; k < 2; ++k) dst[n][k] = *(const LAS f16x8*)(lds + PG8_SB(b, h) + boff + n * 2048 + k * 1024); } while (0)
; #define PG8_MMA(ai, bj, At, Bt) do { __builtin_amdgcn_s_setprio(1); _Pragma("unroll") for (int m = 0; m < 4; ++m) _Pragma("unroll") for (int n = 0; n < 2; ++n) _Pragma("unroll") for (int k = 0; k < 2; ++k) \
;         acc[ai][bj][m][n] = mma16_<Epi::BF16>(Bt[n][k], At[m][k], acc[ai][bj][m][n]); __builtin_amdgcn_s_setprio(0); } while (0)
; #define PG8_WAIT_V(n) asm volatile("s_waitcnt vmcnt(" #n ")" ::: "memory")
; #define PG8_WAIT_L(n) asm volatile("s_waitcnt lgkmcnt(" #n ")" ::: "memory")
; #define PG8_BAR __builtin_amdgcn_s_barrier()
; #define PG8_SCHED __builtin_amdgcn_sched_barrier(0)
;     ...
;             const bool last = (t == nt - 2);
;             const char* a1 = cA + (size_t)(t + 1) * kstep;
;             const char* a2 = last ? nA : cA + (size_t)(t + 2) * kstep; const char* b2 = last ? nB : cB + (size_t)(t + 2) * kstep;
;             const char* a3 = a2 + kstep; const char* b3 = b2 + kstep;
;             if constexpr (SP2) {
;             PG8_LDB(B0, 0, 0); PG8_LDB(B1, 0, 1); PG8_SCHED; PG8_LDA(At, 0, 0); PG8_STAGE(PG8_SA(1, 1), a1 + hA, voffA);
;             PG8_WAIT_V(8); PG8_WAIT_L(0); PG8_BAR; PG8_MMA(0, 0, At, B0); PG8_MMA(0, 1, At, B1); PG8_BAR; PG8_SCHED;
;             PG8_LDA(At, 0, 1); PG8_STAGE(PG8_SB(0, 0), b2, voffB); PG8_STAGE(PG8_SB(0, 1), b2 + hB, voffB); PG8_STAGE(PG8_SA(0, 0), a2, voffA);
;             PG8_WAIT_V(8); PG8_WAIT_L(0); PG8_BAR; if (!cur.half) { PG8_MMA(1, 0, At, B0); PG8_MMA(1, 1, At, B1); } PG8_BAR; PG8_SCHED;
.LBB0_1103:
	s_mov_b64 s[42:43], s[30:31]
	s_add_u32 s30, s42, 0x100
	s_addc_u32 s31, s43, 0
	s_add_i32 s29, 0, 0x10000
	s_cmp_eq_u32 s14, 40
	s_cselect_b32 s45, s25, s31
	s_cselect_b32 s44, s24, s30
	s_cselect_b32 s37, s27, s3
	s_cselect_b32 s36, s26, s2
	s_add_i32 s69, 0, 0x14000
	v_add_u32_e32 v130, s29, v243
	v_add_u32_e32 v142, s69, v243
	ds_read_b128 v[146:149], v130
	ds_read_b128 v[150:153], v130 offset:1024
	ds_read_b128 v[154:157], v130 offset:2048
	ds_read_b128 v[158:161], v130 offset:3072
	ds_read_b128 v[130:133], v142
	ds_read_b128 v[134:137], v142 offset:1024
	ds_read_b128 v[138:141], v142 offset:2048
	ds_read_b128 v[142:145], v142 offset:3072
	s_add_i32 m0, s53, 0xc000
	s_waitcnt lgkmcnt(0)
	ds_read_b128 v[162:165], v244
	ds_read_b128 v[166:169], v244 offset:1024
	ds_read_b128 v[170:173], v244 offset:2048
	ds_read_b128 v[174:177], v244 offset:3072
	ds_read_b128 v[178:181], v244 offset:4096
	ds_read_b128 v[182:185], v244 offset:5120
	ds_read_b128 v[186:189], v244 offset:6144
	ds_read_b128 v[190:193], v244 offset:7168
	global_load_lds_dwordx4 v222, s[42:43]
	s_add_i32 m0, s53, 0xe000
	s_nop 0
	global_load_lds_dwordx4 v224, s[42:43]
	s_waitcnt vmcnt(8)
	s_waitcnt lgkmcnt(0)
	s_barrier
	s_setprio 1
	v_mfma_f32_16x16x32_bf16 v[126:129], v[146:149], v[162:165], v[126:129]
	v_mfma_f32_16x16x32_bf16 v[122:125], v[154:157], v[162:165], v[122:125]
	v_mfma_f32_16x16x32_bf16 v[118:121], v[146:149], v[170:173], v[118:121]
	v_mfma_f32_16x16x32_bf16 v[114:117], v[154:157], v[170:173], v[114:117]
	v_mfma_f32_16x16x32_bf16 v[110:113], v[146:149], v[178:181], v[110:113]
	v_mfma_f32_16x16x32_bf16 v[106:109], v[154:157], v[178:181], v[106:109]
	v_mfma_f32_16x16x32_bf16 v[102:105], v[146:149], v[186:189], v[102:105]
	v_mfma_f32_16x16x32_bf16 v[98:101], v[154:157], v[186:189], v[98:101]
	v_mfma_f32_16x16x32_bf16 v[126:129], v[150:153], v[166:169], v[126:129]
	v_mfma_f32_16x16x32_bf16 v[122:125], v[158:161], v[166:169], v[122:125]
	v_mfma_f32_16x16x32_bf16 v[118:121], v[150:153], v[174:177], v[118:121]
	v_mfma_f32_16x16x32_bf16 v[114:117], v[158:161], v[174:177], v[114:117]
	v_mfma_f32_16x16x32_bf16 v[110:113], v[150:153], v[182:185], v[110:113]
	v_mfma_f32_16x16x32_bf16 v[106:109], v[158:161], v[182:185], v[106:109]
	v_mfma_f32_16x16x32_bf16 v[102:105], v[150:153], v[190:193], v[102:105]
	v_mfma_f32_16x16x32_bf16 v[98:101], v[158:161], v[190:193], v[98:101]
	s_setprio 0
	s_setprio 1
	v_mfma_f32_16x16x32_bf16 v[78:81], v[130:133], v[162:165], v[78:81]
	v_mfma_f32_16x16x32_bf16 v[74:77], v[138:141], v[162:165], v[74:77]
	v_mfma_f32_16x16x32_bf16 v[62:65], v[130:133], v[170:173], v[62:65]
	v_mfma_f32_16x16x32_bf16 v[58:61], v[138:141], v[170:173], v[58:61]
	v_mfma_f32_16x16x32_bf16 v[46:49], v[130:133], v[178:181], v[46:49]
	v_mfma_f32_16x16x32_bf16 v[42:45], v[138:141], v[178:181], v[42:45]
	v_mfma_f32_16x16x32_bf16 v[38:41], v[130:133], v[186:189], v[38:41]
	v_mfma_f32_16x16x32_bf16 v[34:37], v[138:141], v[186:189], v[34:37]
	v_mfma_f32_16x16x32_bf16 v[78:81], v[134:137], v[166:169], v[78:81]
	v_mfma_f32_16x16x32_bf16 v[74:77], v[142:145], v[166:169], v[74:77]
	v_mfma_f32_16x16x32_bf16 v[62:65], v[134:137], v[174:177], v[62:65]
	v_mfma_f32_16x16x32_bf16 v[58:61], v[142:145], v[174:177], v[58:61]
	v_mfma_f32_16x16x32_bf16 v[46:49], v[134:137], v[182:185], v[46:49]
	v_mfma_f32_16x16x32_bf16 v[42:45], v[142:145], v[182:185], v[42:45]
	v_mfma_f32_16x16x32_bf16 v[38:41], v[134:137], v[190:193], v[38:41]
	v_mfma_f32_16x16x32_bf16 v[34:37], v[142:145], v[190:193], v[34:37]
	s_setprio 0
	s_barrier
	s_add_i32 s29, s29, s52
	v_lshl_add_u64 v[226:227], s[36:37], 0, v[214:215]
	s_mov_b32 m0, s29
	ds_read_b128 v[186:189], v244 offset:16384
	ds_read_b128 v[190:193], v244 offset:17408
	ds_read_b128 v[178:181], v244 offset:18432
	ds_read_b128 v[182:185], v244 offset:19456
	ds_read_b128 v[170:173], v244 offset:20480
	ds_read_b128 v[174:177], v244 offset:21504
	ds_read_b128 v[162:165], v244 offset:22528
	ds_read_b128 v[166:169], v244 offset:23552
	global_load_lds_dwordx4 v[226:227], off
	s_add_i32 m0, s29, 0x2000
	s_add_u32 s42, s36, 0xb0000
	v_lshl_add_u64 v[228:229], s[36:37], 0, v[218:219]
	s_addc_u32 s43, s37, 0
	s_add_i32 s29, s69, s52
	global_load_lds_dwordx4 v[228:229], off
	s_mov_b32 m0, s29
	v_lshl_add_u64 v[230:231], s[44:45], 0, v[194:195]
	global_load_lds_dwordx4 v214, s[42:43]
	s_add_i32 m0, s29, 0x2000
	v_lshl_add_u64 v[232:233], s[44:45], 0, v[216:217]
	global_load_lds_dwordx4 v218, s[42:43]
	s_mov_b32 m0, s53
	v_cndmask_b32_e64 v200, 0, 1, s[34:35]
	global_load_lds_dwordx4 v[230:231], off
	s_mov_b32 m0, s54
	v_cmp_ne_u32_e64 s[42:43], 1, v200
	global_load_lds_dwordx4 v[232:233], off
	s_waitcnt vmcnt(8)
	s_waitcnt lgkmcnt(0)
	s_andn2_b64 vcc, exec, s[34:35]
	s_barrier
	s_cbranch_vccnz .LBB0_1105
	s_setprio 1
	v_mfma_f32_16x16x32_bf16 v[94:97], v[146:149], v[186:189], v[94:97]
	v_mfma_f32_16x16x32_bf16 v[90:93], v[154:157], v[186:189], v[90:93]
	v_mfma_f32_16x16x32_bf16 v[86:89], v[146:149], v[178:181], v[86:89]
	v_mfma_f32_16x16x32_bf16 v[82:85], v[154:157], v[178:181], v[82:85]
	v_mfma_f32_16x16x32_bf16 v[70:73], v[146:149], v[170:173], v[70:73]
	v_mfma_f32_16x16x32_bf16 v[66:69], v[154:157], v[170:173], v[66:69]
	v_mfma_f32_16x16x32_bf16 v[54:57], v[146:149], v[162:165], v[54:57]
	v_mfma_f32_16x16x32_bf16 v[50:53], v[154:157], v[162:165], v[50:53]
	v_mfma_f32_16x16x32_bf16 v[94:97], v[150:153], v[190:193], v[94:97]
	v_mfma_f32_16x16x32_bf16 v[90:93], v[158:161], v[190:193], v[90:93]
	v_mfma_f32_16x16x32_bf16 v[86:89], v[150:153], v[182:185], v[86:89]
	v_mfma_f32_16x16x32_bf16 v[82:85], v[158:161], v[182:185], v[82:85]
	v_mfma_f32_16x16x32_bf16 v[70:73], v[150:153], v[174:177], v[70:73]
	v_mfma_f32_16x16x32_bf16 v[66:69], v[158:161], v[174:177], v[66:69]
	v_mfma_f32_16x16x32_bf16 v[54:57], v[150:153], v[166:169], v[54:57]
	v_mfma_f32_16x16x32_bf16 v[50:53], v[158:161], v[166:169], v[50:53]
	s_setprio 0
	s_setprio 1
	v_mfma_f32_16x16x32_bf16 v[30:33], v[130:133], v[186:189], v[30:33]
	v_mfma_f32_16x16x32_bf16 v[26:29], v[138:141], v[186:189], v[26:29]
	v_mfma_f32_16x16x32_bf16 v[22:25], v[130:133], v[178:181], v[22:25]
	v_mfma_f32_16x16x32_bf16 v[18:21], v[138:141], v[178:181], v[18:21]
	v_mfma_f32_16x16x32_bf16 v[14:17], v[130:133], v[170:173], v[14:17]
	v_mfma_f32_16x16x32_bf16 v[10:13], v[138:141], v[170:173], v[10:13]
	v_mfma_f32_16x16x32_bf16 v[6:9], v[130:133], v[162:165], v[6:9]
	v_mfma_f32_16x16x32_bf16 v[2:5], v[138:141], v[162:165], v[2:5]
	v_mfma_f32_16x16x32_bf16 v[30:33], v[134:137], v[190:193], v[30:33]
	v_mfma_f32_16x16x32_bf16 v[26:29], v[142:145], v[190:193], v[26:29]
	v_mfma_f32_16x16x32_bf16 v[22:25], v[134:137], v[182:185], v[22:25]
	v_mfma_f32_16x16x32_bf16 v[18:21], v[142:145], v[182:185], v[18:21]
	v_mfma_f32_16x16x32_bf16 v[14:17], v[134:137], v[174:177], v[14:17]
	v_mfma_f32_16x16x32_bf16 v[10:13], v[142:145], v[174:177], v[10:13]
	v_mfma_f32_16x16x32_bf16 v[6:9], v[134:137], v[166:169], v[6:9]
	v_mfma_f32_16x16x32_bf16 v[2:5], v[142:145], v[166:169], v[2:5]
	s_setprio 0
; #define PG8_STAGE(bufoff, gbase, voff) do { _Pragma("unroll") for (int _i = 0; _i < 2; ++_i) \
;         __builtin_amdgcn_global_load_lds((const unsigned*)((const char*)(gbase) + (voff)[_i]), (LAS unsigned*)(lds + (bufoff) + ldsw + _i * 8192), 16, 0, 0); } while (0)
; #define PG8_LDA(dst, b, h) do { _Pragma("unroll") for (int m = 0; m < 4; ++m) _Pragma("unroll") for (int k = 0; k < 2; ++k) dst[m][k] = *(const LAS f16x8*)(lds + PG8_SA(b, h) + aoff + m * 2048 + k * 1024); } while (0)
; #define PG8_LDB(dst, b, h) do { _Pragma("unroll") for (int n = 0; n < 2; ++n) _Pragma("unroll") for (int k = 0; k < 2; ++k) dst[n][k] = *(const LAS f16x8*)(lds + PG8_SB(b, h) + boff + n * 2048 + k * 1024); } while (0)
; #define PG8_MMA(ai, bj, At, Bt) do { __builtin_amdgcn_s_setprio(1); _Pragma("unroll") for (int m = 0; m < 4; ++m) _Pragma("unroll") for (int n = 0; n < 2; ++n) _Pragma("unroll") for (int k = 0; k < 2; ++k) \
;         acc[ai][bj][m][n] = mma16_<Epi::BF16>(Bt[n][k], At[m][k], acc[ai][bj][m][n]); __builtin_amdgcn_s_setprio(0); } while (0)
; #define PG8_WAIT_V(n) asm volatile("s_waitcnt vmcnt(" #n ")" ::: "memory")
; #define PG8_WAIT_L(n) asm volatile("s_waitcnt lgkmcnt(" #n ")" ::: "memory")
; #define PG8_BAR __builtin_amdgcn_s_barrier()
; #define PG8_SCHED __builtin_amdgcn_sched_barrier(0)
;     ...
;             PG8_LDB(B0, 1, 0); PG8_LDB(B1, 1, 1); PG8_SCHED; PG8_LDA(At, 1, 0); PG8_STAGE(PG8_SA(0, 1), a2 + hA, voffA);
;             PG8_WAIT_V(8); PG8_WAIT_L(0); PG8_BAR; PG8_MMA(0, 0, At, B0); PG8_MMA(0, 1, At, B1); PG8_BAR; PG8_SCHED;
;             PG8_LDA(At, 1, 1); PG8_STAGE(PG8_SB(1, 0), b3, voffB); PG8_STAGE(PG8_SB(1, 1), b3 + hB, voffB); PG8_STAGE(PG8_SA(1, 0), a3, voffA);
;             PG8_WAIT_V(8); PG8_WAIT_L(0); PG8_BAR; if (!cur.half) { PG8_MMA(1, 0, At, B0); PG8_MMA(1, 1, At, B1); } PG8_BAR; PG8_SCHED;
.LBB0_1105:
	s_barrier
	s_add_i32 s29, 0, 0x18000
	s_add_i32 s69, 0, 0x1c000
	v_add_u32_e32 v130, s29, v243
	v_add_u32_e32 v142, s69, v243
	ds_read_b128 v[146:149], v130
	ds_read_b128 v[150:153], v130 offset:1024
	ds_read_b128 v[154:157], v130 offset:2048
	ds_read_b128 v[158:161], v130 offset:3072
	ds_read_b128 v[130:133], v142
	ds_read_b128 v[134:137], v142 offset:1024
	ds_read_b128 v[138:141], v142 offset:2048
	ds_read_b128 v[142:145], v142 offset:3072
	s_add_u32 s44, s44, 0xb0000
	s_addc_u32 s45, s45, 0
	s_mov_b32 m0, s55
	s_waitcnt lgkmcnt(0)
	ds_read_b128 v[162:165], v244 offset:32768
	ds_read_b128 v[166:169], v244 offset:33792
	ds_read_b128 v[170:173], v244 offset:34816
	ds_read_b128 v[174:177], v244 offset:35840
	ds_read_b128 v[178:181], v244 offset:36864
	ds_read_b128 v[182:185], v244 offset:37888
	ds_read_b128 v[186:189], v244 offset:38912
	ds_read_b128 v[190:193], v244 offset:39936
	global_load_lds_dwordx4 v194, s[44:45]
	s_mov_b32 m0, s56
	s_nop 0
	global_load_lds_dwordx4 v216, s[44:45]
	s_waitcnt vmcnt(8)
	s_waitcnt lgkmcnt(0)
	s_barrier
	s_setprio 1
	v_mfma_f32_16x16x32_bf16 v[126:129], v[146:149], v[162:165], v[126:129]
	v_mfma_f32_16x16x32_bf16 v[122:125], v[154:157], v[162:165], v[122:125]
	v_mfma_f32_16x16x32_bf16 v[118:121], v[146:149], v[170:173], v[118:121]
	v_mfma_f32_16x16x32_bf16 v[114:117], v[154:157], v[170:173], v[114:117]
	v_mfma_f32_16x16x32_bf16 v[110:113], v[146:149], v[178:181], v[110:113]
	v_mfma_f32_16x16x32_bf16 v[106:109], v[154:157], v[178:181], v[106:109]
	v_mfma_f32_16x16x32_bf16 v[102:105], v[146:149], v[186:189], v[102:105]
	v_mfma_f32_16x16x32_bf16 v[98:101], v[154:157], v[186:189], v[98:101]
	v_mfma_f32_16x16x32_bf16 v[126:129], v[150:153], v[166:169], v[126:129]
	v_mfma_f32_16x16x32_bf16 v[122:125], v[158:161], v[166:169], v[122:125]
	v_mfma_f32_16x16x32_bf16 v[118:121], v[150:153], v[174:177], v[118:121]
	v_mfma_f32_16x16x32_bf16 v[114:117], v[158:161], v[174:177], v[114:117]
	v_mfma_f32_16x16x32_bf16 v[110:113], v[150:153], v[182:185], v[110:113]
	v_mfma_f32_16x16x32_bf16 v[106:109], v[158:161], v[182:185], v[106:109]
	v_mfma_f32_16x16x32_bf16 v[102:105], v[150:153], v[190:193], v[102:105]
	v_mfma_f32_16x16x32_bf16 v[98:101], v[158:161], v[190:193], v[98:101]
	s_setprio 0
	s_setprio 1
	v_mfma_f32_16x16x32_bf16 v[78:81], v[130:133], v[162:165], v[78:81]
	v_mfma_f32_16x16x32_bf16 v[74:77], v[138:141], v[162:165], v[74:77]
	v_mfma_f32_16x16x32_bf16 v[62:65], v[130:133], v[170:173], v[62:65]
	v_mfma_f32_16x16x32_bf16 v[58:61], v[138:141], v[170:173], v[58:61]
	v_mfma_f32_16x16x32_bf16 v[46:49], v[130:133], v[178:181], v[46:49]
	v_mfma_f32_16x16x32_bf16 v[42:45], v[138:141], v[178:181], v[42:45]
	v_mfma_f32_16x16x32_bf16 v[38:41], v[130:133], v[186:189], v[38:41]
	v_mfma_f32_16x16x32_bf16 v[34:37], v[138:141], v[186:189], v[34:37]
	v_mfma_f32_16x16x32_bf16 v[78:81], v[134:137], v[166:169], v[78:81]
	v_mfma_f32_16x16x32_bf16 v[74:77], v[142:145], v[166:169], v[74:77]
	v_mfma_f32_16x16x32_bf16 v[62:65], v[134:137], v[174:177], v[62:65]
	v_mfma_f32_16x16x32_bf16 v[58:61], v[142:145], v[174:177], v[58:61]
	v_mfma_f32_16x16x32_bf16 v[46:49], v[134:137], v[182:185], v[46:49]
	v_mfma_f32_16x16x32_bf16 v[42:45], v[142:145], v[182:185], v[42:45]
	v_mfma_f32_16x16x32_bf16 v[38:41], v[134:137], v[190:193], v[38:41]
	v_mfma_f32_16x16x32_bf16 v[34:37], v[142:145], v[190:193], v[34:37]
	s_setprio 0
	s_barrier
	s_add_i32 s29, s29, s52
	v_lshl_add_u64 v[200:201], v[226:227], 0, s[96:97]
	s_mov_b32 m0, s29
	ds_read_b128 v[186:189], v244 offset:49152
	ds_read_b128 v[190:193], v244 offset:50176
	ds_read_b128 v[178:181], v244 offset:51200
	ds_read_b128 v[182:185], v244 offset:52224
	ds_read_b128 v[170:173], v244 offset:53248
	ds_read_b128 v[174:177], v244 offset:54272
	ds_read_b128 v[162:165], v244 offset:55296
	ds_read_b128 v[166:169], v244 offset:56320
	global_load_lds_dwordx4 v[200:201], off
	s_add_i32 m0, s29, 0x2000
	s_add_u32 s36, s36, 0xb0080
	v_lshl_add_u64 v[200:201], v[228:229], 0, s[96:97]
	s_addc_u32 s37, s37, 0
	s_add_i32 s29, s69, s52
	global_load_lds_dwordx4 v[200:201], off
	s_mov_b32 m0, s29
	s_and_b64 vcc, exec, s[42:43]
	global_load_lds_dwordx4 v214, s[36:37]
	s_add_i32 m0, s29, 0x2000
	s_nop 0
	global_load_lds_dwordx4 v218, s[36:37]
	v_lshl_add_u64 v[200:201], v[230:231], 0, s[96:97]
	s_mov_b32 m0, s59
	s_nop 0
	global_load_lds_dwordx4 v[200:201], off
	v_lshl_add_u64 v[200:201], v[232:233], 0, s[96:97]
	s_mov_b32 m0, s60
	s_nop 0
	global_load_lds_dwordx4 v[200:201], off
	s_waitcnt vmcnt(8)
	s_waitcnt lgkmcnt(0)
	s_barrier
	s_cbranch_vccnz .LBB0_1102
	s_setprio 1
	v_mfma_f32_16x16x32_bf16 v[94:97], v[146:149], v[186:189], v[94:97]
	v_mfma_f32_16x16x32_bf16 v[90:93], v[154:157], v[186:189], v[90:93]
	v_mfma_f32_16x16x32_bf16 v[86:89], v[146:149], v[178:181], v[86:89]
	v_mfma_f32_16x16x32_bf16 v[82:85], v[154:157], v[178:181], v[82:85]
	v_mfma_f32_16x16x32_bf16 v[70:73], v[146:149], v[170:173], v[70:73]
	v_mfma_f32_16x16x32_bf16 v[66:69], v[154:157], v[170:173], v[66:69]
	v_mfma_f32_16x16x32_bf16 v[54:57], v[146:149], v[162:165], v[54:57]
	v_mfma_f32_16x16x32_bf16 v[50:53], v[154:157], v[162:165], v[50:53]
	v_mfma_f32_16x16x32_bf16 v[94:97], v[150:153], v[190:193], v[94:97]
	v_mfma_f32_16x16x32_bf16 v[90:93], v[158:161], v[190:193], v[90:93]
	v_mfma_f32_16x16x32_bf16 v[86:89], v[150:153], v[182:185], v[86:89]
	v_mfma_f32_16x16x32_bf16 v[82:85], v[158:161], v[182:185], v[82:85]
	v_mfma_f32_16x16x32_bf16 v[70:73], v[150:153], v[174:177], v[70:73]
	v_mfma_f32_16x16x32_bf16 v[66:69], v[158:161], v[174:177], v[66:69]
	v_mfma_f32_16x16x32_bf16 v[54:57], v[150:153], v[166:169], v[54:57]
	v_mfma_f32_16x16x32_bf16 v[50:53], v[158:161], v[166:169], v[50:53]
	s_setprio 0
	s_setprio 1
	v_mfma_f32_16x16x32_bf16 v[30:33], v[130:133], v[186:189], v[30:33]
	v_mfma_f32_16x16x32_bf16 v[26:29], v[138:141], v[186:189], v[26:29]
	v_mfma_f32_16x16x32_bf16 v[22:25], v[130:133], v[178:181], v[22:25]
	v_mfma_f32_16x16x32_bf16 v[18:21], v[138:141], v[178:181], v[18:21]
	v_mfma_f32_16x16x32_bf16 v[14:17], v[130:133], v[170:173], v[14:17]
	v_mfma_f32_16x16x32_bf16 v[10:13], v[138:141], v[170:173], v[10:13]
	v_mfma_f32_16x16x32_bf16 v[6:9], v[130:133], v[162:165], v[6:9]
	v_mfma_f32_16x16x32_bf16 v[2:5], v[138:141], v[162:165], v[2:5]
	v_mfma_f32_16x16x32_bf16 v[30:33], v[134:137], v[190:193], v[30:33]
	v_mfma_f32_16x16x32_bf16 v[26:29], v[142:145], v[190:193], v[26:29]
	v_mfma_f32_16x16x32_bf16 v[22:25], v[134:137], v[182:185], v[22:25]
	v_mfma_f32_16x16x32_bf16 v[18:21], v[142:145], v[182:185], v[18:21]
	v_mfma_f32_16x16x32_bf16 v[14:17], v[134:137], v[174:177], v[14:17]
	v_mfma_f32_16x16x32_bf16 v[10:13], v[142:145], v[174:177], v[10:13]
	v_mfma_f32_16x16x32_bf16 v[6:9], v[134:137], v[166:169], v[6:9]
	v_mfma_f32_16x16x32_bf16 v[2:5], v[142:145], v[166:169], v[2:5]
	s_setprio 0
	s_branch .LBB0_1102
